# GEMM load segments: LDS-DMA loads issued first, ds_reads after
# speedup vs baseline: 1.0029x; 1.0029x over previous
; #define PG8_STAGE(bufoff, gbase, voff) do { _Pragma("unroll") for (int _i = 0; _i < 2; ++_i) \
;         __builtin_amdgcn_global_load_lds((const unsigned*)((const char*)(gbase) + (voff)[_i]), (PG8_LAS unsigned*)(lds + (bufoff) + ldsw + _i * 8192), 16, 0, 0); } while (0)
; #define PG8_LDA(dst, b, h) do { _Pragma("unroll") for (int m = 0; m < 4; ++m) _Pragma("unroll") for (int k = 0; k < 2; ++k) dst[m][k] = *(const PG8_LAS bf16x8*)(lds + PG8_SA(b, h) + aoff + m * 2048 + k * 1024); } while (0)
; #define PG8_LDB(dst, b, h) do { _Pragma("unroll") for (int n = 0; n < 2; ++n) _Pragma("unroll") for (int k = 0; k < 2; ++k) dst[n][k] = *(const PG8_LAS bf16x8*)(lds + PG8_SB(b, h) + boff + n * 2048 + k * 1024); } while (0)
; #define PG8_MMA(ai, bj, At, Bt) do { __builtin_amdgcn_s_setprio(1); _Pragma("unroll") for (int m = 0; m < 4; ++m) _Pragma("unroll") for (int n = 0; n < 2; ++n) _Pragma("unroll") for (int k = 0; k < 2; ++k) \
;         acc[ai][bj][m][n] = __builtin_amdgcn_mfma_f32_16x16x32_bf16(Bt[n][k], At[m][k], acc[ai][bj][m][n], 0, 0, 0); __builtin_amdgcn_s_setprio(0); } while (0)
; #define PG8_WAIT_V(n) asm volatile("s_waitcnt vmcnt(" #n ")" ::: "memory")
; #define PG8_WAIT_L(n) asm volatile("s_waitcnt lgkmcnt(" #n ")" ::: "memory")
; template <class Epi, class Sched, bool ALIGN_EPI = false, bool SP2 = false>
; __device__ __forceinline__ void gemm_phase(PG8_LAS unsigned char* lds, const Gemm g, const Sched& S, const Epi& E) {
;     ...
;             const bool last = (t == nt - 2);
;             const char* a1 = cA + (size_t)(t + 1) * kstep;
;             const char* a2 = last ? nA : cA + (size_t)(t + 2) * kstep; const char* b2 = last ? nB : cB + (size_t)(t + 2) * kstep;
;             const char* a3 = a2 + kstep; const char* b3 = b2 + kstep;
;             if (last && has_next) S.a_ready(nxt);
;             if constexpr (SP2) {
;             PG8_LDB(B0, 0, 0); PG8_LDB(B1, 0, 1); PG8_SCHED; PG8_LDA(At, 0, 0); PG8_STAGE(PG8_SA(1, 1), a1 + hstep, voffA);
;             PG8_WAIT_V(8); PG8_WAIT_L(0); PG8_BAR; PG8_MMA(0, 0, At, B0); PG8_MMA(0, 1, At, B1); PG8_BAR; PG8_SCHED;
;             PG8_LDA(At, 0, 1); PG8_STAGE(PG8_SB(0, 0), b2, voffB); PG8_STAGE(PG8_SB(0, 1), b2 + hstep, voffB); PG8_STAGE(PG8_SA(0, 0), a2, voffA);
;             PG8_WAIT_V(8); PG8_WAIT_L(0); PG8_BAR; PG8_MMA(1, 0, At, B0); PG8_MMA(1, 1, At, B1); PG8_BAR; PG8_SCHED;
.LBB0_673:
	s_add_u32 s20, s22, 0xfff00080
	s_addc_u32 s21, s23, -1
	s_cmp_eq_u32 s35, 60
	s_cselect_b32 s25, s11, s21
	s_cselect_b32 s24, s52, s20
	s_cselect_b32 s21, s13, s34
	s_cselect_b32 s20, s53, s62
	s_add_i32 m0, s19, 0xc000
	s_nop 0
	global_load_lds_dwordx4 v138, s[22:23]
	s_add_i32 m0, s19, 0xe000
	s_nop 0
	global_load_lds_dwordx4 v140, s[22:23]
	ds_read_b128 v[148:151], v241 offset:0
	ds_read_b128 v[156:159], v241 offset:1024
	ds_read_b128 v[166:169], v241 offset:2048
	ds_read_b128 v[170:173], v241 offset:3072
	ds_read_b128 v[174:177], v241 offset:16384
	ds_read_b128 v[178:181], v241 offset:17408
	ds_read_b128 v[182:185], v241 offset:18432
	ds_read_b128 v[186:189], v241 offset:19456
	ds_read_b128 v[190:193], v161
	ds_read_b128 v[194:197], v161 offset:1024
	ds_read_b128 v[198:201], v161 offset:2048
	ds_read_b128 v[202:205], v161 offset:3072
	ds_read_b128 v[206:209], v161 offset:4096
	ds_read_b128 v[210:213], v161 offset:5120
	ds_read_b128 v[214:217], v161 offset:6144
	ds_read_b128 v[218:221], v161 offset:7168
	s_waitcnt vmcnt(8)
	s_waitcnt lgkmcnt(0)
	s_barrier
	s_waitcnt lgkmcnt(0)
	v_mfma_f32_16x16x32_bf16 v[118:121], v[148:151], v[190:193], v[118:121]
	v_mfma_f32_16x16x32_bf16 v[114:117], v[166:169], v[190:193], v[114:117]
	v_mfma_f32_16x16x32_bf16 v[102:105], v[148:151], v[198:201], v[102:105]
	v_mfma_f32_16x16x32_bf16 v[98:101], v[166:169], v[198:201], v[98:101]
	v_mfma_f32_16x16x32_bf16 v[86:89], v[148:151], v[206:209], v[86:89]
	v_mfma_f32_16x16x32_bf16 v[82:85], v[166:169], v[206:209], v[82:85]
	v_mfma_f32_16x16x32_bf16 v[70:73], v[148:151], v[214:217], v[70:73]
	v_mfma_f32_16x16x32_bf16 v[66:69], v[166:169], v[214:217], v[66:69]
	v_mfma_f32_16x16x32_bf16 v[118:121], v[156:159], v[194:197], v[118:121]
	v_mfma_f32_16x16x32_bf16 v[114:117], v[170:173], v[194:197], v[114:117]
	v_mfma_f32_16x16x32_bf16 v[102:105], v[156:159], v[202:205], v[102:105]
	v_mfma_f32_16x16x32_bf16 v[98:101], v[170:173], v[202:205], v[98:101]
	v_mfma_f32_16x16x32_bf16 v[86:89], v[156:159], v[210:213], v[86:89]
	v_mfma_f32_16x16x32_bf16 v[82:85], v[170:173], v[210:213], v[82:85]
	v_mfma_f32_16x16x32_bf16 v[70:73], v[156:159], v[218:221], v[70:73]
	v_mfma_f32_16x16x32_bf16 v[66:69], v[170:173], v[218:221], v[66:69]
	v_mfma_f32_16x16x32_bf16 v[126:129], v[174:177], v[190:193], v[126:129]
	v_mfma_f32_16x16x32_bf16 v[122:125], v[182:185], v[190:193], v[122:125]
	v_mfma_f32_16x16x32_bf16 v[110:113], v[174:177], v[198:201], v[110:113]
	v_mfma_f32_16x16x32_bf16 v[106:109], v[182:185], v[198:201], v[106:109]
	v_mfma_f32_16x16x32_bf16 v[94:97], v[174:177], v[206:209], v[94:97]
	v_mfma_f32_16x16x32_bf16 v[90:93], v[182:185], v[206:209], v[90:93]
	v_mfma_f32_16x16x32_bf16 v[78:81], v[174:177], v[214:217], v[78:81]
	v_mfma_f32_16x16x32_bf16 v[74:77], v[182:185], v[214:217], v[74:77]
	v_mfma_f32_16x16x32_bf16 v[126:129], v[178:181], v[194:197], v[126:129]
	v_mfma_f32_16x16x32_bf16 v[122:125], v[186:189], v[194:197], v[122:125]
	v_mfma_f32_16x16x32_bf16 v[110:113], v[178:181], v[202:205], v[110:113]
	v_mfma_f32_16x16x32_bf16 v[106:109], v[186:189], v[202:205], v[106:109]
	v_mfma_f32_16x16x32_bf16 v[94:97], v[178:181], v[210:213], v[94:97]
	v_mfma_f32_16x16x32_bf16 v[90:93], v[186:189], v[210:213], v[90:93]
	v_mfma_f32_16x16x32_bf16 v[78:81], v[178:181], v[218:221], v[78:81]
	v_mfma_f32_16x16x32_bf16 v[74:77], v[186:189], v[218:221], v[74:77]
	s_barrier
	s_add_i32 s63, s43, s26
	s_mov_b32 m0, s63
	s_nop 0
	global_load_lds_dwordx4 v132, s[20:21]
	s_add_i32 m0, s63, 0x2000
	s_add_u32 s64, s20, 0x100000
	s_addc_u32 s65, s21, 0
	s_add_i32 s63, s46, s26
	global_load_lds_dwordx4 v136, s[20:21]
	s_mov_b32 m0, s63
	s_add_u32 s100, s24, 0x80
	s_addc_u32 s101, s25, 0
	global_load_lds_dwordx4 v132, s[64:65]
	s_add_i32 m0, s63, 0x2000
	s_nop 0
	global_load_lds_dwordx4 v136, s[64:65]
	s_mov_b32 m0, s19
	s_nop 0
	global_load_lds_dwordx4 v130, s[24:25]
	s_mov_b32 m0, s29
	s_nop 0
	global_load_lds_dwordx4 v134, s[24:25]
	ds_read_b128 v[190:193], v161 offset:16384
	ds_read_b128 v[194:197], v161 offset:17408
	ds_read_b128 v[198:201], v161 offset:18432
	ds_read_b128 v[202:205], v161 offset:19456
	ds_read_b128 v[206:209], v161 offset:20480
	ds_read_b128 v[210:213], v161 offset:21504
	ds_read_b128 v[214:217], v161 offset:22528
	ds_read_b128 v[218:221], v161 offset:23552
	s_waitcnt vmcnt(8)
	s_waitcnt lgkmcnt(0)
	s_barrier
	s_waitcnt lgkmcnt(0)
	v_mfma_f32_16x16x32_bf16 v[54:57], v[148:151], v[190:193], v[54:57]
	v_mfma_f32_16x16x32_bf16 v[50:53], v[166:169], v[190:193], v[50:53]
	v_mfma_f32_16x16x32_bf16 v[38:41], v[148:151], v[198:201], v[38:41]
	v_mfma_f32_16x16x32_bf16 v[34:37], v[166:169], v[198:201], v[34:37]
	v_mfma_f32_16x16x32_bf16 v[22:25], v[148:151], v[206:209], v[22:25]
	v_mfma_f32_16x16x32_bf16 v[18:21], v[166:169], v[206:209], v[18:21]
	v_mfma_f32_16x16x32_bf16 v[6:9], v[148:151], v[214:217], v[6:9]
	v_mfma_f32_16x16x32_bf16 v[2:5], v[166:169], v[214:217], v[2:5]
	v_mfma_f32_16x16x32_bf16 v[54:57], v[156:159], v[194:197], v[54:57]
	v_mfma_f32_16x16x32_bf16 v[50:53], v[170:173], v[194:197], v[50:53]
	v_mfma_f32_16x16x32_bf16 v[38:41], v[156:159], v[202:205], v[38:41]
	v_mfma_f32_16x16x32_bf16 v[34:37], v[170:173], v[202:205], v[34:37]
	v_mfma_f32_16x16x32_bf16 v[22:25], v[156:159], v[210:213], v[22:25]
	v_mfma_f32_16x16x32_bf16 v[18:21], v[170:173], v[210:213], v[18:21]
	v_mfma_f32_16x16x32_bf16 v[6:9], v[156:159], v[218:221], v[6:9]
	v_mfma_f32_16x16x32_bf16 v[2:5], v[170:173], v[218:221], v[2:5]
	v_mfma_f32_16x16x32_bf16 v[62:65], v[174:177], v[190:193], v[62:65]
	v_mfma_f32_16x16x32_bf16 v[58:61], v[182:185], v[190:193], v[58:61]
	v_mfma_f32_16x16x32_bf16 v[46:49], v[174:177], v[198:201], v[46:49]
	v_mfma_f32_16x16x32_bf16 v[42:45], v[182:185], v[198:201], v[42:45]
	v_mfma_f32_16x16x32_bf16 v[30:33], v[174:177], v[206:209], v[30:33]
	v_mfma_f32_16x16x32_bf16 v[26:29], v[182:185], v[206:209], v[26:29]
	v_mfma_f32_16x16x32_bf16 v[10:13], v[174:177], v[214:217], v[10:13]
	v_mfma_f32_16x16x32_bf16 v[14:17], v[182:185], v[214:217], v[14:17]
	v_mfma_f32_16x16x32_bf16 v[62:65], v[178:181], v[194:197], v[62:65]
	v_mfma_f32_16x16x32_bf16 v[58:61], v[186:189], v[194:197], v[58:61]
	v_mfma_f32_16x16x32_bf16 v[46:49], v[178:181], v[202:205], v[46:49]
	v_mfma_f32_16x16x32_bf16 v[42:45], v[186:189], v[202:205], v[42:45]
	v_mfma_f32_16x16x32_bf16 v[30:33], v[178:181], v[210:213], v[30:33]
	v_mfma_f32_16x16x32_bf16 v[26:29], v[186:189], v[210:213], v[26:29]
	v_mfma_f32_16x16x32_bf16 v[10:13], v[178:181], v[218:221], v[10:13]
	v_mfma_f32_16x16x32_bf16 v[14:17], v[186:189], v[218:221], v[14:17]
	s_barrier
; #define PG8_STAGE(bufoff, gbase, voff) do { _Pragma("unroll") for (int _i = 0; _i < 2; ++_i) \
;         __builtin_amdgcn_global_load_lds((const unsigned*)((const char*)(gbase) + (voff)[_i]), (PG8_LAS unsigned*)(lds + (bufoff) + ldsw + _i * 8192), 16, 0, 0); } while (0)
; #define PG8_LDA(dst, b, h) do { _Pragma("unroll") for (int m = 0; m < 4; ++m) _Pragma("unroll") for (int k = 0; k < 2; ++k) dst[m][k] = *(const PG8_LAS bf16x8*)(lds + PG8_SA(b, h) + aoff + m * 2048 + k * 1024); } while (0)
; #define PG8_LDB(dst, b, h) do { _Pragma("unroll") for (int n = 0; n < 2; ++n) _Pragma("unroll") for (int k = 0; k < 2; ++k) dst[n][k] = *(const PG8_LAS bf16x8*)(lds + PG8_SB(b, h) + boff + n * 2048 + k * 1024); } while (0)
; #define PG8_MMA(ai, bj, At, Bt) do { __builtin_amdgcn_s_setprio(1); _Pragma("unroll") for (int m = 0; m < 4; ++m) _Pragma("unroll") for (int n = 0; n < 2; ++n) _Pragma("unroll") for (int k = 0; k < 2; ++k) \
;         acc[ai][bj][m][n] = __builtin_amdgcn_mfma_f32_16x16x32_bf16(Bt[n][k], At[m][k], acc[ai][bj][m][n], 0, 0, 0); __builtin_amdgcn_s_setprio(0); } while (0)
; #define PG8_WAIT_V(n) asm volatile("s_waitcnt vmcnt(" #n ")" ::: "memory")
; #define PG8_WAIT_L(n) asm volatile("s_waitcnt lgkmcnt(" #n ")" ::: "memory")
; #define PG8_BAR __builtin_amdgcn_s_barrier()
; #define PG8_SCHED __builtin_amdgcn_sched_barrier(0)
; template <class Epi, class Sched, bool ALIGN_EPI = false, bool SP2 = false>
; __device__ __forceinline__ void gemm_phase(PG8_LAS unsigned char* lds, const Gemm g, const Sched& S, const Epi& E) {
;     ...
;             PG8_LDB(B0, 1, 0); PG8_LDB(B1, 1, 1); PG8_SCHED; PG8_LDA(At, 1, 0); PG8_STAGE(PG8_SA(0, 1), a2 + hstep, voffA);
;             PG8_WAIT_V(8); PG8_WAIT_L(0); PG8_BAR; PG8_MMA(0, 0, At, B0); PG8_MMA(0, 1, At, B1); PG8_BAR; PG8_SCHED;
;             PG8_LDA(At, 1, 1); PG8_STAGE(PG8_SB(1, 0), b3, voffB); PG8_STAGE(PG8_SB(1, 1), b3 + hstep, voffB); PG8_STAGE(PG8_SA(1, 0), a3, voffA);
;             PG8_WAIT_V(8); PG8_WAIT_L(0); PG8_BAR; PG8_MMA(1, 0, At, B0); PG8_MMA(1, 1, At, B1); PG8_BAR; PG8_SCHED;
	s_add_i32 s63, 0, 0x18000
	s_add_i32 s64, 0, 0x1c000
	s_add_u32 s24, s24, 0x100000
	s_addc_u32 s25, s25, 0
	s_mov_b32 m0, s30
	s_nop 0
	global_load_lds_dwordx4 v130, s[24:25]
	s_mov_b32 m0, s31
	s_nop 0
	global_load_lds_dwordx4 v134, s[24:25]
	ds_read_b128 v[148:151], v241 offset:32768
	ds_read_b128 v[156:159], v241 offset:33792
	ds_read_b128 v[166:169], v241 offset:34816
	ds_read_b128 v[170:173], v241 offset:35840
	ds_read_b128 v[174:177], v241 offset:49152
	ds_read_b128 v[178:181], v241 offset:50176
	ds_read_b128 v[182:185], v241 offset:51200
	ds_read_b128 v[186:189], v241 offset:52224
	ds_read_b128 v[190:193], v161 offset:32768
	ds_read_b128 v[194:197], v161 offset:33792
	ds_read_b128 v[198:201], v161 offset:34816
	ds_read_b128 v[202:205], v161 offset:35840
	ds_read_b128 v[206:209], v161 offset:36864
	ds_read_b128 v[210:213], v161 offset:37888
	ds_read_b128 v[214:217], v161 offset:38912
	ds_read_b128 v[218:221], v161 offset:39936
	s_waitcnt vmcnt(8)
	s_waitcnt lgkmcnt(0)
	s_barrier
	s_waitcnt lgkmcnt(0)
	v_mfma_f32_16x16x32_bf16 v[118:121], v[148:151], v[190:193], v[118:121]
	v_mfma_f32_16x16x32_bf16 v[114:117], v[166:169], v[190:193], v[114:117]
	v_mfma_f32_16x16x32_bf16 v[102:105], v[148:151], v[198:201], v[102:105]
	v_mfma_f32_16x16x32_bf16 v[98:101], v[166:169], v[198:201], v[98:101]
	v_mfma_f32_16x16x32_bf16 v[86:89], v[148:151], v[206:209], v[86:89]
	v_mfma_f32_16x16x32_bf16 v[82:85], v[166:169], v[206:209], v[82:85]
	v_mfma_f32_16x16x32_bf16 v[70:73], v[148:151], v[214:217], v[70:73]
	v_mfma_f32_16x16x32_bf16 v[66:69], v[166:169], v[214:217], v[66:69]
	v_mfma_f32_16x16x32_bf16 v[118:121], v[156:159], v[194:197], v[118:121]
	v_mfma_f32_16x16x32_bf16 v[114:117], v[170:173], v[194:197], v[114:117]
	v_mfma_f32_16x16x32_bf16 v[102:105], v[156:159], v[202:205], v[102:105]
	v_mfma_f32_16x16x32_bf16 v[98:101], v[170:173], v[202:205], v[98:101]
	v_mfma_f32_16x16x32_bf16 v[86:89], v[156:159], v[210:213], v[86:89]
	v_mfma_f32_16x16x32_bf16 v[82:85], v[170:173], v[210:213], v[82:85]
	v_mfma_f32_16x16x32_bf16 v[70:73], v[156:159], v[218:221], v[70:73]
	v_mfma_f32_16x16x32_bf16 v[66:69], v[170:173], v[218:221], v[66:69]
	v_mfma_f32_16x16x32_bf16 v[126:129], v[174:177], v[190:193], v[126:129]
	v_mfma_f32_16x16x32_bf16 v[122:125], v[182:185], v[190:193], v[122:125]
	v_mfma_f32_16x16x32_bf16 v[110:113], v[174:177], v[198:201], v[110:113]
	v_mfma_f32_16x16x32_bf16 v[106:109], v[182:185], v[198:201], v[106:109]
	v_mfma_f32_16x16x32_bf16 v[94:97], v[174:177], v[206:209], v[94:97]
	v_mfma_f32_16x16x32_bf16 v[90:93], v[182:185], v[206:209], v[90:93]
	v_mfma_f32_16x16x32_bf16 v[78:81], v[174:177], v[214:217], v[78:81]
	v_mfma_f32_16x16x32_bf16 v[74:77], v[182:185], v[214:217], v[74:77]
	v_mfma_f32_16x16x32_bf16 v[126:129], v[178:181], v[194:197], v[126:129]
	v_mfma_f32_16x16x32_bf16 v[122:125], v[186:189], v[194:197], v[122:125]
	v_mfma_f32_16x16x32_bf16 v[110:113], v[178:181], v[202:205], v[110:113]
	v_mfma_f32_16x16x32_bf16 v[106:109], v[186:189], v[202:205], v[106:109]
	v_mfma_f32_16x16x32_bf16 v[94:97], v[178:181], v[210:213], v[94:97]
	v_mfma_f32_16x16x32_bf16 v[90:93], v[186:189], v[210:213], v[90:93]
	v_mfma_f32_16x16x32_bf16 v[78:81], v[178:181], v[218:221], v[78:81]
	v_mfma_f32_16x16x32_bf16 v[74:77], v[186:189], v[218:221], v[74:77]
	s_barrier
	s_add_i32 s24, s63, s26
	s_add_i32 m0, s24, 0xffffff80
	s_nop 0
	global_load_lds_dwordx4 v132, s[20:21] offset:128
	s_add_i32 m0, s24, 0x1f80
	s_add_i32 s24, s64, s26
	global_load_lds_dwordx4 v136, s[20:21] offset:128
	s_add_u32 s20, s20, 0x100080
	s_addc_u32 s21, s21, 0
	s_mov_b32 m0, s24
	s_nop 0
	global_load_lds_dwordx4 v132, s[20:21]
	s_add_i32 m0, s24, 0x2000
	s_nop 0
	global_load_lds_dwordx4 v136, s[20:21]
	s_mov_b32 m0, s40
	s_nop 0
	global_load_lds_dwordx4 v130, s[100:101]
	s_mov_b32 m0, s41
	s_nop 0
	global_load_lds_dwordx4 v134, s[100:101]
	ds_read_b128 v[190:193], v161 offset:49152
	ds_read_b128 v[194:197], v161 offset:50176
	ds_read_b128 v[198:201], v161 offset:51200
	ds_read_b128 v[202:205], v161 offset:52224
	ds_read_b128 v[206:209], v161 offset:53248
	ds_read_b128 v[210:213], v161 offset:54272
	ds_read_b128 v[214:217], v161 offset:55296
	ds_read_b128 v[218:221], v161 offset:56320
	s_waitcnt vmcnt(8)
	s_waitcnt lgkmcnt(0)
	s_barrier
	s_waitcnt lgkmcnt(0)
	v_mfma_f32_16x16x32_bf16 v[54:57], v[148:151], v[190:193], v[54:57]
	v_mfma_f32_16x16x32_bf16 v[50:53], v[166:169], v[190:193], v[50:53]
	v_mfma_f32_16x16x32_bf16 v[38:41], v[148:151], v[198:201], v[38:41]
	v_mfma_f32_16x16x32_bf16 v[34:37], v[166:169], v[198:201], v[34:37]
	v_mfma_f32_16x16x32_bf16 v[22:25], v[148:151], v[206:209], v[22:25]
	v_mfma_f32_16x16x32_bf16 v[18:21], v[166:169], v[206:209], v[18:21]
	v_mfma_f32_16x16x32_bf16 v[6:9], v[148:151], v[214:217], v[6:9]
	v_mfma_f32_16x16x32_bf16 v[2:5], v[166:169], v[214:217], v[2:5]
	v_mfma_f32_16x16x32_bf16 v[54:57], v[156:159], v[194:197], v[54:57]
	v_mfma_f32_16x16x32_bf16 v[50:53], v[170:173], v[194:197], v[50:53]
	v_mfma_f32_16x16x32_bf16 v[38:41], v[156:159], v[202:205], v[38:41]
	v_mfma_f32_16x16x32_bf16 v[34:37], v[170:173], v[202:205], v[34:37]
	v_mfma_f32_16x16x32_bf16 v[22:25], v[156:159], v[210:213], v[22:25]
	v_mfma_f32_16x16x32_bf16 v[18:21], v[170:173], v[210:213], v[18:21]
	v_mfma_f32_16x16x32_bf16 v[6:9], v[156:159], v[218:221], v[6:9]
	v_mfma_f32_16x16x32_bf16 v[2:5], v[170:173], v[218:221], v[2:5]
	v_mfma_f32_16x16x32_bf16 v[62:65], v[174:177], v[190:193], v[62:65]
	v_mfma_f32_16x16x32_bf16 v[58:61], v[182:185], v[190:193], v[58:61]
	v_mfma_f32_16x16x32_bf16 v[46:49], v[174:177], v[198:201], v[46:49]
	v_mfma_f32_16x16x32_bf16 v[42:45], v[182:185], v[198:201], v[42:45]
	v_mfma_f32_16x16x32_bf16 v[30:33], v[174:177], v[206:209], v[30:33]
	v_mfma_f32_16x16x32_bf16 v[26:29], v[182:185], v[206:209], v[26:29]
	v_mfma_f32_16x16x32_bf16 v[10:13], v[174:177], v[214:217], v[10:13]
	v_mfma_f32_16x16x32_bf16 v[14:17], v[182:185], v[214:217], v[14:17]
	v_mfma_f32_16x16x32_bf16 v[62:65], v[178:181], v[194:197], v[62:65]
	v_mfma_f32_16x16x32_bf16 v[58:61], v[186:189], v[194:197], v[58:61]
	v_mfma_f32_16x16x32_bf16 v[46:49], v[178:181], v[202:205], v[46:49]
	v_mfma_f32_16x16x32_bf16 v[42:45], v[186:189], v[202:205], v[42:45]
	v_mfma_f32_16x16x32_bf16 v[30:33], v[178:181], v[210:213], v[30:33]
	v_mfma_f32_16x16x32_bf16 v[26:29], v[186:189], v[210:213], v[26:29]
	v_mfma_f32_16x16x32_bf16 v[10:13], v[178:181], v[218:221], v[10:13]
	v_mfma_f32_16x16x32_bf16 v[14:17], v[186:189], v[218:221], v[14:17]
	s_barrier
	s_add_i32 s35, s35, 2
	s_add_u32 s22, s22, 0x100
	s_addc_u32 s23, s23, 0
	s_add_u32 s62, s62, 0x100
	s_addc_u32 s34, s34, 0
	s_cmp_gt_u32 s35, 61
	s_cbranch_scc0 .LBB0_673


; #define PG8_BAR __builtin_amdgcn_s_barrier()
; template <class Epi, class Sched, bool ALIGN_EPI = false, bool SP2 = false>
; __device__ __forceinline__ void gemm_phase(PG8_LAS unsigned char* lds, const Gemm g, const Sched& S, const Epi& E) {
;     ...
;         if constexpr (ALIGN_EPI) { if (wr == 0) PG8_BAR; }
	s_and_b64 vcc, exec, s[8:9]
	s_cbranch_vccz .LBB0_676
	s_barrier

; #define PG8_STAGE(bufoff, gbase, voff) do { _Pragma("unroll") for (int _i = 0; _i < 2; ++_i) \
;         __builtin_amdgcn_global_load_lds((const unsigned*)((const char*)(gbase) + (voff)[_i]), (PG8_LAS unsigned*)(lds + (bufoff) + ldsw + _i * 8192), 16, 0, 0); } while (0)
; #define PG8_LDA(dst, b, h) do { _Pragma("unroll") for (int m = 0; m < 4; ++m) _Pragma("unroll") for (int k = 0; k < 2; ++k) dst[m][k] = *(const PG8_LAS bf16x8*)(lds + PG8_SA(b, h) + aoff + m * 2048 + k * 1024); } while (0)
; #define PG8_LDB(dst, b, h) do { _Pragma("unroll") for (int n = 0; n < 2; ++n) _Pragma("unroll") for (int k = 0; k < 2; ++k) dst[n][k] = *(const PG8_LAS bf16x8*)(lds + PG8_SB(b, h) + boff + n * 2048 + k * 1024); } while (0)
; #define PG8_MMA(ai, bj, At, Bt) do { __builtin_amdgcn_s_setprio(1); _Pragma("unroll") for (int m = 0; m < 4; ++m) _Pragma("unroll") for (int n = 0; n < 2; ++n) _Pragma("unroll") for (int k = 0; k < 2; ++k) \
;         acc[ai][bj][m][n] = __builtin_amdgcn_mfma_f32_16x16x32_bf16(Bt[n][k], At[m][k], acc[ai][bj][m][n], 0, 0, 0); __builtin_amdgcn_s_setprio(0); } while (0)
; #define PG8_WAIT_V(n) asm volatile("s_waitcnt vmcnt(" #n ")" ::: "memory")
; #define PG8_WAIT_L(n) asm volatile("s_waitcnt lgkmcnt(" #n ")" ::: "memory")
; template <class Epi, class Sched, bool ALIGN_EPI = false, bool SP2 = false>
; __device__ __forceinline__ void gemm_phase(PG8_LAS unsigned char* lds, const Gemm g, const Sched& S, const Epi& E) {
;     ...
;             const bool last = (t == nt - 2);
;             const char* a1 = cA + (size_t)(t + 1) * kstep;
;             const char* a2 = last ? nA : cA + (size_t)(t + 2) * kstep; const char* b2 = last ? nB : cB + (size_t)(t + 2) * kstep;
;             const char* a3 = a2 + kstep; const char* b3 = b2 + kstep;
;             if (last && has_next) S.a_ready(nxt);
;             if constexpr (SP2) {
;             PG8_LDB(B0, 0, 0); PG8_LDB(B1, 0, 1); PG8_SCHED; PG8_LDA(At, 0, 0); PG8_STAGE(PG8_SA(1, 1), a1 + hstep, voffA);
;             PG8_WAIT_V(8); PG8_WAIT_L(0); PG8_BAR; PG8_MMA(0, 0, At, B0); PG8_MMA(0, 1, At, B1); PG8_BAR; PG8_SCHED;
;             PG8_LDA(At, 0, 1); PG8_STAGE(PG8_SB(0, 0), b2, voffB); PG8_STAGE(PG8_SB(0, 1), b2 + hstep, voffB); PG8_STAGE(PG8_SA(0, 0), a2, voffA);
;             PG8_WAIT_V(8); PG8_WAIT_L(0); PG8_BAR; PG8_MMA(1, 0, At, B0); PG8_MMA(1, 1, At, B1); PG8_BAR; PG8_SCHED;
.LBB0_1039:
	s_add_u32 s24, s26, 0xfff00080
	s_addc_u32 s25, s27, -1
	s_cmp_eq_u32 s68, 60
	s_cselect_b32 s29, s15, s25
	s_cselect_b32 s28, s21, s24
	s_cselect_b32 s25, s13, s67
	s_cselect_b32 s24, s65, s66
	s_add_i32 m0, s23, 0xc000
	s_nop 0
	global_load_lds_dwordx4 v162, s[26:27]
	s_add_i32 m0, s23, 0xe000
	s_nop 0
	global_load_lds_dwordx4 v166, s[26:27]
	ds_read_b128 v[130:133], v241 offset:0
	ds_read_b128 v[134:137], v241 offset:1024
	ds_read_b128 v[138:141], v241 offset:2048
	ds_read_b128 v[142:145], v241 offset:3072
	ds_read_b128 v[146:149], v241 offset:16384
	ds_read_b128 v[150:153], v241 offset:17408
	ds_read_b128 v[172:175], v241 offset:18432
	ds_read_b128 v[176:179], v241 offset:19456
	ds_read_b128 v[180:183], v185
	ds_read_b128 v[188:191], v185 offset:1024
	ds_read_b128 v[192:195], v185 offset:2048
	ds_read_b128 v[196:199], v185 offset:3072
	ds_read_b128 v[200:203], v185 offset:4096
	ds_read_b128 v[204:207], v185 offset:5120
	ds_read_b128 v[208:211], v185 offset:6144
	ds_read_b128 v[212:215], v185 offset:7168
	s_waitcnt vmcnt(8)
	s_waitcnt lgkmcnt(0)
	s_barrier
	s_waitcnt lgkmcnt(0)
	v_mfma_f32_16x16x32_bf16 v[114:117], v[130:133], v[180:183], v[114:117]
	v_mfma_f32_16x16x32_bf16 v[118:121], v[138:141], v[180:183], v[118:121]
	v_mfma_f32_16x16x32_bf16 v[106:109], v[130:133], v[192:195], v[106:109]
	v_mfma_f32_16x16x32_bf16 v[98:101], v[138:141], v[192:195], v[98:101]
	v_mfma_f32_16x16x32_bf16 v[90:93], v[130:133], v[200:203], v[90:93]
	v_mfma_f32_16x16x32_bf16 v[82:85], v[138:141], v[200:203], v[82:85]
	v_mfma_f32_16x16x32_bf16 v[74:77], v[130:133], v[208:211], v[74:77]
	v_mfma_f32_16x16x32_bf16 v[66:69], v[138:141], v[208:211], v[66:69]
	v_mfma_f32_16x16x32_bf16 v[114:117], v[134:137], v[188:191], v[114:117]
	v_mfma_f32_16x16x32_bf16 v[118:121], v[142:145], v[188:191], v[118:121]
	v_mfma_f32_16x16x32_bf16 v[106:109], v[134:137], v[196:199], v[106:109]
	v_mfma_f32_16x16x32_bf16 v[98:101], v[142:145], v[196:199], v[98:101]
	v_mfma_f32_16x16x32_bf16 v[90:93], v[134:137], v[204:207], v[90:93]
	v_mfma_f32_16x16x32_bf16 v[82:85], v[142:145], v[204:207], v[82:85]
	v_mfma_f32_16x16x32_bf16 v[74:77], v[134:137], v[212:215], v[74:77]
	v_mfma_f32_16x16x32_bf16 v[66:69], v[142:145], v[212:215], v[66:69]
	v_mfma_f32_16x16x32_bf16 v[122:125], v[146:149], v[180:183], v[122:125]
	v_mfma_f32_16x16x32_bf16 v[126:129], v[172:175], v[180:183], v[126:129]
	v_mfma_f32_16x16x32_bf16 v[110:113], v[146:149], v[192:195], v[110:113]
	v_mfma_f32_16x16x32_bf16 v[102:105], v[172:175], v[192:195], v[102:105]
	v_mfma_f32_16x16x32_bf16 v[94:97], v[146:149], v[200:203], v[94:97]
	v_mfma_f32_16x16x32_bf16 v[86:89], v[172:175], v[200:203], v[86:89]
	v_mfma_f32_16x16x32_bf16 v[78:81], v[146:149], v[208:211], v[78:81]
	v_mfma_f32_16x16x32_bf16 v[70:73], v[172:175], v[208:211], v[70:73]
	v_mfma_f32_16x16x32_bf16 v[122:125], v[150:153], v[188:191], v[122:125]
	v_mfma_f32_16x16x32_bf16 v[126:129], v[176:179], v[188:191], v[126:129]
	v_mfma_f32_16x16x32_bf16 v[110:113], v[150:153], v[196:199], v[110:113]
	v_mfma_f32_16x16x32_bf16 v[102:105], v[176:179], v[196:199], v[102:105]
	v_mfma_f32_16x16x32_bf16 v[94:97], v[150:153], v[204:207], v[94:97]
	v_mfma_f32_16x16x32_bf16 v[86:89], v[176:179], v[204:207], v[86:89]
	v_mfma_f32_16x16x32_bf16 v[78:81], v[150:153], v[212:215], v[78:81]
	v_mfma_f32_16x16x32_bf16 v[70:73], v[176:179], v[212:215], v[70:73]
	s_barrier
	s_add_i32 s33, s62, s36
	s_mov_b32 m0, s33
	s_nop 0
	global_load_lds_dwordx4 v156, s[24:25]
	s_add_i32 m0, s33, 0x2000
	s_add_u32 s72, s24, 0x100000
	s_addc_u32 s73, s25, 0
	s_add_i32 s33, s63, s36
	global_load_lds_dwordx4 v160, s[24:25]
	s_mov_b32 m0, s33
	s_add_u32 s100, s28, 0x80
	s_addc_u32 s101, s29, 0
	global_load_lds_dwordx4 v156, s[72:73]
	s_add_i32 m0, s33, 0x2000
	s_nop 0
	global_load_lds_dwordx4 v160, s[72:73]
	s_mov_b32 m0, s23
	s_nop 0
	global_load_lds_dwordx4 v154, s[28:29]
	s_mov_b32 m0, s37
	s_nop 0
	global_load_lds_dwordx4 v158, s[28:29]
	ds_read_b128 v[180:183], v185 offset:16384
	ds_read_b128 v[188:191], v185 offset:17408
	ds_read_b128 v[192:195], v185 offset:18432
	ds_read_b128 v[196:199], v185 offset:19456
	ds_read_b128 v[200:203], v185 offset:20480
	ds_read_b128 v[204:207], v185 offset:21504
	ds_read_b128 v[208:211], v185 offset:22528
	ds_read_b128 v[212:215], v185 offset:23552
	s_waitcnt vmcnt(8)
	s_waitcnt lgkmcnt(0)
	s_barrier
	s_waitcnt lgkmcnt(0)
	v_mfma_f32_16x16x32_bf16 v[58:61], v[130:133], v[180:183], v[58:61]
	v_mfma_f32_16x16x32_bf16 v[54:57], v[138:141], v[180:183], v[54:57]
	v_mfma_f32_16x16x32_bf16 v[42:45], v[130:133], v[192:195], v[42:45]
	v_mfma_f32_16x16x32_bf16 v[34:37], v[138:141], v[192:195], v[34:37]
	v_mfma_f32_16x16x32_bf16 v[26:29], v[130:133], v[200:203], v[26:29]
	v_mfma_f32_16x16x32_bf16 v[18:21], v[138:141], v[200:203], v[18:21]
	v_mfma_f32_16x16x32_bf16 v[6:9], v[130:133], v[208:211], v[6:9]
	v_mfma_f32_16x16x32_bf16 v[2:5], v[138:141], v[208:211], v[2:5]
	v_mfma_f32_16x16x32_bf16 v[58:61], v[134:137], v[188:191], v[58:61]
	v_mfma_f32_16x16x32_bf16 v[54:57], v[142:145], v[188:191], v[54:57]
	v_mfma_f32_16x16x32_bf16 v[42:45], v[134:137], v[196:199], v[42:45]
	v_mfma_f32_16x16x32_bf16 v[34:37], v[142:145], v[196:199], v[34:37]
	v_mfma_f32_16x16x32_bf16 v[26:29], v[134:137], v[204:207], v[26:29]
	v_mfma_f32_16x16x32_bf16 v[18:21], v[142:145], v[204:207], v[18:21]
	v_mfma_f32_16x16x32_bf16 v[6:9], v[134:137], v[212:215], v[6:9]
	v_mfma_f32_16x16x32_bf16 v[2:5], v[142:145], v[212:215], v[2:5]
	v_mfma_f32_16x16x32_bf16 v[62:65], v[146:149], v[180:183], v[62:65]
	v_mfma_f32_16x16x32_bf16 v[50:53], v[172:175], v[180:183], v[50:53]
	v_mfma_f32_16x16x32_bf16 v[46:49], v[146:149], v[192:195], v[46:49]
	v_mfma_f32_16x16x32_bf16 v[38:41], v[172:175], v[192:195], v[38:41]
	v_mfma_f32_16x16x32_bf16 v[30:33], v[146:149], v[200:203], v[30:33]
	v_mfma_f32_16x16x32_bf16 v[22:25], v[172:175], v[200:203], v[22:25]
	v_mfma_f32_16x16x32_bf16 v[10:13], v[146:149], v[208:211], v[10:13]
	v_mfma_f32_16x16x32_bf16 v[14:17], v[172:175], v[208:211], v[14:17]
	v_mfma_f32_16x16x32_bf16 v[62:65], v[150:153], v[188:191], v[62:65]
	v_mfma_f32_16x16x32_bf16 v[50:53], v[176:179], v[188:191], v[50:53]
	v_mfma_f32_16x16x32_bf16 v[46:49], v[150:153], v[196:199], v[46:49]
	v_mfma_f32_16x16x32_bf16 v[38:41], v[176:179], v[196:199], v[38:41]
	v_mfma_f32_16x16x32_bf16 v[30:33], v[150:153], v[204:207], v[30:33]
	v_mfma_f32_16x16x32_bf16 v[22:25], v[176:179], v[204:207], v[22:25]
	v_mfma_f32_16x16x32_bf16 v[10:13], v[150:153], v[212:215], v[10:13]
	v_mfma_f32_16x16x32_bf16 v[14:17], v[176:179], v[212:215], v[14:17]
	s_barrier
; #define PG8_STAGE(bufoff, gbase, voff) do { _Pragma("unroll") for (int _i = 0; _i < 2; ++_i) \
;         __builtin_amdgcn_global_load_lds((const unsigned*)((const char*)(gbase) + (voff)[_i]), (PG8_LAS unsigned*)(lds + (bufoff) + ldsw + _i * 8192), 16, 0, 0); } while (0)
; #define PG8_LDA(dst, b, h) do { _Pragma("unroll") for (int m = 0; m < 4; ++m) _Pragma("unroll") for (int k = 0; k < 2; ++k) dst[m][k] = *(const PG8_LAS bf16x8*)(lds + PG8_SA(b, h) + aoff + m * 2048 + k * 1024); } while (0)
; #define PG8_LDB(dst, b, h) do { _Pragma("unroll") for (int n = 0; n < 2; ++n) _Pragma("unroll") for (int k = 0; k < 2; ++k) dst[n][k] = *(const PG8_LAS bf16x8*)(lds + PG8_SB(b, h) + boff + n * 2048 + k * 1024); } while (0)
; #define PG8_MMA(ai, bj, At, Bt) do { __builtin_amdgcn_s_setprio(1); _Pragma("unroll") for (int m = 0; m < 4; ++m) _Pragma("unroll") for (int n = 0; n < 2; ++n) _Pragma("unroll") for (int k = 0; k < 2; ++k) \
;         acc[ai][bj][m][n] = __builtin_amdgcn_mfma_f32_16x16x32_bf16(Bt[n][k], At[m][k], acc[ai][bj][m][n], 0, 0, 0); __builtin_amdgcn_s_setprio(0); } while (0)
; #define PG8_WAIT_V(n) asm volatile("s_waitcnt vmcnt(" #n ")" ::: "memory")
; #define PG8_WAIT_L(n) asm volatile("s_waitcnt lgkmcnt(" #n ")" ::: "memory")
; #define PG8_BAR __builtin_amdgcn_s_barrier()
; #define PG8_SCHED __builtin_amdgcn_sched_barrier(0)
; template <class Epi, class Sched, bool ALIGN_EPI = false, bool SP2 = false>
; __device__ __forceinline__ void gemm_phase(PG8_LAS unsigned char* lds, const Gemm g, const Sched& S, const Epi& E) {
;     ...
;             PG8_LDB(B0, 1, 0); PG8_LDB(B1, 1, 1); PG8_SCHED; PG8_LDA(At, 1, 0); PG8_STAGE(PG8_SA(0, 1), a2 + hstep, voffA);
;             PG8_WAIT_V(8); PG8_WAIT_L(0); PG8_BAR; PG8_MMA(0, 0, At, B0); PG8_MMA(0, 1, At, B1); PG8_BAR; PG8_SCHED;
;             PG8_LDA(At, 1, 1); PG8_STAGE(PG8_SB(1, 0), b3, voffB); PG8_STAGE(PG8_SB(1, 1), b3 + hstep, voffB); PG8_STAGE(PG8_SA(1, 0), a3, voffA);
;             PG8_WAIT_V(8); PG8_WAIT_L(0); PG8_BAR; PG8_MMA(1, 0, At, B0); PG8_MMA(1, 1, At, B1); PG8_BAR; PG8_SCHED;
	s_add_i32 s33, 0, 0x18000
	s_add_i32 s42, 0, 0x1c000
	s_add_u32 s28, s28, 0x100000
	s_addc_u32 s29, s29, 0
	s_mov_b32 m0, s40
	s_nop 0
	global_load_lds_dwordx4 v154, s[28:29]
	s_mov_b32 m0, s41
	s_nop 0
	global_load_lds_dwordx4 v158, s[28:29]
	ds_read_b128 v[130:133], v241 offset:32768
	ds_read_b128 v[134:137], v241 offset:33792
	ds_read_b128 v[138:141], v241 offset:34816
	ds_read_b128 v[142:145], v241 offset:35840
	ds_read_b128 v[146:149], v241 offset:49152
	ds_read_b128 v[150:153], v241 offset:50176
	ds_read_b128 v[172:175], v241 offset:51200
	ds_read_b128 v[176:179], v241 offset:52224
	ds_read_b128 v[180:183], v185 offset:32768
	ds_read_b128 v[188:191], v185 offset:33792
	ds_read_b128 v[192:195], v185 offset:34816
	ds_read_b128 v[196:199], v185 offset:35840
	ds_read_b128 v[200:203], v185 offset:36864
	ds_read_b128 v[204:207], v185 offset:37888
	ds_read_b128 v[208:211], v185 offset:38912
	ds_read_b128 v[212:215], v185 offset:39936
	s_waitcnt vmcnt(8)
	s_waitcnt lgkmcnt(0)
	s_barrier
	s_waitcnt lgkmcnt(0)
	v_mfma_f32_16x16x32_bf16 v[114:117], v[130:133], v[180:183], v[114:117]
	v_mfma_f32_16x16x32_bf16 v[118:121], v[138:141], v[180:183], v[118:121]
	v_mfma_f32_16x16x32_bf16 v[106:109], v[130:133], v[192:195], v[106:109]
	v_mfma_f32_16x16x32_bf16 v[98:101], v[138:141], v[192:195], v[98:101]
	v_mfma_f32_16x16x32_bf16 v[90:93], v[130:133], v[200:203], v[90:93]
	v_mfma_f32_16x16x32_bf16 v[82:85], v[138:141], v[200:203], v[82:85]
	v_mfma_f32_16x16x32_bf16 v[74:77], v[130:133], v[208:211], v[74:77]
	v_mfma_f32_16x16x32_bf16 v[66:69], v[138:141], v[208:211], v[66:69]
	v_mfma_f32_16x16x32_bf16 v[114:117], v[134:137], v[188:191], v[114:117]
	v_mfma_f32_16x16x32_bf16 v[118:121], v[142:145], v[188:191], v[118:121]
	v_mfma_f32_16x16x32_bf16 v[106:109], v[134:137], v[196:199], v[106:109]
	v_mfma_f32_16x16x32_bf16 v[98:101], v[142:145], v[196:199], v[98:101]
	v_mfma_f32_16x16x32_bf16 v[90:93], v[134:137], v[204:207], v[90:93]
	v_mfma_f32_16x16x32_bf16 v[82:85], v[142:145], v[204:207], v[82:85]
	v_mfma_f32_16x16x32_bf16 v[74:77], v[134:137], v[212:215], v[74:77]
	v_mfma_f32_16x16x32_bf16 v[66:69], v[142:145], v[212:215], v[66:69]
	v_mfma_f32_16x16x32_bf16 v[122:125], v[146:149], v[180:183], v[122:125]
	v_mfma_f32_16x16x32_bf16 v[126:129], v[172:175], v[180:183], v[126:129]
	v_mfma_f32_16x16x32_bf16 v[110:113], v[146:149], v[192:195], v[110:113]
	v_mfma_f32_16x16x32_bf16 v[102:105], v[172:175], v[192:195], v[102:105]
	v_mfma_f32_16x16x32_bf16 v[94:97], v[146:149], v[200:203], v[94:97]
	v_mfma_f32_16x16x32_bf16 v[86:89], v[172:175], v[200:203], v[86:89]
	v_mfma_f32_16x16x32_bf16 v[78:81], v[146:149], v[208:211], v[78:81]
	v_mfma_f32_16x16x32_bf16 v[70:73], v[172:175], v[208:211], v[70:73]
	v_mfma_f32_16x16x32_bf16 v[122:125], v[150:153], v[188:191], v[122:125]
	v_mfma_f32_16x16x32_bf16 v[126:129], v[176:179], v[188:191], v[126:129]
	v_mfma_f32_16x16x32_bf16 v[110:113], v[150:153], v[196:199], v[110:113]
	v_mfma_f32_16x16x32_bf16 v[102:105], v[176:179], v[196:199], v[102:105]
	v_mfma_f32_16x16x32_bf16 v[94:97], v[150:153], v[204:207], v[94:97]
	v_mfma_f32_16x16x32_bf16 v[86:89], v[176:179], v[204:207], v[86:89]
	v_mfma_f32_16x16x32_bf16 v[78:81], v[150:153], v[212:215], v[78:81]
	v_mfma_f32_16x16x32_bf16 v[70:73], v[176:179], v[212:215], v[70:73]
	s_barrier
	s_add_i32 s28, s33, s36
	s_add_i32 m0, s28, 0xffffff80
	s_nop 0
	global_load_lds_dwordx4 v156, s[24:25] offset:128
	s_add_i32 m0, s28, 0x1f80
	s_add_i32 s28, s42, s36
	global_load_lds_dwordx4 v160, s[24:25] offset:128
	s_add_u32 s24, s24, 0x100080
	s_addc_u32 s25, s25, 0
	s_mov_b32 m0, s28
	s_nop 0
	global_load_lds_dwordx4 v156, s[24:25]
	s_add_i32 m0, s28, 0x2000
	s_nop 0
	global_load_lds_dwordx4 v160, s[24:25]
	s_mov_b32 m0, s46
	s_nop 0
	global_load_lds_dwordx4 v154, s[100:101]
	s_mov_b32 m0, s47
	s_nop 0
	global_load_lds_dwordx4 v158, s[100:101]
	ds_read_b128 v[180:183], v185 offset:49152
	ds_read_b128 v[188:191], v185 offset:50176
	ds_read_b128 v[192:195], v185 offset:51200
	ds_read_b128 v[196:199], v185 offset:52224
	ds_read_b128 v[200:203], v185 offset:53248
	ds_read_b128 v[204:207], v185 offset:54272
	ds_read_b128 v[208:211], v185 offset:55296
	ds_read_b128 v[212:215], v185 offset:56320
	s_waitcnt vmcnt(8)
	s_waitcnt lgkmcnt(0)
	s_barrier
	s_waitcnt lgkmcnt(0)
	v_mfma_f32_16x16x32_bf16 v[58:61], v[130:133], v[180:183], v[58:61]
	v_mfma_f32_16x16x32_bf16 v[54:57], v[138:141], v[180:183], v[54:57]
	v_mfma_f32_16x16x32_bf16 v[42:45], v[130:133], v[192:195], v[42:45]
	v_mfma_f32_16x16x32_bf16 v[34:37], v[138:141], v[192:195], v[34:37]
	v_mfma_f32_16x16x32_bf16 v[26:29], v[130:133], v[200:203], v[26:29]
	v_mfma_f32_16x16x32_bf16 v[18:21], v[138:141], v[200:203], v[18:21]
	v_mfma_f32_16x16x32_bf16 v[6:9], v[130:133], v[208:211], v[6:9]
	v_mfma_f32_16x16x32_bf16 v[2:5], v[138:141], v[208:211], v[2:5]
	v_mfma_f32_16x16x32_bf16 v[58:61], v[134:137], v[188:191], v[58:61]
	v_mfma_f32_16x16x32_bf16 v[54:57], v[142:145], v[188:191], v[54:57]
	v_mfma_f32_16x16x32_bf16 v[42:45], v[134:137], v[196:199], v[42:45]
	v_mfma_f32_16x16x32_bf16 v[34:37], v[142:145], v[196:199], v[34:37]
	v_mfma_f32_16x16x32_bf16 v[26:29], v[134:137], v[204:207], v[26:29]
	v_mfma_f32_16x16x32_bf16 v[18:21], v[142:145], v[204:207], v[18:21]
	v_mfma_f32_16x16x32_bf16 v[6:9], v[134:137], v[212:215], v[6:9]
	v_mfma_f32_16x16x32_bf16 v[2:5], v[142:145], v[212:215], v[2:5]
	v_mfma_f32_16x16x32_bf16 v[62:65], v[146:149], v[180:183], v[62:65]
	v_mfma_f32_16x16x32_bf16 v[50:53], v[172:175], v[180:183], v[50:53]
	v_mfma_f32_16x16x32_bf16 v[46:49], v[146:149], v[192:195], v[46:49]
	v_mfma_f32_16x16x32_bf16 v[38:41], v[172:175], v[192:195], v[38:41]
	v_mfma_f32_16x16x32_bf16 v[30:33], v[146:149], v[200:203], v[30:33]
	v_mfma_f32_16x16x32_bf16 v[22:25], v[172:175], v[200:203], v[22:25]
	v_mfma_f32_16x16x32_bf16 v[10:13], v[146:149], v[208:211], v[10:13]
	v_mfma_f32_16x16x32_bf16 v[14:17], v[172:175], v[208:211], v[14:17]
	v_mfma_f32_16x16x32_bf16 v[62:65], v[150:153], v[188:191], v[62:65]
	v_mfma_f32_16x16x32_bf16 v[50:53], v[176:179], v[188:191], v[50:53]
	v_mfma_f32_16x16x32_bf16 v[46:49], v[150:153], v[196:199], v[46:49]
	v_mfma_f32_16x16x32_bf16 v[38:41], v[176:179], v[196:199], v[38:41]
	v_mfma_f32_16x16x32_bf16 v[30:33], v[150:153], v[204:207], v[30:33]
	v_mfma_f32_16x16x32_bf16 v[22:25], v[176:179], v[204:207], v[22:25]
	v_mfma_f32_16x16x32_bf16 v[10:13], v[150:153], v[212:215], v[10:13]
	v_mfma_f32_16x16x32_bf16 v[14:17], v[176:179], v[212:215], v[14:17]
	s_barrier
	s_add_i32 s68, s68, 2
	s_add_u32 s26, s26, 0x100
	s_addc_u32 s27, s27, 0
	s_add_u32 s66, s66, 0x100
	s_addc_u32 s67, s67, 0
	s_cmp_gt_u32 s68, 61
	s_cbranch_scc0 .LBB0_1039


; #define PG8_BAR __builtin_amdgcn_s_barrier()
; template <class Epi, class Sched, bool ALIGN_EPI = false, bool SP2 = false>
; __device__ __forceinline__ void gemm_phase(PG8_LAS unsigned char* lds, const Gemm g, const Sched& S, const Epi& E) {
;     ...
;         if constexpr (ALIGN_EPI) { if (wr == 0) PG8_BAR; }
	s_and_b64 vcc, exec, s[10:11]
	s_cbranch_vccz .LBB0_1042
	s_barrier

; #define PG8_STAGE(bufoff, gbase, voff) do { _Pragma("unroll") for (int _i = 0; _i < 2; ++_i) \
;         __builtin_amdgcn_global_load_lds((const unsigned*)((const char*)(gbase) + (voff)[_i]), (PG8_LAS unsigned*)(lds + (bufoff) + ldsw + _i * 8192), 16, 0, 0); } while (0)
; #define PG8_LDA(dst, b, h) do { _Pragma("unroll") for (int m = 0; m < 4; ++m) _Pragma("unroll") for (int k = 0; k < 2; ++k) dst[m][k] = *(const PG8_LAS bf16x8*)(lds + PG8_SA(b, h) + aoff + m * 2048 + k * 1024); } while (0)
; #define PG8_LDB(dst, b, h) do { _Pragma("unroll") for (int n = 0; n < 2; ++n) _Pragma("unroll") for (int k = 0; k < 2; ++k) dst[n][k] = *(const PG8_LAS bf16x8*)(lds + PG8_SB(b, h) + boff + n * 2048 + k * 1024); } while (0)
; #define PG8_MMA(ai, bj, At, Bt) do { __builtin_amdgcn_s_setprio(1); _Pragma("unroll") for (int m = 0; m < 4; ++m) _Pragma("unroll") for (int n = 0; n < 2; ++n) _Pragma("unroll") for (int k = 0; k < 2; ++k) \
;         acc[ai][bj][m][n] = __builtin_amdgcn_mfma_f32_16x16x32_bf16(Bt[n][k], At[m][k], acc[ai][bj][m][n], 0, 0, 0); __builtin_amdgcn_s_setprio(0); } while (0)
; #define PG8_WAIT_V(n) asm volatile("s_waitcnt vmcnt(" #n ")" ::: "memory")
; #define PG8_WAIT_L(n) asm volatile("s_waitcnt lgkmcnt(" #n ")" ::: "memory")
; template <class Epi, class Sched, bool ALIGN_EPI = false, bool SP2 = false>
; __device__ __forceinline__ void gemm_phase(PG8_LAS unsigned char* lds, const Gemm g, const Sched& S, const Epi& E) {
;     ...
;             const bool last = (t == nt - 2);
;             const char* a1 = cA + (size_t)(t + 1) * kstep;
;             const char* a2 = last ? nA : cA + (size_t)(t + 2) * kstep; const char* b2 = last ? nB : cB + (size_t)(t + 2) * kstep;
;             const char* a3 = a2 + kstep; const char* b3 = b2 + kstep;
;             if (last && has_next) S.a_ready(nxt);
;             if constexpr (SP2) {
;             PG8_LDB(B0, 0, 0); PG8_LDB(B1, 0, 1); PG8_SCHED; PG8_LDA(At, 0, 0); PG8_STAGE(PG8_SA(1, 1), a1 + hstep, voffA);
;             PG8_WAIT_V(8); PG8_WAIT_L(0); PG8_BAR; PG8_MMA(0, 0, At, B0); PG8_MMA(0, 1, At, B1); PG8_BAR; PG8_SCHED;
;             PG8_LDA(At, 0, 1); PG8_STAGE(PG8_SB(0, 0), b2, voffB); PG8_STAGE(PG8_SB(0, 1), b2 + hstep, voffB); PG8_STAGE(PG8_SA(0, 0), a2, voffA);
;             PG8_WAIT_V(8); PG8_WAIT_L(0); PG8_BAR; PG8_MMA(1, 0, At, B0); PG8_MMA(1, 1, At, B1); PG8_BAR; PG8_SCHED;
.LBB0_1126:
	s_add_u32 s22, s24, 0xfff00080
	s_addc_u32 s23, s25, -1
	s_cmp_eq_u32 s68, 60
	s_cselect_b32 s27, s15, s23
	s_cselect_b32 s26, s64, s22
	s_cselect_b32 s23, s13, s67
	s_cselect_b32 s22, s65, s66
	s_add_i32 m0, s21, 0xc000
	s_nop 0
	global_load_lds_dwordx4 v138, s[24:25]
	s_add_i32 m0, s21, 0xe000
	s_nop 0
	global_load_lds_dwordx4 v140, s[24:25]
	ds_read_b128 v[160:163], v241 offset:0
	ds_read_b128 v[166:169], v241 offset:1024
	ds_read_b128 v[170:173], v241 offset:2048
	ds_read_b128 v[174:177], v241 offset:3072
	ds_read_b128 v[178:181], v241 offset:16384
	ds_read_b128 v[182:185], v241 offset:17408
	ds_read_b128 v[186:189], v241 offset:18432
	ds_read_b128 v[190:193], v241 offset:19456
	ds_read_b128 v[194:197], v155
	ds_read_b128 v[198:201], v155 offset:1024
	ds_read_b128 v[202:205], v155 offset:2048
	ds_read_b128 v[206:209], v155 offset:3072
	ds_read_b128 v[210:213], v155 offset:4096
	ds_read_b128 v[214:217], v155 offset:5120
	ds_read_b128 v[218:221], v155 offset:6144
	ds_read_b128 v[222:225], v155 offset:7168
	s_waitcnt vmcnt(8)
	s_waitcnt lgkmcnt(0)
	s_barrier
	s_waitcnt lgkmcnt(0)
	v_mfma_f32_16x16x32_bf16 v[122:125], v[160:163], v[194:197], v[122:125]
	v_mfma_f32_16x16x32_bf16 v[114:117], v[170:173], v[194:197], v[114:117]
	v_mfma_f32_16x16x32_bf16 v[106:109], v[160:163], v[202:205], v[106:109]
	v_mfma_f32_16x16x32_bf16 v[98:101], v[170:173], v[202:205], v[98:101]
	v_mfma_f32_16x16x32_bf16 v[90:93], v[160:163], v[210:213], v[90:93]
	v_mfma_f32_16x16x32_bf16 v[82:85], v[170:173], v[210:213], v[82:85]
	v_mfma_f32_16x16x32_bf16 v[74:77], v[160:163], v[218:221], v[74:77]
	v_mfma_f32_16x16x32_bf16 v[62:65], v[170:173], v[218:221], v[62:65]
	v_mfma_f32_16x16x32_bf16 v[122:125], v[166:169], v[198:201], v[122:125]
	v_mfma_f32_16x16x32_bf16 v[114:117], v[174:177], v[198:201], v[114:117]
	v_mfma_f32_16x16x32_bf16 v[106:109], v[166:169], v[206:209], v[106:109]
	v_mfma_f32_16x16x32_bf16 v[98:101], v[174:177], v[206:209], v[98:101]
	v_mfma_f32_16x16x32_bf16 v[90:93], v[166:169], v[214:217], v[90:93]
	v_mfma_f32_16x16x32_bf16 v[82:85], v[174:177], v[214:217], v[82:85]
	v_mfma_f32_16x16x32_bf16 v[74:77], v[166:169], v[222:225], v[74:77]
	v_mfma_f32_16x16x32_bf16 v[62:65], v[174:177], v[222:225], v[62:65]
	v_mfma_f32_16x16x32_bf16 v[126:129], v[178:181], v[194:197], v[126:129]
	v_mfma_f32_16x16x32_bf16 v[118:121], v[186:189], v[194:197], v[118:121]
	v_mfma_f32_16x16x32_bf16 v[110:113], v[178:181], v[202:205], v[110:113]
	v_mfma_f32_16x16x32_bf16 v[102:105], v[186:189], v[202:205], v[102:105]
	v_mfma_f32_16x16x32_bf16 v[94:97], v[178:181], v[210:213], v[94:97]
	v_mfma_f32_16x16x32_bf16 v[86:89], v[186:189], v[210:213], v[86:89]
	v_mfma_f32_16x16x32_bf16 v[78:81], v[178:181], v[218:221], v[78:81]
	v_mfma_f32_16x16x32_bf16 v[70:73], v[186:189], v[218:221], v[70:73]
	v_mfma_f32_16x16x32_bf16 v[126:129], v[182:185], v[198:201], v[126:129]
	v_mfma_f32_16x16x32_bf16 v[118:121], v[190:193], v[198:201], v[118:121]
	v_mfma_f32_16x16x32_bf16 v[110:113], v[182:185], v[206:209], v[110:113]
	v_mfma_f32_16x16x32_bf16 v[102:105], v[190:193], v[206:209], v[102:105]
	v_mfma_f32_16x16x32_bf16 v[94:97], v[182:185], v[214:217], v[94:97]
	v_mfma_f32_16x16x32_bf16 v[86:89], v[190:193], v[214:217], v[86:89]
	v_mfma_f32_16x16x32_bf16 v[78:81], v[182:185], v[222:225], v[78:81]
	v_mfma_f32_16x16x32_bf16 v[70:73], v[190:193], v[222:225], v[70:73]
	s_barrier
	s_add_i32 s33, s52, s29
	s_mov_b32 m0, s33
	s_nop 0
	global_load_lds_dwordx4 v132, s[22:23]
	s_add_i32 m0, s33, 0x2000
	s_add_u32 s72, s22, 0x100000
	s_addc_u32 s73, s23, 0
	s_add_i32 s33, s53, s29
	global_load_lds_dwordx4 v136, s[22:23]
	s_mov_b32 m0, s33
	s_add_u32 s100, s26, 0x80
	s_addc_u32 s101, s27, 0
	global_load_lds_dwordx4 v132, s[72:73]
	s_add_i32 m0, s33, 0x2000
	s_nop 0
	global_load_lds_dwordx4 v136, s[72:73]
	s_mov_b32 m0, s21
	s_nop 0
	global_load_lds_dwordx4 v130, s[26:27]
	s_mov_b32 m0, s36
	s_nop 0
	global_load_lds_dwordx4 v134, s[26:27]
	ds_read_b128 v[194:197], v155 offset:16384
	ds_read_b128 v[198:201], v155 offset:17408
	ds_read_b128 v[202:205], v155 offset:18432
	ds_read_b128 v[206:209], v155 offset:19456
	ds_read_b128 v[210:213], v155 offset:20480
	ds_read_b128 v[214:217], v155 offset:21504
	ds_read_b128 v[218:221], v155 offset:22528
	ds_read_b128 v[222:225], v155 offset:23552
	s_waitcnt vmcnt(8)
	s_waitcnt lgkmcnt(0)
	s_barrier
	s_waitcnt lgkmcnt(0)
	v_mfma_f32_16x16x32_bf16 v[58:61], v[160:163], v[194:197], v[58:61]
	v_mfma_f32_16x16x32_bf16 v[50:53], v[170:173], v[194:197], v[50:53]
	v_mfma_f32_16x16x32_bf16 v[42:45], v[160:163], v[202:205], v[42:45]
	v_mfma_f32_16x16x32_bf16 v[34:37], v[170:173], v[202:205], v[34:37]
	v_mfma_f32_16x16x32_bf16 v[26:29], v[160:163], v[210:213], v[26:29]
	v_mfma_f32_16x16x32_bf16 v[18:21], v[170:173], v[210:213], v[18:21]
	v_mfma_f32_16x16x32_bf16 v[10:13], v[160:163], v[218:221], v[10:13]
	v_mfma_f32_16x16x32_bf16 v[2:5], v[170:173], v[218:221], v[2:5]
	v_mfma_f32_16x16x32_bf16 v[58:61], v[166:169], v[198:201], v[58:61]
	v_mfma_f32_16x16x32_bf16 v[50:53], v[174:177], v[198:201], v[50:53]
	v_mfma_f32_16x16x32_bf16 v[42:45], v[166:169], v[206:209], v[42:45]
	v_mfma_f32_16x16x32_bf16 v[34:37], v[174:177], v[206:209], v[34:37]
	v_mfma_f32_16x16x32_bf16 v[26:29], v[166:169], v[214:217], v[26:29]
	v_mfma_f32_16x16x32_bf16 v[18:21], v[174:177], v[214:217], v[18:21]
	v_mfma_f32_16x16x32_bf16 v[10:13], v[166:169], v[222:225], v[10:13]
	v_mfma_f32_16x16x32_bf16 v[2:5], v[174:177], v[222:225], v[2:5]
	v_mfma_f32_16x16x32_bf16 v[66:69], v[178:181], v[194:197], v[66:69]
	v_mfma_f32_16x16x32_bf16 v[54:57], v[186:189], v[194:197], v[54:57]
	v_mfma_f32_16x16x32_bf16 v[46:49], v[178:181], v[202:205], v[46:49]
	v_mfma_f32_16x16x32_bf16 v[38:41], v[186:189], v[202:205], v[38:41]
	v_mfma_f32_16x16x32_bf16 v[30:33], v[178:181], v[210:213], v[30:33]
	v_mfma_f32_16x16x32_bf16 v[22:25], v[186:189], v[210:213], v[22:25]
	v_mfma_f32_16x16x32_bf16 v[14:17], v[178:181], v[218:221], v[14:17]
	v_mfma_f32_16x16x32_bf16 v[6:9], v[186:189], v[218:221], v[6:9]
	v_mfma_f32_16x16x32_bf16 v[66:69], v[182:185], v[198:201], v[66:69]
	v_mfma_f32_16x16x32_bf16 v[54:57], v[190:193], v[198:201], v[54:57]
	v_mfma_f32_16x16x32_bf16 v[46:49], v[182:185], v[206:209], v[46:49]
	v_mfma_f32_16x16x32_bf16 v[38:41], v[190:193], v[206:209], v[38:41]
	v_mfma_f32_16x16x32_bf16 v[30:33], v[182:185], v[214:217], v[30:33]
	v_mfma_f32_16x16x32_bf16 v[22:25], v[190:193], v[214:217], v[22:25]
	v_mfma_f32_16x16x32_bf16 v[14:17], v[182:185], v[222:225], v[14:17]
	v_mfma_f32_16x16x32_bf16 v[6:9], v[190:193], v[222:225], v[6:9]
	s_barrier
; #define PG8_STAGE(bufoff, gbase, voff) do { _Pragma("unroll") for (int _i = 0; _i < 2; ++_i) \
;         __builtin_amdgcn_global_load_lds((const unsigned*)((const char*)(gbase) + (voff)[_i]), (PG8_LAS unsigned*)(lds + (bufoff) + ldsw + _i * 8192), 16, 0, 0); } while (0)
; #define PG8_LDA(dst, b, h) do { _Pragma("unroll") for (int m = 0; m < 4; ++m) _Pragma("unroll") for (int k = 0; k < 2; ++k) dst[m][k] = *(const PG8_LAS bf16x8*)(lds + PG8_SA(b, h) + aoff + m * 2048 + k * 1024); } while (0)
; #define PG8_LDB(dst, b, h) do { _Pragma("unroll") for (int n = 0; n < 2; ++n) _Pragma("unroll") for (int k = 0; k < 2; ++k) dst[n][k] = *(const PG8_LAS bf16x8*)(lds + PG8_SB(b, h) + boff + n * 2048 + k * 1024); } while (0)
; #define PG8_MMA(ai, bj, At, Bt) do { __builtin_amdgcn_s_setprio(1); _Pragma("unroll") for (int m = 0; m < 4; ++m) _Pragma("unroll") for (int n = 0; n < 2; ++n) _Pragma("unroll") for (int k = 0; k < 2; ++k) \
;         acc[ai][bj][m][n] = __builtin_amdgcn_mfma_f32_16x16x32_bf16(Bt[n][k], At[m][k], acc[ai][bj][m][n], 0, 0, 0); __builtin_amdgcn_s_setprio(0); } while (0)
; #define PG8_WAIT_V(n) asm volatile("s_waitcnt vmcnt(" #n ")" ::: "memory")
; #define PG8_WAIT_L(n) asm volatile("s_waitcnt lgkmcnt(" #n ")" ::: "memory")
; #define PG8_BAR __builtin_amdgcn_s_barrier()
; #define PG8_SCHED __builtin_amdgcn_sched_barrier(0)
; template <class Epi, class Sched, bool ALIGN_EPI = false, bool SP2 = false>
; __device__ __forceinline__ void gemm_phase(PG8_LAS unsigned char* lds, const Gemm g, const Sched& S, const Epi& E) {
;     ...
;             PG8_LDB(B0, 1, 0); PG8_LDB(B1, 1, 1); PG8_SCHED; PG8_LDA(At, 1, 0); PG8_STAGE(PG8_SA(0, 1), a2 + hstep, voffA);
;             PG8_WAIT_V(8); PG8_WAIT_L(0); PG8_BAR; PG8_MMA(0, 0, At, B0); PG8_MMA(0, 1, At, B1); PG8_BAR; PG8_SCHED;
;             PG8_LDA(At, 1, 1); PG8_STAGE(PG8_SB(1, 0), b3, voffB); PG8_STAGE(PG8_SB(1, 1), b3 + hstep, voffB); PG8_STAGE(PG8_SA(1, 0), a3, voffA);
;             PG8_WAIT_V(8); PG8_WAIT_L(0); PG8_BAR; PG8_MMA(1, 0, At, B0); PG8_MMA(1, 1, At, B1); PG8_BAR; PG8_SCHED;
	s_add_i32 s33, 0, 0x18000
	s_add_i32 s42, 0, 0x1c000
	s_add_u32 s26, s26, 0x100000
	s_addc_u32 s27, s27, 0
	s_mov_b32 m0, s37
	s_nop 0
	global_load_lds_dwordx4 v130, s[26:27]
	s_mov_b32 m0, s40
	s_nop 0
	global_load_lds_dwordx4 v134, s[26:27]
	ds_read_b128 v[160:163], v241 offset:32768
	ds_read_b128 v[166:169], v241 offset:33792
	ds_read_b128 v[170:173], v241 offset:34816
	ds_read_b128 v[174:177], v241 offset:35840
	ds_read_b128 v[178:181], v241 offset:49152
	ds_read_b128 v[182:185], v241 offset:50176
	ds_read_b128 v[186:189], v241 offset:51200
	ds_read_b128 v[190:193], v241 offset:52224
	ds_read_b128 v[194:197], v155 offset:32768
	ds_read_b128 v[198:201], v155 offset:33792
	ds_read_b128 v[202:205], v155 offset:34816
	ds_read_b128 v[206:209], v155 offset:35840
	ds_read_b128 v[210:213], v155 offset:36864
	ds_read_b128 v[214:217], v155 offset:37888
	ds_read_b128 v[218:221], v155 offset:38912
	ds_read_b128 v[222:225], v155 offset:39936
	s_waitcnt vmcnt(8)
	s_waitcnt lgkmcnt(0)
	s_barrier
	s_waitcnt lgkmcnt(0)
	v_mfma_f32_16x16x32_bf16 v[122:125], v[160:163], v[194:197], v[122:125]
	v_mfma_f32_16x16x32_bf16 v[114:117], v[170:173], v[194:197], v[114:117]
	v_mfma_f32_16x16x32_bf16 v[106:109], v[160:163], v[202:205], v[106:109]
	v_mfma_f32_16x16x32_bf16 v[98:101], v[170:173], v[202:205], v[98:101]
	v_mfma_f32_16x16x32_bf16 v[90:93], v[160:163], v[210:213], v[90:93]
	v_mfma_f32_16x16x32_bf16 v[82:85], v[170:173], v[210:213], v[82:85]
	v_mfma_f32_16x16x32_bf16 v[74:77], v[160:163], v[218:221], v[74:77]
	v_mfma_f32_16x16x32_bf16 v[62:65], v[170:173], v[218:221], v[62:65]
	v_mfma_f32_16x16x32_bf16 v[122:125], v[166:169], v[198:201], v[122:125]
	v_mfma_f32_16x16x32_bf16 v[114:117], v[174:177], v[198:201], v[114:117]
	v_mfma_f32_16x16x32_bf16 v[106:109], v[166:169], v[206:209], v[106:109]
	v_mfma_f32_16x16x32_bf16 v[98:101], v[174:177], v[206:209], v[98:101]
	v_mfma_f32_16x16x32_bf16 v[90:93], v[166:169], v[214:217], v[90:93]
	v_mfma_f32_16x16x32_bf16 v[82:85], v[174:177], v[214:217], v[82:85]
	v_mfma_f32_16x16x32_bf16 v[74:77], v[166:169], v[222:225], v[74:77]
	v_mfma_f32_16x16x32_bf16 v[62:65], v[174:177], v[222:225], v[62:65]
	v_mfma_f32_16x16x32_bf16 v[126:129], v[178:181], v[194:197], v[126:129]
	v_mfma_f32_16x16x32_bf16 v[118:121], v[186:189], v[194:197], v[118:121]
	v_mfma_f32_16x16x32_bf16 v[110:113], v[178:181], v[202:205], v[110:113]
	v_mfma_f32_16x16x32_bf16 v[102:105], v[186:189], v[202:205], v[102:105]
	v_mfma_f32_16x16x32_bf16 v[94:97], v[178:181], v[210:213], v[94:97]
	v_mfma_f32_16x16x32_bf16 v[86:89], v[186:189], v[210:213], v[86:89]
	v_mfma_f32_16x16x32_bf16 v[78:81], v[178:181], v[218:221], v[78:81]
	v_mfma_f32_16x16x32_bf16 v[70:73], v[186:189], v[218:221], v[70:73]
	v_mfma_f32_16x16x32_bf16 v[126:129], v[182:185], v[198:201], v[126:129]
	v_mfma_f32_16x16x32_bf16 v[118:121], v[190:193], v[198:201], v[118:121]
	v_mfma_f32_16x16x32_bf16 v[110:113], v[182:185], v[206:209], v[110:113]
	v_mfma_f32_16x16x32_bf16 v[102:105], v[190:193], v[206:209], v[102:105]
	v_mfma_f32_16x16x32_bf16 v[94:97], v[182:185], v[214:217], v[94:97]
	v_mfma_f32_16x16x32_bf16 v[86:89], v[190:193], v[214:217], v[86:89]
	v_mfma_f32_16x16x32_bf16 v[78:81], v[182:185], v[222:225], v[78:81]
	v_mfma_f32_16x16x32_bf16 v[70:73], v[190:193], v[222:225], v[70:73]
	s_barrier
	s_add_i32 s26, s33, s29
	s_add_i32 m0, s26, 0xffffff80
	s_nop 0
	global_load_lds_dwordx4 v132, s[22:23] offset:128
	s_add_i32 m0, s26, 0x1f80
	s_add_i32 s26, s42, s29
	global_load_lds_dwordx4 v136, s[22:23] offset:128
	s_add_u32 s22, s22, 0x100080
	s_addc_u32 s23, s23, 0
	s_mov_b32 m0, s26
	s_nop 0
	global_load_lds_dwordx4 v132, s[22:23]
	s_add_i32 m0, s26, 0x2000
	s_nop 0
	global_load_lds_dwordx4 v136, s[22:23]
	s_mov_b32 m0, s46
	s_nop 0
	global_load_lds_dwordx4 v130, s[100:101]
	s_mov_b32 m0, s47
	s_nop 0
	global_load_lds_dwordx4 v134, s[100:101]
	ds_read_b128 v[194:197], v155 offset:49152
	ds_read_b128 v[198:201], v155 offset:50176
	ds_read_b128 v[202:205], v155 offset:51200
	ds_read_b128 v[206:209], v155 offset:52224
	ds_read_b128 v[210:213], v155 offset:53248
	ds_read_b128 v[214:217], v155 offset:54272
	ds_read_b128 v[218:221], v155 offset:55296
	ds_read_b128 v[222:225], v155 offset:56320
	s_waitcnt vmcnt(8)
	s_waitcnt lgkmcnt(0)
	s_barrier
	s_waitcnt lgkmcnt(0)
	v_mfma_f32_16x16x32_bf16 v[58:61], v[160:163], v[194:197], v[58:61]
	v_mfma_f32_16x16x32_bf16 v[50:53], v[170:173], v[194:197], v[50:53]
	v_mfma_f32_16x16x32_bf16 v[42:45], v[160:163], v[202:205], v[42:45]
	v_mfma_f32_16x16x32_bf16 v[34:37], v[170:173], v[202:205], v[34:37]
	v_mfma_f32_16x16x32_bf16 v[26:29], v[160:163], v[210:213], v[26:29]
	v_mfma_f32_16x16x32_bf16 v[18:21], v[170:173], v[210:213], v[18:21]
	v_mfma_f32_16x16x32_bf16 v[10:13], v[160:163], v[218:221], v[10:13]
	v_mfma_f32_16x16x32_bf16 v[2:5], v[170:173], v[218:221], v[2:5]
	v_mfma_f32_16x16x32_bf16 v[58:61], v[166:169], v[198:201], v[58:61]
	v_mfma_f32_16x16x32_bf16 v[50:53], v[174:177], v[198:201], v[50:53]
	v_mfma_f32_16x16x32_bf16 v[42:45], v[166:169], v[206:209], v[42:45]
	v_mfma_f32_16x16x32_bf16 v[34:37], v[174:177], v[206:209], v[34:37]
	v_mfma_f32_16x16x32_bf16 v[26:29], v[166:169], v[214:217], v[26:29]
	v_mfma_f32_16x16x32_bf16 v[18:21], v[174:177], v[214:217], v[18:21]
	v_mfma_f32_16x16x32_bf16 v[10:13], v[166:169], v[222:225], v[10:13]
	v_mfma_f32_16x16x32_bf16 v[2:5], v[174:177], v[222:225], v[2:5]
	v_mfma_f32_16x16x32_bf16 v[66:69], v[178:181], v[194:197], v[66:69]
	v_mfma_f32_16x16x32_bf16 v[54:57], v[186:189], v[194:197], v[54:57]
	v_mfma_f32_16x16x32_bf16 v[46:49], v[178:181], v[202:205], v[46:49]
	v_mfma_f32_16x16x32_bf16 v[38:41], v[186:189], v[202:205], v[38:41]
	v_mfma_f32_16x16x32_bf16 v[30:33], v[178:181], v[210:213], v[30:33]
	v_mfma_f32_16x16x32_bf16 v[22:25], v[186:189], v[210:213], v[22:25]
	v_mfma_f32_16x16x32_bf16 v[14:17], v[178:181], v[218:221], v[14:17]
	v_mfma_f32_16x16x32_bf16 v[6:9], v[186:189], v[218:221], v[6:9]
	v_mfma_f32_16x16x32_bf16 v[66:69], v[182:185], v[198:201], v[66:69]
	v_mfma_f32_16x16x32_bf16 v[54:57], v[190:193], v[198:201], v[54:57]
	v_mfma_f32_16x16x32_bf16 v[46:49], v[182:185], v[206:209], v[46:49]
	v_mfma_f32_16x16x32_bf16 v[38:41], v[190:193], v[206:209], v[38:41]
	v_mfma_f32_16x16x32_bf16 v[30:33], v[182:185], v[214:217], v[30:33]
	v_mfma_f32_16x16x32_bf16 v[22:25], v[190:193], v[214:217], v[22:25]
	v_mfma_f32_16x16x32_bf16 v[14:17], v[182:185], v[222:225], v[14:17]
	v_mfma_f32_16x16x32_bf16 v[6:9], v[190:193], v[222:225], v[6:9]
	s_barrier
	s_add_i32 s68, s68, 2
	s_add_u32 s24, s24, 0x100
	s_addc_u32 s25, s25, 0
	s_add_u32 s66, s66, 0x100
	s_addc_u32 s67, s67, 0
	s_cmp_gt_u32 s68, 61
	s_cbranch_scc0 .LBB0_1126


; #define PG8_BAR __builtin_amdgcn_s_barrier()
; template <class Epi, class Sched, bool ALIGN_EPI = false, bool SP2 = false>
; __device__ __forceinline__ void gemm_phase(PG8_LAS unsigned char* lds, const Gemm g, const Sched& S, const Epi& E) {
;     ...
;         }
;         if constexpr (ALIGN_EPI) { if (wr == 0) PG8_BAR; }
	s_and_b64 vcc, exec, s[8:9]
	s_cbranch_vccz .LBB0_1129
	s_barrier

; #define PG8_STAGE(bufoff, gbase, voff) do { _Pragma("unroll") for (int _i = 0; _i < 2; ++_i) \
;         __builtin_amdgcn_global_load_lds((const unsigned*)((const char*)(gbase) + (voff)[_i]), (PG8_LAS unsigned*)(lds + (bufoff) + ldsw + _i * 8192), 16, 0, 0); } while (0)
; #define PG8_LDA(dst, b, h) do { _Pragma("unroll") for (int m = 0; m < 4; ++m) _Pragma("unroll") for (int k = 0; k < 2; ++k) dst[m][k] = *(const PG8_LAS bf16x8*)(lds + PG8_SA(b, h) + aoff + m * 2048 + k * 1024); } while (0)
; #define PG8_LDB(dst, b, h) do { _Pragma("unroll") for (int n = 0; n < 2; ++n) _Pragma("unroll") for (int k = 0; k < 2; ++k) dst[n][k] = *(const PG8_LAS bf16x8*)(lds + PG8_SB(b, h) + boff + n * 2048 + k * 1024); } while (0)
; #define PG8_MMA(ai, bj, At, Bt) do { __builtin_amdgcn_s_setprio(1); _Pragma("unroll") for (int m = 0; m < 4; ++m) _Pragma("unroll") for (int n = 0; n < 2; ++n) _Pragma("unroll") for (int k = 0; k < 2; ++k) \
;         acc[ai][bj][m][n] = __builtin_amdgcn_mfma_f32_16x16x32_bf16(Bt[n][k], At[m][k], acc[ai][bj][m][n], 0, 0, 0); __builtin_amdgcn_s_setprio(0); } while (0)
; #define PG8_WAIT_V(n) asm volatile("s_waitcnt vmcnt(" #n ")" ::: "memory")
; #define PG8_WAIT_L(n) asm volatile("s_waitcnt lgkmcnt(" #n ")" ::: "memory")
; #define PG8_BAR __builtin_amdgcn_s_barrier()
; #define PG8_SCHED __builtin_amdgcn_sched_barrier(0)
; template <class Epi, class Sched, bool ALIGN_EPI = false, bool SP2 = false>
; __device__ __forceinline__ void gemm_phase(PG8_LAS unsigned char* lds, const Gemm g, const Sched& S, const Epi& E) {
;     ...
;             PG8_LDB(B0, 0, 0); PG8_LDB(B1, 0, 1); PG8_SCHED; PG8_LDA(At, 0, 0); PG8_STAGE(PG8_SA(1, 1), a1 + hstep, voffA);
;             PG8_WAIT_V(8); PG8_WAIT_L(0); PG8_BAR; PG8_MMA(0, 0, At, B0); PG8_MMA(0, 1, At, B1); PG8_BAR; PG8_SCHED;
;             PG8_LDA(At, 0, 1); PG8_STAGE(PG8_SB(0, 0), b2, voffB); PG8_STAGE(PG8_SB(0, 1), b2 + hstep, voffB); PG8_STAGE(PG8_SA(0, 0), a2, voffA);
;             PG8_WAIT_V(8); PG8_WAIT_L(0); PG8_BAR; PG8_MMA(1, 0, At, B0); PG8_MMA(1, 1, At, B1); PG8_BAR; PG8_SCHED;
.LBB0_1245:
	s_add_u32 s16, s18, 0xffd50080
	s_addc_u32 s17, s19, -1
	s_cmpk_eq_i32 s64, 0xa8
	s_cselect_b32 s21, s5, s17
	s_cselect_b32 s20, s4, s16
	s_cselect_b32 s17, s15, s63
	s_cselect_b32 s16, s14, s62
	s_add_i32 m0, s25, 0xc000
	s_nop 0
	global_load_lds_dwordx4 v162, s[18:19]
	s_add_i32 m0, s25, 0xe000
	s_nop 0
	global_load_lds_dwordx4 v166, s[18:19]
	ds_read_b128 v[130:133], v241 offset:0
	ds_read_b128 v[134:137], v241 offset:1024
	ds_read_b128 v[138:141], v241 offset:2048
	ds_read_b128 v[142:145], v241 offset:3072
	ds_read_b128 v[146:149], v241 offset:16384
	ds_read_b128 v[150:153], v241 offset:17408
	ds_read_b128 v[172:175], v241 offset:18432
	ds_read_b128 v[176:179], v241 offset:19456
	ds_read_b128 v[180:183], v185
	ds_read_b128 v[188:191], v185 offset:1024
	ds_read_b128 v[192:195], v185 offset:2048
	ds_read_b128 v[196:199], v185 offset:3072
	ds_read_b128 v[200:203], v185 offset:4096
	ds_read_b128 v[204:207], v185 offset:5120
	ds_read_b128 v[208:211], v185 offset:6144
	ds_read_b128 v[212:215], v185 offset:7168
	s_waitcnt vmcnt(8)
	s_waitcnt lgkmcnt(0)
	s_barrier
	s_waitcnt lgkmcnt(0)
	v_mfma_f32_16x16x32_bf16 v[114:117], v[130:133], v[180:183], v[114:117]
	v_mfma_f32_16x16x32_bf16 v[118:121], v[138:141], v[180:183], v[118:121]
	v_mfma_f32_16x16x32_bf16 v[106:109], v[130:133], v[192:195], v[106:109]
	v_mfma_f32_16x16x32_bf16 v[98:101], v[138:141], v[192:195], v[98:101]
	v_mfma_f32_16x16x32_bf16 v[90:93], v[130:133], v[200:203], v[90:93]
	v_mfma_f32_16x16x32_bf16 v[82:85], v[138:141], v[200:203], v[82:85]
	v_mfma_f32_16x16x32_bf16 v[74:77], v[130:133], v[208:211], v[74:77]
	v_mfma_f32_16x16x32_bf16 v[66:69], v[138:141], v[208:211], v[66:69]
	v_mfma_f32_16x16x32_bf16 v[114:117], v[134:137], v[188:191], v[114:117]
	v_mfma_f32_16x16x32_bf16 v[118:121], v[142:145], v[188:191], v[118:121]
	v_mfma_f32_16x16x32_bf16 v[106:109], v[134:137], v[196:199], v[106:109]
	v_mfma_f32_16x16x32_bf16 v[98:101], v[142:145], v[196:199], v[98:101]
	v_mfma_f32_16x16x32_bf16 v[90:93], v[134:137], v[204:207], v[90:93]
	v_mfma_f32_16x16x32_bf16 v[82:85], v[142:145], v[204:207], v[82:85]
	v_mfma_f32_16x16x32_bf16 v[74:77], v[134:137], v[212:215], v[74:77]
	v_mfma_f32_16x16x32_bf16 v[66:69], v[142:145], v[212:215], v[66:69]
	v_mfma_f32_16x16x32_bf16 v[122:125], v[146:149], v[180:183], v[122:125]
	v_mfma_f32_16x16x32_bf16 v[126:129], v[172:175], v[180:183], v[126:129]
	v_mfma_f32_16x16x32_bf16 v[110:113], v[146:149], v[192:195], v[110:113]
	v_mfma_f32_16x16x32_bf16 v[102:105], v[172:175], v[192:195], v[102:105]
	v_mfma_f32_16x16x32_bf16 v[94:97], v[146:149], v[200:203], v[94:97]
	v_mfma_f32_16x16x32_bf16 v[86:89], v[172:175], v[200:203], v[86:89]
	v_mfma_f32_16x16x32_bf16 v[78:81], v[146:149], v[208:211], v[78:81]
	v_mfma_f32_16x16x32_bf16 v[70:73], v[172:175], v[208:211], v[70:73]
	v_mfma_f32_16x16x32_bf16 v[122:125], v[150:153], v[188:191], v[122:125]
	v_mfma_f32_16x16x32_bf16 v[126:129], v[176:179], v[188:191], v[126:129]
	v_mfma_f32_16x16x32_bf16 v[110:113], v[150:153], v[196:199], v[110:113]
	v_mfma_f32_16x16x32_bf16 v[102:105], v[176:179], v[196:199], v[102:105]
	v_mfma_f32_16x16x32_bf16 v[94:97], v[150:153], v[204:207], v[94:97]
	v_mfma_f32_16x16x32_bf16 v[86:89], v[176:179], v[204:207], v[86:89]
	v_mfma_f32_16x16x32_bf16 v[78:81], v[150:153], v[212:215], v[78:81]
	v_mfma_f32_16x16x32_bf16 v[70:73], v[176:179], v[212:215], v[70:73]
	s_barrier
	s_add_i32 s33, s40, s24
	s_mov_b32 m0, s33
	s_nop 0
	global_load_lds_dwordx4 v156, s[16:17]
	s_add_i32 m0, s33, 0x2000
	s_add_u32 s66, s16, 0x2b0000
	s_addc_u32 s67, s17, 0
	s_add_i32 s33, s41, s24
	global_load_lds_dwordx4 v160, s[16:17]
	s_mov_b32 m0, s33
	s_add_u32 s100, s20, 0x80
	s_addc_u32 s101, s21, 0
	global_load_lds_dwordx4 v156, s[66:67]
	s_add_i32 m0, s33, 0x2000
	s_nop 0
	global_load_lds_dwordx4 v160, s[66:67]
	s_mov_b32 m0, s25
	s_nop 0
	global_load_lds_dwordx4 v154, s[20:21]
	s_mov_b32 m0, s26
	s_nop 0
	global_load_lds_dwordx4 v158, s[20:21]
	ds_read_b128 v[180:183], v185 offset:16384
	ds_read_b128 v[188:191], v185 offset:17408
	ds_read_b128 v[192:195], v185 offset:18432
	ds_read_b128 v[196:199], v185 offset:19456
	ds_read_b128 v[200:203], v185 offset:20480
	ds_read_b128 v[204:207], v185 offset:21504
	ds_read_b128 v[208:211], v185 offset:22528
	ds_read_b128 v[212:215], v185 offset:23552
	s_waitcnt vmcnt(8)
	s_waitcnt lgkmcnt(0)
	s_barrier
	s_waitcnt lgkmcnt(0)
	v_mfma_f32_16x16x32_bf16 v[58:61], v[130:133], v[180:183], v[58:61]
	v_mfma_f32_16x16x32_bf16 v[54:57], v[138:141], v[180:183], v[54:57]
	v_mfma_f32_16x16x32_bf16 v[42:45], v[130:133], v[192:195], v[42:45]
	v_mfma_f32_16x16x32_bf16 v[34:37], v[138:141], v[192:195], v[34:37]
	v_mfma_f32_16x16x32_bf16 v[26:29], v[130:133], v[200:203], v[26:29]
	v_mfma_f32_16x16x32_bf16 v[18:21], v[138:141], v[200:203], v[18:21]
	v_mfma_f32_16x16x32_bf16 v[6:9], v[130:133], v[208:211], v[6:9]
	v_mfma_f32_16x16x32_bf16 v[2:5], v[138:141], v[208:211], v[2:5]
	v_mfma_f32_16x16x32_bf16 v[58:61], v[134:137], v[188:191], v[58:61]
	v_mfma_f32_16x16x32_bf16 v[54:57], v[142:145], v[188:191], v[54:57]
	v_mfma_f32_16x16x32_bf16 v[42:45], v[134:137], v[196:199], v[42:45]
	v_mfma_f32_16x16x32_bf16 v[34:37], v[142:145], v[196:199], v[34:37]
	v_mfma_f32_16x16x32_bf16 v[26:29], v[134:137], v[204:207], v[26:29]
	v_mfma_f32_16x16x32_bf16 v[18:21], v[142:145], v[204:207], v[18:21]
	v_mfma_f32_16x16x32_bf16 v[6:9], v[134:137], v[212:215], v[6:9]
	v_mfma_f32_16x16x32_bf16 v[2:5], v[142:145], v[212:215], v[2:5]
	v_mfma_f32_16x16x32_bf16 v[62:65], v[146:149], v[180:183], v[62:65]
	v_mfma_f32_16x16x32_bf16 v[50:53], v[172:175], v[180:183], v[50:53]
	v_mfma_f32_16x16x32_bf16 v[46:49], v[146:149], v[192:195], v[46:49]
	v_mfma_f32_16x16x32_bf16 v[38:41], v[172:175], v[192:195], v[38:41]
	v_mfma_f32_16x16x32_bf16 v[30:33], v[146:149], v[200:203], v[30:33]
	v_mfma_f32_16x16x32_bf16 v[22:25], v[172:175], v[200:203], v[22:25]
	v_mfma_f32_16x16x32_bf16 v[10:13], v[146:149], v[208:211], v[10:13]
	v_mfma_f32_16x16x32_bf16 v[14:17], v[172:175], v[208:211], v[14:17]
	v_mfma_f32_16x16x32_bf16 v[62:65], v[150:153], v[188:191], v[62:65]
	v_mfma_f32_16x16x32_bf16 v[50:53], v[176:179], v[188:191], v[50:53]
	v_mfma_f32_16x16x32_bf16 v[46:49], v[150:153], v[196:199], v[46:49]
	v_mfma_f32_16x16x32_bf16 v[38:41], v[176:179], v[196:199], v[38:41]
	v_mfma_f32_16x16x32_bf16 v[30:33], v[150:153], v[204:207], v[30:33]
	v_mfma_f32_16x16x32_bf16 v[22:25], v[176:179], v[204:207], v[22:25]
	v_mfma_f32_16x16x32_bf16 v[10:13], v[150:153], v[212:215], v[10:13]
	v_mfma_f32_16x16x32_bf16 v[14:17], v[176:179], v[212:215], v[14:17]
	s_barrier
; #define PG8_STAGE(bufoff, gbase, voff) do { _Pragma("unroll") for (int _i = 0; _i < 2; ++_i) \
;         __builtin_amdgcn_global_load_lds((const unsigned*)((const char*)(gbase) + (voff)[_i]), (PG8_LAS unsigned*)(lds + (bufoff) + ldsw + _i * 8192), 16, 0, 0); } while (0)
; #define PG8_LDA(dst, b, h) do { _Pragma("unroll") for (int m = 0; m < 4; ++m) _Pragma("unroll") for (int k = 0; k < 2; ++k) dst[m][k] = *(const PG8_LAS bf16x8*)(lds + PG8_SA(b, h) + aoff + m * 2048 + k * 1024); } while (0)
; #define PG8_LDB(dst, b, h) do { _Pragma("unroll") for (int n = 0; n < 2; ++n) _Pragma("unroll") for (int k = 0; k < 2; ++k) dst[n][k] = *(const PG8_LAS bf16x8*)(lds + PG8_SB(b, h) + boff + n * 2048 + k * 1024); } while (0)
; #define PG8_MMA(ai, bj, At, Bt) do { __builtin_amdgcn_s_setprio(1); _Pragma("unroll") for (int m = 0; m < 4; ++m) _Pragma("unroll") for (int n = 0; n < 2; ++n) _Pragma("unroll") for (int k = 0; k < 2; ++k) \
;         acc[ai][bj][m][n] = __builtin_amdgcn_mfma_f32_16x16x32_bf16(Bt[n][k], At[m][k], acc[ai][bj][m][n], 0, 0, 0); __builtin_amdgcn_s_setprio(0); } while (0)
; #define PG8_WAIT_V(n) asm volatile("s_waitcnt vmcnt(" #n ")" ::: "memory")
; #define PG8_WAIT_L(n) asm volatile("s_waitcnt lgkmcnt(" #n ")" ::: "memory")
; #define PG8_BAR __builtin_amdgcn_s_barrier()
; #define PG8_SCHED __builtin_amdgcn_sched_barrier(0)
; template <class Epi, class Sched, bool ALIGN_EPI = false, bool SP2 = false>
; __device__ __forceinline__ void gemm_phase(PG8_LAS unsigned char* lds, const Gemm g, const Sched& S, const Epi& E) {
;     ...
;             PG8_LDB(B0, 1, 0); PG8_LDB(B1, 1, 1); PG8_SCHED; PG8_LDA(At, 1, 0); PG8_STAGE(PG8_SA(0, 1), a2 + hstep, voffA);
;             PG8_WAIT_V(8); PG8_WAIT_L(0); PG8_BAR; PG8_MMA(0, 0, At, B0); PG8_MMA(0, 1, At, B1); PG8_BAR; PG8_SCHED;
;             PG8_LDA(At, 1, 1); PG8_STAGE(PG8_SB(1, 0), b3, voffB); PG8_STAGE(PG8_SB(1, 1), b3 + hstep, voffB); PG8_STAGE(PG8_SA(1, 0), a3, voffA);
;             PG8_WAIT_V(8); PG8_WAIT_L(0); PG8_BAR; PG8_MMA(1, 0, At, B0); PG8_MMA(1, 1, At, B1); PG8_BAR; PG8_SCHED;
	s_add_i32 s33, 0, 0x18000
	s_add_i32 s42, 0, 0x1c000
	s_add_u32 s20, s20, 0x2b0000
	s_addc_u32 s21, s21, 0
	s_mov_b32 m0, s27
	s_nop 0
	global_load_lds_dwordx4 v154, s[20:21]
	s_mov_b32 m0, s28
	s_nop 0
	global_load_lds_dwordx4 v158, s[20:21]
	ds_read_b128 v[130:133], v241 offset:32768
	ds_read_b128 v[134:137], v241 offset:33792
	ds_read_b128 v[138:141], v241 offset:34816
	ds_read_b128 v[142:145], v241 offset:35840
	ds_read_b128 v[146:149], v241 offset:49152
	ds_read_b128 v[150:153], v241 offset:50176
	ds_read_b128 v[172:175], v241 offset:51200
	ds_read_b128 v[176:179], v241 offset:52224
	ds_read_b128 v[180:183], v185 offset:32768
	ds_read_b128 v[188:191], v185 offset:33792
	ds_read_b128 v[192:195], v185 offset:34816
	ds_read_b128 v[196:199], v185 offset:35840
	ds_read_b128 v[200:203], v185 offset:36864
	ds_read_b128 v[204:207], v185 offset:37888
	ds_read_b128 v[208:211], v185 offset:38912
	ds_read_b128 v[212:215], v185 offset:39936
	s_waitcnt vmcnt(8)
	s_waitcnt lgkmcnt(0)
	s_barrier
	s_waitcnt lgkmcnt(0)
	v_mfma_f32_16x16x32_bf16 v[114:117], v[130:133], v[180:183], v[114:117]
	v_mfma_f32_16x16x32_bf16 v[118:121], v[138:141], v[180:183], v[118:121]
	v_mfma_f32_16x16x32_bf16 v[106:109], v[130:133], v[192:195], v[106:109]
	v_mfma_f32_16x16x32_bf16 v[98:101], v[138:141], v[192:195], v[98:101]
	v_mfma_f32_16x16x32_bf16 v[90:93], v[130:133], v[200:203], v[90:93]
	v_mfma_f32_16x16x32_bf16 v[82:85], v[138:141], v[200:203], v[82:85]
	v_mfma_f32_16x16x32_bf16 v[74:77], v[130:133], v[208:211], v[74:77]
	v_mfma_f32_16x16x32_bf16 v[66:69], v[138:141], v[208:211], v[66:69]
	v_mfma_f32_16x16x32_bf16 v[114:117], v[134:137], v[188:191], v[114:117]
	v_mfma_f32_16x16x32_bf16 v[118:121], v[142:145], v[188:191], v[118:121]
	v_mfma_f32_16x16x32_bf16 v[106:109], v[134:137], v[196:199], v[106:109]
	v_mfma_f32_16x16x32_bf16 v[98:101], v[142:145], v[196:199], v[98:101]
	v_mfma_f32_16x16x32_bf16 v[90:93], v[134:137], v[204:207], v[90:93]
	v_mfma_f32_16x16x32_bf16 v[82:85], v[142:145], v[204:207], v[82:85]
	v_mfma_f32_16x16x32_bf16 v[74:77], v[134:137], v[212:215], v[74:77]
	v_mfma_f32_16x16x32_bf16 v[66:69], v[142:145], v[212:215], v[66:69]
	v_mfma_f32_16x16x32_bf16 v[122:125], v[146:149], v[180:183], v[122:125]
	v_mfma_f32_16x16x32_bf16 v[126:129], v[172:175], v[180:183], v[126:129]
	v_mfma_f32_16x16x32_bf16 v[110:113], v[146:149], v[192:195], v[110:113]
	v_mfma_f32_16x16x32_bf16 v[102:105], v[172:175], v[192:195], v[102:105]
	v_mfma_f32_16x16x32_bf16 v[94:97], v[146:149], v[200:203], v[94:97]
	v_mfma_f32_16x16x32_bf16 v[86:89], v[172:175], v[200:203], v[86:89]
	v_mfma_f32_16x16x32_bf16 v[78:81], v[146:149], v[208:211], v[78:81]
	v_mfma_f32_16x16x32_bf16 v[70:73], v[172:175], v[208:211], v[70:73]
	v_mfma_f32_16x16x32_bf16 v[122:125], v[150:153], v[188:191], v[122:125]
	v_mfma_f32_16x16x32_bf16 v[126:129], v[176:179], v[188:191], v[126:129]
	v_mfma_f32_16x16x32_bf16 v[110:113], v[150:153], v[196:199], v[110:113]
	v_mfma_f32_16x16x32_bf16 v[102:105], v[176:179], v[196:199], v[102:105]
	v_mfma_f32_16x16x32_bf16 v[94:97], v[150:153], v[204:207], v[94:97]
	v_mfma_f32_16x16x32_bf16 v[86:89], v[176:179], v[204:207], v[86:89]
	v_mfma_f32_16x16x32_bf16 v[78:81], v[150:153], v[212:215], v[78:81]
	v_mfma_f32_16x16x32_bf16 v[70:73], v[176:179], v[212:215], v[70:73]
	s_barrier
	s_add_i32 s20, s33, s24
	s_add_i32 m0, s20, 0xffffff80
	s_nop 0
	global_load_lds_dwordx4 v156, s[16:17] offset:128
	s_add_i32 m0, s20, 0x1f80
	s_add_i32 s20, s42, s24
	global_load_lds_dwordx4 v160, s[16:17] offset:128
	s_add_u32 s16, s16, 0x2b0080
	s_addc_u32 s17, s17, 0
	s_mov_b32 m0, s20
	s_nop 0
	global_load_lds_dwordx4 v156, s[16:17]
	s_add_i32 m0, s20, 0x2000
	s_nop 0
	global_load_lds_dwordx4 v160, s[16:17]
	s_mov_b32 m0, s34
	s_nop 0
	global_load_lds_dwordx4 v154, s[100:101]
	s_mov_b32 m0, s35
	s_nop 0
	global_load_lds_dwordx4 v158, s[100:101]
	ds_read_b128 v[180:183], v185 offset:49152
	ds_read_b128 v[188:191], v185 offset:50176
	ds_read_b128 v[192:195], v185 offset:51200
	ds_read_b128 v[196:199], v185 offset:52224
	ds_read_b128 v[200:203], v185 offset:53248
	ds_read_b128 v[204:207], v185 offset:54272
	ds_read_b128 v[208:211], v185 offset:55296
	ds_read_b128 v[212:215], v185 offset:56320
	s_waitcnt vmcnt(8)
	s_waitcnt lgkmcnt(0)
	s_barrier
	s_waitcnt lgkmcnt(0)
	v_mfma_f32_16x16x32_bf16 v[58:61], v[130:133], v[180:183], v[58:61]
	v_mfma_f32_16x16x32_bf16 v[54:57], v[138:141], v[180:183], v[54:57]
	v_mfma_f32_16x16x32_bf16 v[42:45], v[130:133], v[192:195], v[42:45]
	v_mfma_f32_16x16x32_bf16 v[34:37], v[138:141], v[192:195], v[34:37]
	v_mfma_f32_16x16x32_bf16 v[26:29], v[130:133], v[200:203], v[26:29]
	v_mfma_f32_16x16x32_bf16 v[18:21], v[138:141], v[200:203], v[18:21]
	v_mfma_f32_16x16x32_bf16 v[6:9], v[130:133], v[208:211], v[6:9]
	v_mfma_f32_16x16x32_bf16 v[2:5], v[138:141], v[208:211], v[2:5]
	v_mfma_f32_16x16x32_bf16 v[58:61], v[134:137], v[188:191], v[58:61]
	v_mfma_f32_16x16x32_bf16 v[54:57], v[142:145], v[188:191], v[54:57]
	v_mfma_f32_16x16x32_bf16 v[42:45], v[134:137], v[196:199], v[42:45]
	v_mfma_f32_16x16x32_bf16 v[34:37], v[142:145], v[196:199], v[34:37]
	v_mfma_f32_16x16x32_bf16 v[26:29], v[134:137], v[204:207], v[26:29]
	v_mfma_f32_16x16x32_bf16 v[18:21], v[142:145], v[204:207], v[18:21]
	v_mfma_f32_16x16x32_bf16 v[6:9], v[134:137], v[212:215], v[6:9]
	v_mfma_f32_16x16x32_bf16 v[2:5], v[142:145], v[212:215], v[2:5]
	v_mfma_f32_16x16x32_bf16 v[62:65], v[146:149], v[180:183], v[62:65]
	v_mfma_f32_16x16x32_bf16 v[50:53], v[172:175], v[180:183], v[50:53]
	v_mfma_f32_16x16x32_bf16 v[46:49], v[146:149], v[192:195], v[46:49]
	v_mfma_f32_16x16x32_bf16 v[38:41], v[172:175], v[192:195], v[38:41]
	v_mfma_f32_16x16x32_bf16 v[30:33], v[146:149], v[200:203], v[30:33]
	v_mfma_f32_16x16x32_bf16 v[22:25], v[172:175], v[200:203], v[22:25]
	v_mfma_f32_16x16x32_bf16 v[10:13], v[146:149], v[208:211], v[10:13]
	v_mfma_f32_16x16x32_bf16 v[14:17], v[172:175], v[208:211], v[14:17]
	v_mfma_f32_16x16x32_bf16 v[62:65], v[150:153], v[188:191], v[62:65]
	v_mfma_f32_16x16x32_bf16 v[50:53], v[176:179], v[188:191], v[50:53]
	v_mfma_f32_16x16x32_bf16 v[46:49], v[150:153], v[196:199], v[46:49]
	v_mfma_f32_16x16x32_bf16 v[38:41], v[176:179], v[196:199], v[38:41]
	v_mfma_f32_16x16x32_bf16 v[30:33], v[150:153], v[204:207], v[30:33]
	v_mfma_f32_16x16x32_bf16 v[22:25], v[176:179], v[204:207], v[22:25]
	v_mfma_f32_16x16x32_bf16 v[10:13], v[150:153], v[212:215], v[10:13]
	v_mfma_f32_16x16x32_bf16 v[14:17], v[176:179], v[212:215], v[14:17]
	s_barrier
	s_add_i32 s64, s64, 2
	s_add_u32 s18, s18, 0x100
	s_addc_u32 s19, s19, 0
	s_add_u32 s62, s62, 0x100
	s_addc_u32 s63, s63, 0
	s_cmpk_gt_u32 s64, 0xa9
	s_cbranch_scc0 .LBB0_1245


; #define PG8_BAR __builtin_amdgcn_s_barrier()
; template <class Epi, class Sched, bool ALIGN_EPI = false, bool SP2 = false>
; __device__ __forceinline__ void gemm_phase(PG8_LAS unsigned char* lds, const Gemm g, const Sched& S, const Epi& E) {
;     ...
;         }
;         if constexpr (ALIGN_EPI) { if (wr == 0) PG8_BAR; }
	s_and_b64 vcc, exec, s[12:13]
	s_cbranch_vccz .LBB0_1248
	s_barrier

; #define PG8_STAGE(bufoff, gbase, voff) do { _Pragma("unroll") for (int _i = 0; _i < 2; ++_i) \
;         __builtin_amdgcn_global_load_lds((const unsigned*)((const char*)(gbase) + (voff)[_i]), (PG8_LAS unsigned*)(lds + (bufoff) + ldsw + _i * 8192), 16, 0, 0); } while (0)
; #define PG8_LDA(dst, b, h) do { _Pragma("unroll") for (int m = 0; m < 4; ++m) _Pragma("unroll") for (int k = 0; k < 2; ++k) dst[m][k] = *(const PG8_LAS bf16x8*)(lds + PG8_SA(b, h) + aoff + m * 2048 + k * 1024); } while (0)
; #define PG8_LDB(dst, b, h) do { _Pragma("unroll") for (int n = 0; n < 2; ++n) _Pragma("unroll") for (int k = 0; k < 2; ++k) dst[n][k] = *(const PG8_LAS bf16x8*)(lds + PG8_SB(b, h) + boff + n * 2048 + k * 1024); } while (0)
; #define PG8_MMA(ai, bj, At, Bt) do { __builtin_amdgcn_s_setprio(1); _Pragma("unroll") for (int m = 0; m < 4; ++m) _Pragma("unroll") for (int n = 0; n < 2; ++n) _Pragma("unroll") for (int k = 0; k < 2; ++k) \
;         acc[ai][bj][m][n] = __builtin_amdgcn_mfma_f32_16x16x32_bf16(Bt[n][k], At[m][k], acc[ai][bj][m][n], 0, 0, 0); __builtin_amdgcn_s_setprio(0); } while (0)
; #define PG8_WAIT_V(n) asm volatile("s_waitcnt vmcnt(" #n ")" ::: "memory")
; #define PG8_WAIT_L(n) asm volatile("s_waitcnt lgkmcnt(" #n ")" ::: "memory")
; #define PG8_BAR __builtin_amdgcn_s_barrier()
; #define PG8_SCHED __builtin_amdgcn_sched_barrier(0)
; template <class Epi, class Sched, bool ALIGN_EPI = false, bool SP2 = false>
; __device__ __forceinline__ void gemm_phase(PG8_LAS unsigned char* lds, const Gemm g, const Sched& S, const Epi& E) {
;     ...
;             PG8_LDB(B0, 0, 0); PG8_LDB(B1, 0, 1); PG8_SCHED; PG8_LDA(At, 0, 0); PG8_STAGE(PG8_SA(1, 1), a1 + hstep, voffA);
;             PG8_WAIT_V(8); PG8_WAIT_L(0); PG8_BAR; PG8_MMA(0, 0, At, B0); PG8_MMA(0, 1, At, B1); PG8_BAR; PG8_SCHED;
;             PG8_LDA(At, 0, 1); PG8_STAGE(PG8_SB(0, 0), b2, voffB); PG8_STAGE(PG8_SB(0, 1), b2 + hstep, voffB); PG8_STAGE(PG8_SA(0, 0), a2, voffA);
;             PG8_WAIT_V(8); PG8_WAIT_L(0); PG8_BAR; PG8_MMA(1, 0, At, B0); PG8_MMA(1, 1, At, B1); PG8_BAR; PG8_SCHED;
.LBB0_1332:
	s_add_u32 s20, s22, 0xfff00080
	s_addc_u32 s21, s23, -1
	s_cmp_eq_u32 s67, 60
	s_cselect_b32 s25, s13, s21
	s_cselect_b32 s24, s63, s20
	s_cselect_b32 s21, s11, s66
	s_cselect_b32 s20, s64, s65
	s_add_i32 m0, s19, 0xc000
	s_nop 0
	global_load_lds_dwordx4 v138, s[22:23]
	s_add_i32 m0, s19, 0xe000
	s_nop 0
	global_load_lds_dwordx4 v140, s[22:23]
	ds_read_b128 v[148:151], v241 offset:0
	ds_read_b128 v[156:159], v241 offset:1024
	ds_read_b128 v[166:169], v241 offset:2048
	ds_read_b128 v[170:173], v241 offset:3072
	ds_read_b128 v[174:177], v241 offset:16384
	ds_read_b128 v[178:181], v241 offset:17408
	ds_read_b128 v[182:185], v241 offset:18432
	ds_read_b128 v[186:189], v241 offset:19456
	ds_read_b128 v[190:193], v155
	ds_read_b128 v[194:197], v155 offset:1024
	ds_read_b128 v[198:201], v155 offset:2048
	ds_read_b128 v[202:205], v155 offset:3072
	ds_read_b128 v[206:209], v155 offset:4096
	ds_read_b128 v[210:213], v155 offset:5120
	ds_read_b128 v[214:217], v155 offset:6144
	ds_read_b128 v[218:221], v155 offset:7168
	s_waitcnt vmcnt(8)
	s_waitcnt lgkmcnt(0)
	s_barrier
	s_waitcnt lgkmcnt(0)
	v_mfma_f32_16x16x32_bf16 v[118:121], v[148:151], v[190:193], v[118:121]
	v_mfma_f32_16x16x32_bf16 v[114:117], v[166:169], v[190:193], v[114:117]
	v_mfma_f32_16x16x32_bf16 v[102:105], v[148:151], v[198:201], v[102:105]
	v_mfma_f32_16x16x32_bf16 v[98:101], v[166:169], v[198:201], v[98:101]
	v_mfma_f32_16x16x32_bf16 v[86:89], v[148:151], v[206:209], v[86:89]
	v_mfma_f32_16x16x32_bf16 v[82:85], v[166:169], v[206:209], v[82:85]
	v_mfma_f32_16x16x32_bf16 v[70:73], v[148:151], v[214:217], v[70:73]
	v_mfma_f32_16x16x32_bf16 v[66:69], v[166:169], v[214:217], v[66:69]
	v_mfma_f32_16x16x32_bf16 v[118:121], v[156:159], v[194:197], v[118:121]
	v_mfma_f32_16x16x32_bf16 v[114:117], v[170:173], v[194:197], v[114:117]
	v_mfma_f32_16x16x32_bf16 v[102:105], v[156:159], v[202:205], v[102:105]
	v_mfma_f32_16x16x32_bf16 v[98:101], v[170:173], v[202:205], v[98:101]
	v_mfma_f32_16x16x32_bf16 v[86:89], v[156:159], v[210:213], v[86:89]
	v_mfma_f32_16x16x32_bf16 v[82:85], v[170:173], v[210:213], v[82:85]
	v_mfma_f32_16x16x32_bf16 v[70:73], v[156:159], v[218:221], v[70:73]
	v_mfma_f32_16x16x32_bf16 v[66:69], v[170:173], v[218:221], v[66:69]
	v_mfma_f32_16x16x32_bf16 v[126:129], v[174:177], v[190:193], v[126:129]
	v_mfma_f32_16x16x32_bf16 v[122:125], v[182:185], v[190:193], v[122:125]
	v_mfma_f32_16x16x32_bf16 v[110:113], v[174:177], v[198:201], v[110:113]
	v_mfma_f32_16x16x32_bf16 v[106:109], v[182:185], v[198:201], v[106:109]
	v_mfma_f32_16x16x32_bf16 v[94:97], v[174:177], v[206:209], v[94:97]
	v_mfma_f32_16x16x32_bf16 v[90:93], v[182:185], v[206:209], v[90:93]
	v_mfma_f32_16x16x32_bf16 v[78:81], v[174:177], v[214:217], v[78:81]
	v_mfma_f32_16x16x32_bf16 v[74:77], v[182:185], v[214:217], v[74:77]
	v_mfma_f32_16x16x32_bf16 v[126:129], v[178:181], v[194:197], v[126:129]
	v_mfma_f32_16x16x32_bf16 v[122:125], v[186:189], v[194:197], v[122:125]
	v_mfma_f32_16x16x32_bf16 v[110:113], v[178:181], v[202:205], v[110:113]
	v_mfma_f32_16x16x32_bf16 v[106:109], v[186:189], v[202:205], v[106:109]
	v_mfma_f32_16x16x32_bf16 v[94:97], v[178:181], v[210:213], v[94:97]
	v_mfma_f32_16x16x32_bf16 v[90:93], v[186:189], v[210:213], v[90:93]
	v_mfma_f32_16x16x32_bf16 v[78:81], v[178:181], v[218:221], v[78:81]
	v_mfma_f32_16x16x32_bf16 v[74:77], v[186:189], v[218:221], v[74:77]
	s_barrier
	s_add_i32 s33, s47, s28
	s_mov_b32 m0, s33
	s_nop 0
	global_load_lds_dwordx4 v132, s[20:21]
	s_add_i32 m0, s33, 0x2000
	s_add_u32 s68, s20, 0x100000
	s_addc_u32 s69, s21, 0
	s_add_i32 s33, s52, s28
	global_load_lds_dwordx4 v136, s[20:21]
	s_mov_b32 m0, s33
	s_add_u32 s100, s24, 0x80
	s_addc_u32 s101, s25, 0
	global_load_lds_dwordx4 v132, s[68:69]
	s_add_i32 m0, s33, 0x2000
	s_nop 0
	global_load_lds_dwordx4 v136, s[68:69]
	s_mov_b32 m0, s19
	s_nop 0
	global_load_lds_dwordx4 v130, s[24:25]
	s_mov_b32 m0, s35
	s_nop 0
	global_load_lds_dwordx4 v134, s[24:25]
	ds_read_b128 v[190:193], v155 offset:16384
	ds_read_b128 v[194:197], v155 offset:17408
	ds_read_b128 v[198:201], v155 offset:18432
	ds_read_b128 v[202:205], v155 offset:19456
	ds_read_b128 v[206:209], v155 offset:20480
	ds_read_b128 v[210:213], v155 offset:21504
	ds_read_b128 v[214:217], v155 offset:22528
	ds_read_b128 v[218:221], v155 offset:23552
	s_waitcnt vmcnt(8)
	s_waitcnt lgkmcnt(0)
	s_barrier
	s_waitcnt lgkmcnt(0)
	v_mfma_f32_16x16x32_bf16 v[54:57], v[148:151], v[190:193], v[54:57]
	v_mfma_f32_16x16x32_bf16 v[50:53], v[166:169], v[190:193], v[50:53]
	v_mfma_f32_16x16x32_bf16 v[38:41], v[148:151], v[198:201], v[38:41]
	v_mfma_f32_16x16x32_bf16 v[34:37], v[166:169], v[198:201], v[34:37]
	v_mfma_f32_16x16x32_bf16 v[22:25], v[148:151], v[206:209], v[22:25]
	v_mfma_f32_16x16x32_bf16 v[18:21], v[166:169], v[206:209], v[18:21]
	v_mfma_f32_16x16x32_bf16 v[6:9], v[148:151], v[214:217], v[6:9]
	v_mfma_f32_16x16x32_bf16 v[2:5], v[166:169], v[214:217], v[2:5]
	v_mfma_f32_16x16x32_bf16 v[54:57], v[156:159], v[194:197], v[54:57]
	v_mfma_f32_16x16x32_bf16 v[50:53], v[170:173], v[194:197], v[50:53]
	v_mfma_f32_16x16x32_bf16 v[38:41], v[156:159], v[202:205], v[38:41]
	v_mfma_f32_16x16x32_bf16 v[34:37], v[170:173], v[202:205], v[34:37]
	v_mfma_f32_16x16x32_bf16 v[22:25], v[156:159], v[210:213], v[22:25]
	v_mfma_f32_16x16x32_bf16 v[18:21], v[170:173], v[210:213], v[18:21]
	v_mfma_f32_16x16x32_bf16 v[6:9], v[156:159], v[218:221], v[6:9]
	v_mfma_f32_16x16x32_bf16 v[2:5], v[170:173], v[218:221], v[2:5]
	v_mfma_f32_16x16x32_bf16 v[62:65], v[174:177], v[190:193], v[62:65]
	v_mfma_f32_16x16x32_bf16 v[58:61], v[182:185], v[190:193], v[58:61]
	v_mfma_f32_16x16x32_bf16 v[46:49], v[174:177], v[198:201], v[46:49]
	v_mfma_f32_16x16x32_bf16 v[42:45], v[182:185], v[198:201], v[42:45]
	v_mfma_f32_16x16x32_bf16 v[30:33], v[174:177], v[206:209], v[30:33]
	v_mfma_f32_16x16x32_bf16 v[26:29], v[182:185], v[206:209], v[26:29]
	v_mfma_f32_16x16x32_bf16 v[10:13], v[174:177], v[214:217], v[10:13]
	v_mfma_f32_16x16x32_bf16 v[14:17], v[182:185], v[214:217], v[14:17]
	v_mfma_f32_16x16x32_bf16 v[62:65], v[178:181], v[194:197], v[62:65]
	v_mfma_f32_16x16x32_bf16 v[58:61], v[186:189], v[194:197], v[58:61]
	v_mfma_f32_16x16x32_bf16 v[46:49], v[178:181], v[202:205], v[46:49]
	v_mfma_f32_16x16x32_bf16 v[42:45], v[186:189], v[202:205], v[42:45]
	v_mfma_f32_16x16x32_bf16 v[30:33], v[178:181], v[210:213], v[30:33]
	v_mfma_f32_16x16x32_bf16 v[26:29], v[186:189], v[210:213], v[26:29]
	v_mfma_f32_16x16x32_bf16 v[10:13], v[178:181], v[218:221], v[10:13]
	v_mfma_f32_16x16x32_bf16 v[14:17], v[186:189], v[218:221], v[14:17]
	s_barrier
; #define PG8_STAGE(bufoff, gbase, voff) do { _Pragma("unroll") for (int _i = 0; _i < 2; ++_i) \
;         __builtin_amdgcn_global_load_lds((const unsigned*)((const char*)(gbase) + (voff)[_i]), (PG8_LAS unsigned*)(lds + (bufoff) + ldsw + _i * 8192), 16, 0, 0); } while (0)
; #define PG8_LDA(dst, b, h) do { _Pragma("unroll") for (int m = 0; m < 4; ++m) _Pragma("unroll") for (int k = 0; k < 2; ++k) dst[m][k] = *(const PG8_LAS bf16x8*)(lds + PG8_SA(b, h) + aoff + m * 2048 + k * 1024); } while (0)
; #define PG8_LDB(dst, b, h) do { _Pragma("unroll") for (int n = 0; n < 2; ++n) _Pragma("unroll") for (int k = 0; k < 2; ++k) dst[n][k] = *(const PG8_LAS bf16x8*)(lds + PG8_SB(b, h) + boff + n * 2048 + k * 1024); } while (0)
; #define PG8_MMA(ai, bj, At, Bt) do { __builtin_amdgcn_s_setprio(1); _Pragma("unroll") for (int m = 0; m < 4; ++m) _Pragma("unroll") for (int n = 0; n < 2; ++n) _Pragma("unroll") for (int k = 0; k < 2; ++k) \
;         acc[ai][bj][m][n] = __builtin_amdgcn_mfma_f32_16x16x32_bf16(Bt[n][k], At[m][k], acc[ai][bj][m][n], 0, 0, 0); __builtin_amdgcn_s_setprio(0); } while (0)
; #define PG8_WAIT_V(n) asm volatile("s_waitcnt vmcnt(" #n ")" ::: "memory")
; #define PG8_WAIT_L(n) asm volatile("s_waitcnt lgkmcnt(" #n ")" ::: "memory")
; #define PG8_BAR __builtin_amdgcn_s_barrier()
; #define PG8_SCHED __builtin_amdgcn_sched_barrier(0)
; template <class Epi, class Sched, bool ALIGN_EPI = false, bool SP2 = false>
; __device__ __forceinline__ void gemm_phase(PG8_LAS unsigned char* lds, const Gemm g, const Sched& S, const Epi& E) {
;     ...
;             PG8_LDB(B0, 1, 0); PG8_LDB(B1, 1, 1); PG8_SCHED; PG8_LDA(At, 1, 0); PG8_STAGE(PG8_SA(0, 1), a2 + hstep, voffA);
;             PG8_WAIT_V(8); PG8_WAIT_L(0); PG8_BAR; PG8_MMA(0, 0, At, B0); PG8_MMA(0, 1, At, B1); PG8_BAR; PG8_SCHED;
;             PG8_LDA(At, 1, 1); PG8_STAGE(PG8_SB(1, 0), b3, voffB); PG8_STAGE(PG8_SB(1, 1), b3 + hstep, voffB); PG8_STAGE(PG8_SA(1, 0), a3, voffA);
;             PG8_WAIT_V(8); PG8_WAIT_L(0); PG8_BAR; PG8_MMA(1, 0, At, B0); PG8_MMA(1, 1, At, B1); PG8_BAR; PG8_SCHED;
	s_add_i32 s33, 0, 0x18000
	s_add_i32 s42, 0, 0x1c000
	s_add_u32 s24, s24, 0x100000
	s_addc_u32 s25, s25, 0
	s_mov_b32 m0, s36
	s_nop 0
	global_load_lds_dwordx4 v130, s[24:25]
	s_mov_b32 m0, s37
	s_nop 0
	global_load_lds_dwordx4 v134, s[24:25]
	ds_read_b128 v[148:151], v241 offset:32768
	ds_read_b128 v[156:159], v241 offset:33792
	ds_read_b128 v[166:169], v241 offset:34816
	ds_read_b128 v[170:173], v241 offset:35840
	ds_read_b128 v[174:177], v241 offset:49152
	ds_read_b128 v[178:181], v241 offset:50176
	ds_read_b128 v[182:185], v241 offset:51200
	ds_read_b128 v[186:189], v241 offset:52224
	ds_read_b128 v[190:193], v155 offset:32768
	ds_read_b128 v[194:197], v155 offset:33792
	ds_read_b128 v[198:201], v155 offset:34816
	ds_read_b128 v[202:205], v155 offset:35840
	ds_read_b128 v[206:209], v155 offset:36864
	ds_read_b128 v[210:213], v155 offset:37888
	ds_read_b128 v[214:217], v155 offset:38912
	ds_read_b128 v[218:221], v155 offset:39936
	s_waitcnt vmcnt(8)
	s_waitcnt lgkmcnt(0)
	s_barrier
	s_waitcnt lgkmcnt(0)
	v_mfma_f32_16x16x32_bf16 v[118:121], v[148:151], v[190:193], v[118:121]
	v_mfma_f32_16x16x32_bf16 v[114:117], v[166:169], v[190:193], v[114:117]
	v_mfma_f32_16x16x32_bf16 v[102:105], v[148:151], v[198:201], v[102:105]
	v_mfma_f32_16x16x32_bf16 v[98:101], v[166:169], v[198:201], v[98:101]
	v_mfma_f32_16x16x32_bf16 v[86:89], v[148:151], v[206:209], v[86:89]
	v_mfma_f32_16x16x32_bf16 v[82:85], v[166:169], v[206:209], v[82:85]
	v_mfma_f32_16x16x32_bf16 v[70:73], v[148:151], v[214:217], v[70:73]
	v_mfma_f32_16x16x32_bf16 v[66:69], v[166:169], v[214:217], v[66:69]
	v_mfma_f32_16x16x32_bf16 v[118:121], v[156:159], v[194:197], v[118:121]
	v_mfma_f32_16x16x32_bf16 v[114:117], v[170:173], v[194:197], v[114:117]
	v_mfma_f32_16x16x32_bf16 v[102:105], v[156:159], v[202:205], v[102:105]
	v_mfma_f32_16x16x32_bf16 v[98:101], v[170:173], v[202:205], v[98:101]
	v_mfma_f32_16x16x32_bf16 v[86:89], v[156:159], v[210:213], v[86:89]
	v_mfma_f32_16x16x32_bf16 v[82:85], v[170:173], v[210:213], v[82:85]
	v_mfma_f32_16x16x32_bf16 v[70:73], v[156:159], v[218:221], v[70:73]
	v_mfma_f32_16x16x32_bf16 v[66:69], v[170:173], v[218:221], v[66:69]
	v_mfma_f32_16x16x32_bf16 v[126:129], v[174:177], v[190:193], v[126:129]
	v_mfma_f32_16x16x32_bf16 v[122:125], v[182:185], v[190:193], v[122:125]
	v_mfma_f32_16x16x32_bf16 v[110:113], v[174:177], v[198:201], v[110:113]
	v_mfma_f32_16x16x32_bf16 v[106:109], v[182:185], v[198:201], v[106:109]
	v_mfma_f32_16x16x32_bf16 v[94:97], v[174:177], v[206:209], v[94:97]
	v_mfma_f32_16x16x32_bf16 v[90:93], v[182:185], v[206:209], v[90:93]
	v_mfma_f32_16x16x32_bf16 v[78:81], v[174:177], v[214:217], v[78:81]
	v_mfma_f32_16x16x32_bf16 v[74:77], v[182:185], v[214:217], v[74:77]
	v_mfma_f32_16x16x32_bf16 v[126:129], v[178:181], v[194:197], v[126:129]
	v_mfma_f32_16x16x32_bf16 v[122:125], v[186:189], v[194:197], v[122:125]
	v_mfma_f32_16x16x32_bf16 v[110:113], v[178:181], v[202:205], v[110:113]
	v_mfma_f32_16x16x32_bf16 v[106:109], v[186:189], v[202:205], v[106:109]
	v_mfma_f32_16x16x32_bf16 v[94:97], v[178:181], v[210:213], v[94:97]
	v_mfma_f32_16x16x32_bf16 v[90:93], v[186:189], v[210:213], v[90:93]
	v_mfma_f32_16x16x32_bf16 v[78:81], v[178:181], v[218:221], v[78:81]
	v_mfma_f32_16x16x32_bf16 v[74:77], v[186:189], v[218:221], v[74:77]
	s_barrier
	s_add_i32 s24, s33, s28
	s_add_i32 m0, s24, 0xffffff80
	s_nop 0
	global_load_lds_dwordx4 v132, s[20:21] offset:128
	s_add_i32 m0, s24, 0x1f80
	s_add_i32 s24, s42, s28
	global_load_lds_dwordx4 v136, s[20:21] offset:128
	s_add_u32 s20, s20, 0x100080
	s_addc_u32 s21, s21, 0
	s_mov_b32 m0, s24
	s_nop 0
	global_load_lds_dwordx4 v132, s[20:21]
	s_add_i32 m0, s24, 0x2000
	s_nop 0
	global_load_lds_dwordx4 v136, s[20:21]
	s_mov_b32 m0, s43
	s_nop 0
	global_load_lds_dwordx4 v130, s[100:101]
	s_mov_b32 m0, s46
	s_nop 0
	global_load_lds_dwordx4 v134, s[100:101]
	ds_read_b128 v[190:193], v155 offset:49152
	ds_read_b128 v[194:197], v155 offset:50176
	ds_read_b128 v[198:201], v155 offset:51200
	ds_read_b128 v[202:205], v155 offset:52224
	ds_read_b128 v[206:209], v155 offset:53248
	ds_read_b128 v[210:213], v155 offset:54272
	ds_read_b128 v[214:217], v155 offset:55296
	ds_read_b128 v[218:221], v155 offset:56320
	s_waitcnt vmcnt(8)
	s_waitcnt lgkmcnt(0)
	s_barrier
	s_waitcnt lgkmcnt(0)
	v_mfma_f32_16x16x32_bf16 v[54:57], v[148:151], v[190:193], v[54:57]
	v_mfma_f32_16x16x32_bf16 v[50:53], v[166:169], v[190:193], v[50:53]
	v_mfma_f32_16x16x32_bf16 v[38:41], v[148:151], v[198:201], v[38:41]
	v_mfma_f32_16x16x32_bf16 v[34:37], v[166:169], v[198:201], v[34:37]
	v_mfma_f32_16x16x32_bf16 v[22:25], v[148:151], v[206:209], v[22:25]
	v_mfma_f32_16x16x32_bf16 v[18:21], v[166:169], v[206:209], v[18:21]
	v_mfma_f32_16x16x32_bf16 v[6:9], v[148:151], v[214:217], v[6:9]
	v_mfma_f32_16x16x32_bf16 v[2:5], v[166:169], v[214:217], v[2:5]
	v_mfma_f32_16x16x32_bf16 v[54:57], v[156:159], v[194:197], v[54:57]
	v_mfma_f32_16x16x32_bf16 v[50:53], v[170:173], v[194:197], v[50:53]
	v_mfma_f32_16x16x32_bf16 v[38:41], v[156:159], v[202:205], v[38:41]
	v_mfma_f32_16x16x32_bf16 v[34:37], v[170:173], v[202:205], v[34:37]
	v_mfma_f32_16x16x32_bf16 v[22:25], v[156:159], v[210:213], v[22:25]
	v_mfma_f32_16x16x32_bf16 v[18:21], v[170:173], v[210:213], v[18:21]
	v_mfma_f32_16x16x32_bf16 v[6:9], v[156:159], v[218:221], v[6:9]
	v_mfma_f32_16x16x32_bf16 v[2:5], v[170:173], v[218:221], v[2:5]
	v_mfma_f32_16x16x32_bf16 v[62:65], v[174:177], v[190:193], v[62:65]
	v_mfma_f32_16x16x32_bf16 v[58:61], v[182:185], v[190:193], v[58:61]
	v_mfma_f32_16x16x32_bf16 v[46:49], v[174:177], v[198:201], v[46:49]
	v_mfma_f32_16x16x32_bf16 v[42:45], v[182:185], v[198:201], v[42:45]
	v_mfma_f32_16x16x32_bf16 v[30:33], v[174:177], v[206:209], v[30:33]
	v_mfma_f32_16x16x32_bf16 v[26:29], v[182:185], v[206:209], v[26:29]
	v_mfma_f32_16x16x32_bf16 v[10:13], v[174:177], v[214:217], v[10:13]
	v_mfma_f32_16x16x32_bf16 v[14:17], v[182:185], v[214:217], v[14:17]
	v_mfma_f32_16x16x32_bf16 v[62:65], v[178:181], v[194:197], v[62:65]
	v_mfma_f32_16x16x32_bf16 v[58:61], v[186:189], v[194:197], v[58:61]
	v_mfma_f32_16x16x32_bf16 v[46:49], v[178:181], v[202:205], v[46:49]
	v_mfma_f32_16x16x32_bf16 v[42:45], v[186:189], v[202:205], v[42:45]
	v_mfma_f32_16x16x32_bf16 v[30:33], v[178:181], v[210:213], v[30:33]
	v_mfma_f32_16x16x32_bf16 v[26:29], v[186:189], v[210:213], v[26:29]
	v_mfma_f32_16x16x32_bf16 v[10:13], v[178:181], v[218:221], v[10:13]
	v_mfma_f32_16x16x32_bf16 v[14:17], v[186:189], v[218:221], v[14:17]
	s_barrier
	s_add_i32 s67, s67, 2
	s_add_u32 s22, s22, 0x100
	s_addc_u32 s23, s23, 0
	s_add_u32 s65, s65, 0x100
	s_addc_u32 s66, s66, 0
	s_cmp_gt_u32 s67, 61
	s_cbranch_scc0 .LBB0_1332


; #define PG8_BAR __builtin_amdgcn_s_barrier()
; template <class Epi, class Sched, bool ALIGN_EPI = false, bool SP2 = false>
; __device__ __forceinline__ void gemm_phase(PG8_LAS unsigned char* lds, const Gemm g, const Sched& S, const Epi& E) {
;     ...
;         }
;         if constexpr (ALIGN_EPI) { if (wr == 0) PG8_BAR; }
	s_and_b64 vcc, exec, s[8:9]
	s_cbranch_vccz .LBB0_1335
	s_barrier

; #define PG8_STAGE(bufoff, gbase, voff) do { _Pragma("unroll") for (int _i = 0; _i < 2; ++_i) \
;         __builtin_amdgcn_global_load_lds((const unsigned*)((const char*)(gbase) + (voff)[_i]), (PG8_LAS unsigned*)(lds + (bufoff) + ldsw + _i * 8192), 16, 0, 0); } while (0)
; #define PG8_LDA(dst, b, h) do { _Pragma("unroll") for (int m = 0; m < 4; ++m) _Pragma("unroll") for (int k = 0; k < 2; ++k) dst[m][k] = *(const PG8_LAS bf16x8*)(lds + PG8_SA(b, h) + aoff + m * 2048 + k * 1024); } while (0)
; #define PG8_LDB(dst, b, h) do { _Pragma("unroll") for (int n = 0; n < 2; ++n) _Pragma("unroll") for (int k = 0; k < 2; ++k) dst[n][k] = *(const PG8_LAS bf16x8*)(lds + PG8_SB(b, h) + boff + n * 2048 + k * 1024); } while (0)
; #define PG8_MMA(ai, bj, At, Bt) do { __builtin_amdgcn_s_setprio(1); _Pragma("unroll") for (int m = 0; m < 4; ++m) _Pragma("unroll") for (int n = 0; n < 2; ++n) _Pragma("unroll") for (int k = 0; k < 2; ++k) \
;         acc[ai][bj][m][n] = __builtin_amdgcn_mfma_f32_16x16x32_bf16(Bt[n][k], At[m][k], acc[ai][bj][m][n], 0, 0, 0); __builtin_amdgcn_s_setprio(0); } while (0)
; #define PG8_WAIT_V(n) asm volatile("s_waitcnt vmcnt(" #n ")" ::: "memory")
; #define PG8_WAIT_L(n) asm volatile("s_waitcnt lgkmcnt(" #n ")" ::: "memory")
; #define PG8_BAR __builtin_amdgcn_s_barrier()
; #define PG8_SCHED __builtin_amdgcn_sched_barrier(0)
; template <class Epi, class Sched, bool ALIGN_EPI = false, bool SP2 = false>
; __device__ __forceinline__ void gemm_phase(PG8_LAS unsigned char* lds, const Gemm g, const Sched& S, const Epi& E) {
;     ...
;             PG8_LDB(B0, 0, 0); PG8_LDB(B1, 0, 1); PG8_SCHED; PG8_LDA(At, 0, 0); PG8_STAGE(PG8_SA(1, 1), a1 + hstep, voffA);
;             PG8_WAIT_V(8); PG8_WAIT_L(0); PG8_BAR; PG8_MMA(0, 0, At, B0); PG8_MMA(0, 1, At, B1); PG8_BAR; PG8_SCHED;
;             PG8_LDA(At, 0, 1); PG8_STAGE(PG8_SB(0, 0), b2, voffB); PG8_STAGE(PG8_SB(0, 1), b2 + hstep, voffB); PG8_STAGE(PG8_SA(0, 0), a2, voffA);
;             PG8_WAIT_V(8); PG8_WAIT_L(0); PG8_BAR; PG8_MMA(1, 0, At, B0); PG8_MMA(1, 1, At, B1); PG8_BAR; PG8_SCHED;
.LBB0_1595:
	s_add_u32 s24, s26, 0xfff00080
	s_addc_u32 s25, s27, -1
	s_cmp_eq_u32 s62, 60
	s_cselect_b32 s29, s15, s25
	s_cselect_b32 s28, s21, s24
	s_cselect_b32 s25, s13, s53
	s_cselect_b32 s24, s51, s52
	s_add_i32 m0, s23, 0xc000
	s_nop 0
	global_load_lds_dwordx4 v162, s[26:27]
	s_add_i32 m0, s23, 0xe000
	s_nop 0
	global_load_lds_dwordx4 v166, s[26:27]
	ds_read_b128 v[130:133], v241 offset:0
	ds_read_b128 v[134:137], v241 offset:1024
	ds_read_b128 v[138:141], v241 offset:2048
	ds_read_b128 v[142:145], v241 offset:3072
	ds_read_b128 v[146:149], v241 offset:16384
	ds_read_b128 v[150:153], v241 offset:17408
	ds_read_b128 v[172:175], v241 offset:18432
	ds_read_b128 v[176:179], v241 offset:19456
	ds_read_b128 v[180:183], v185
	ds_read_b128 v[188:191], v185 offset:1024
	ds_read_b128 v[192:195], v185 offset:2048
	ds_read_b128 v[196:199], v185 offset:3072
	ds_read_b128 v[200:203], v185 offset:4096
	ds_read_b128 v[204:207], v185 offset:5120
	ds_read_b128 v[208:211], v185 offset:6144
	ds_read_b128 v[212:215], v185 offset:7168
	s_waitcnt vmcnt(8)
	s_waitcnt lgkmcnt(0)
	s_barrier
	s_waitcnt lgkmcnt(0)
	v_mfma_f32_16x16x32_bf16 v[114:117], v[130:133], v[180:183], v[114:117]
	v_mfma_f32_16x16x32_bf16 v[118:121], v[138:141], v[180:183], v[118:121]
	v_mfma_f32_16x16x32_bf16 v[106:109], v[130:133], v[192:195], v[106:109]
	v_mfma_f32_16x16x32_bf16 v[98:101], v[138:141], v[192:195], v[98:101]
	v_mfma_f32_16x16x32_bf16 v[90:93], v[130:133], v[200:203], v[90:93]
	v_mfma_f32_16x16x32_bf16 v[82:85], v[138:141], v[200:203], v[82:85]
	v_mfma_f32_16x16x32_bf16 v[74:77], v[130:133], v[208:211], v[74:77]
	v_mfma_f32_16x16x32_bf16 v[66:69], v[138:141], v[208:211], v[66:69]
	v_mfma_f32_16x16x32_bf16 v[114:117], v[134:137], v[188:191], v[114:117]
	v_mfma_f32_16x16x32_bf16 v[118:121], v[142:145], v[188:191], v[118:121]
	v_mfma_f32_16x16x32_bf16 v[106:109], v[134:137], v[196:199], v[106:109]
	v_mfma_f32_16x16x32_bf16 v[98:101], v[142:145], v[196:199], v[98:101]
	v_mfma_f32_16x16x32_bf16 v[90:93], v[134:137], v[204:207], v[90:93]
	v_mfma_f32_16x16x32_bf16 v[82:85], v[142:145], v[204:207], v[82:85]
	v_mfma_f32_16x16x32_bf16 v[74:77], v[134:137], v[212:215], v[74:77]
	v_mfma_f32_16x16x32_bf16 v[66:69], v[142:145], v[212:215], v[66:69]
	v_mfma_f32_16x16x32_bf16 v[122:125], v[146:149], v[180:183], v[122:125]
	v_mfma_f32_16x16x32_bf16 v[126:129], v[172:175], v[180:183], v[126:129]
	v_mfma_f32_16x16x32_bf16 v[110:113], v[146:149], v[192:195], v[110:113]
	v_mfma_f32_16x16x32_bf16 v[102:105], v[172:175], v[192:195], v[102:105]
	v_mfma_f32_16x16x32_bf16 v[94:97], v[146:149], v[200:203], v[94:97]
	v_mfma_f32_16x16x32_bf16 v[86:89], v[172:175], v[200:203], v[86:89]
	v_mfma_f32_16x16x32_bf16 v[78:81], v[146:149], v[208:211], v[78:81]
	v_mfma_f32_16x16x32_bf16 v[70:73], v[172:175], v[208:211], v[70:73]
	v_mfma_f32_16x16x32_bf16 v[122:125], v[150:153], v[188:191], v[122:125]
	v_mfma_f32_16x16x32_bf16 v[126:129], v[176:179], v[188:191], v[126:129]
	v_mfma_f32_16x16x32_bf16 v[110:113], v[150:153], v[196:199], v[110:113]
	v_mfma_f32_16x16x32_bf16 v[102:105], v[176:179], v[196:199], v[102:105]
	v_mfma_f32_16x16x32_bf16 v[94:97], v[150:153], v[204:207], v[94:97]
	v_mfma_f32_16x16x32_bf16 v[86:89], v[176:179], v[204:207], v[86:89]
	v_mfma_f32_16x16x32_bf16 v[78:81], v[150:153], v[212:215], v[78:81]
	v_mfma_f32_16x16x32_bf16 v[70:73], v[176:179], v[212:215], v[70:73]
	s_barrier
	s_add_i32 s33, s48, s36
	s_mov_b32 m0, s33
	s_nop 0
	global_load_lds_dwordx4 v156, s[24:25]
	s_add_i32 m0, s33, 0x2000
	s_add_u32 s64, s24, 0x100000
	s_addc_u32 s65, s25, 0
	s_add_i32 s33, s49, s36
	global_load_lds_dwordx4 v160, s[24:25]
	s_mov_b32 m0, s33
	s_add_u32 s100, s28, 0x80
	s_addc_u32 s101, s29, 0
	global_load_lds_dwordx4 v156, s[64:65]
	s_add_i32 m0, s33, 0x2000
	s_nop 0
	global_load_lds_dwordx4 v160, s[64:65]
	s_mov_b32 m0, s23
	s_nop 0
	global_load_lds_dwordx4 v154, s[28:29]
	s_mov_b32 m0, s37
	s_nop 0
	global_load_lds_dwordx4 v158, s[28:29]
	ds_read_b128 v[180:183], v185 offset:16384
	ds_read_b128 v[188:191], v185 offset:17408
	ds_read_b128 v[192:195], v185 offset:18432
	ds_read_b128 v[196:199], v185 offset:19456
	ds_read_b128 v[200:203], v185 offset:20480
	ds_read_b128 v[204:207], v185 offset:21504
	ds_read_b128 v[208:211], v185 offset:22528
	ds_read_b128 v[212:215], v185 offset:23552
	s_waitcnt vmcnt(8)
	s_waitcnt lgkmcnt(0)
	s_barrier
	s_waitcnt lgkmcnt(0)
	v_mfma_f32_16x16x32_bf16 v[58:61], v[130:133], v[180:183], v[58:61]
	v_mfma_f32_16x16x32_bf16 v[54:57], v[138:141], v[180:183], v[54:57]
	v_mfma_f32_16x16x32_bf16 v[42:45], v[130:133], v[192:195], v[42:45]
	v_mfma_f32_16x16x32_bf16 v[34:37], v[138:141], v[192:195], v[34:37]
	v_mfma_f32_16x16x32_bf16 v[26:29], v[130:133], v[200:203], v[26:29]
	v_mfma_f32_16x16x32_bf16 v[18:21], v[138:141], v[200:203], v[18:21]
	v_mfma_f32_16x16x32_bf16 v[6:9], v[130:133], v[208:211], v[6:9]
	v_mfma_f32_16x16x32_bf16 v[2:5], v[138:141], v[208:211], v[2:5]
	v_mfma_f32_16x16x32_bf16 v[58:61], v[134:137], v[188:191], v[58:61]
	v_mfma_f32_16x16x32_bf16 v[54:57], v[142:145], v[188:191], v[54:57]
	v_mfma_f32_16x16x32_bf16 v[42:45], v[134:137], v[196:199], v[42:45]
	v_mfma_f32_16x16x32_bf16 v[34:37], v[142:145], v[196:199], v[34:37]
	v_mfma_f32_16x16x32_bf16 v[26:29], v[134:137], v[204:207], v[26:29]
	v_mfma_f32_16x16x32_bf16 v[18:21], v[142:145], v[204:207], v[18:21]
	v_mfma_f32_16x16x32_bf16 v[6:9], v[134:137], v[212:215], v[6:9]
	v_mfma_f32_16x16x32_bf16 v[2:5], v[142:145], v[212:215], v[2:5]
	v_mfma_f32_16x16x32_bf16 v[62:65], v[146:149], v[180:183], v[62:65]
	v_mfma_f32_16x16x32_bf16 v[50:53], v[172:175], v[180:183], v[50:53]
	v_mfma_f32_16x16x32_bf16 v[46:49], v[146:149], v[192:195], v[46:49]
	v_mfma_f32_16x16x32_bf16 v[38:41], v[172:175], v[192:195], v[38:41]
	v_mfma_f32_16x16x32_bf16 v[30:33], v[146:149], v[200:203], v[30:33]
	v_mfma_f32_16x16x32_bf16 v[22:25], v[172:175], v[200:203], v[22:25]
	v_mfma_f32_16x16x32_bf16 v[10:13], v[146:149], v[208:211], v[10:13]
	v_mfma_f32_16x16x32_bf16 v[14:17], v[172:175], v[208:211], v[14:17]
	v_mfma_f32_16x16x32_bf16 v[62:65], v[150:153], v[188:191], v[62:65]
	v_mfma_f32_16x16x32_bf16 v[50:53], v[176:179], v[188:191], v[50:53]
	v_mfma_f32_16x16x32_bf16 v[46:49], v[150:153], v[196:199], v[46:49]
	v_mfma_f32_16x16x32_bf16 v[38:41], v[176:179], v[196:199], v[38:41]
	v_mfma_f32_16x16x32_bf16 v[30:33], v[150:153], v[204:207], v[30:33]
	v_mfma_f32_16x16x32_bf16 v[22:25], v[176:179], v[204:207], v[22:25]
	v_mfma_f32_16x16x32_bf16 v[10:13], v[150:153], v[212:215], v[10:13]
	v_mfma_f32_16x16x32_bf16 v[14:17], v[176:179], v[212:215], v[14:17]
	s_barrier
; #define PG8_STAGE(bufoff, gbase, voff) do { _Pragma("unroll") for (int _i = 0; _i < 2; ++_i) \
;         __builtin_amdgcn_global_load_lds((const unsigned*)((const char*)(gbase) + (voff)[_i]), (PG8_LAS unsigned*)(lds + (bufoff) + ldsw + _i * 8192), 16, 0, 0); } while (0)
; #define PG8_LDA(dst, b, h) do { _Pragma("unroll") for (int m = 0; m < 4; ++m) _Pragma("unroll") for (int k = 0; k < 2; ++k) dst[m][k] = *(const PG8_LAS bf16x8*)(lds + PG8_SA(b, h) + aoff + m * 2048 + k * 1024); } while (0)
; #define PG8_LDB(dst, b, h) do { _Pragma("unroll") for (int n = 0; n < 2; ++n) _Pragma("unroll") for (int k = 0; k < 2; ++k) dst[n][k] = *(const PG8_LAS bf16x8*)(lds + PG8_SB(b, h) + boff + n * 2048 + k * 1024); } while (0)
; #define PG8_MMA(ai, bj, At, Bt) do { __builtin_amdgcn_s_setprio(1); _Pragma("unroll") for (int m = 0; m < 4; ++m) _Pragma("unroll") for (int n = 0; n < 2; ++n) _Pragma("unroll") for (int k = 0; k < 2; ++k) \
;         acc[ai][bj][m][n] = __builtin_amdgcn_mfma_f32_16x16x32_bf16(Bt[n][k], At[m][k], acc[ai][bj][m][n], 0, 0, 0); __builtin_amdgcn_s_setprio(0); } while (0)
; #define PG8_WAIT_V(n) asm volatile("s_waitcnt vmcnt(" #n ")" ::: "memory")
; #define PG8_WAIT_L(n) asm volatile("s_waitcnt lgkmcnt(" #n ")" ::: "memory")
; #define PG8_BAR __builtin_amdgcn_s_barrier()
; #define PG8_SCHED __builtin_amdgcn_sched_barrier(0)
; template <class Epi, class Sched, bool ALIGN_EPI = false, bool SP2 = false>
; __device__ __forceinline__ void gemm_phase(PG8_LAS unsigned char* lds, const Gemm g, const Sched& S, const Epi& E) {
;     ...
;             PG8_LDB(B0, 1, 0); PG8_LDB(B1, 1, 1); PG8_SCHED; PG8_LDA(At, 1, 0); PG8_STAGE(PG8_SA(0, 1), a2 + hstep, voffA);
;             PG8_WAIT_V(8); PG8_WAIT_L(0); PG8_BAR; PG8_MMA(0, 0, At, B0); PG8_MMA(0, 1, At, B1); PG8_BAR; PG8_SCHED;
;             PG8_LDA(At, 1, 1); PG8_STAGE(PG8_SB(1, 0), b3, voffB); PG8_STAGE(PG8_SB(1, 1), b3 + hstep, voffB); PG8_STAGE(PG8_SA(1, 0), a3, voffA);
;             PG8_WAIT_V(8); PG8_WAIT_L(0); PG8_BAR; PG8_MMA(1, 0, At, B0); PG8_MMA(1, 1, At, B1); PG8_BAR; PG8_SCHED;
	s_add_i32 s33, 0, 0x18000
	s_add_i32 s42, 0, 0x1c000
	s_add_u32 s28, s28, 0x100000
	s_addc_u32 s29, s29, 0
	s_mov_b32 m0, s40
	s_nop 0
	global_load_lds_dwordx4 v154, s[28:29]
	s_mov_b32 m0, s41
	s_nop 0
	global_load_lds_dwordx4 v158, s[28:29]
	ds_read_b128 v[130:133], v241 offset:32768
	ds_read_b128 v[134:137], v241 offset:33792
	ds_read_b128 v[138:141], v241 offset:34816
	ds_read_b128 v[142:145], v241 offset:35840
	ds_read_b128 v[146:149], v241 offset:49152
	ds_read_b128 v[150:153], v241 offset:50176
	ds_read_b128 v[172:175], v241 offset:51200
	ds_read_b128 v[176:179], v241 offset:52224
	ds_read_b128 v[180:183], v185 offset:32768
	ds_read_b128 v[188:191], v185 offset:33792
	ds_read_b128 v[192:195], v185 offset:34816
	ds_read_b128 v[196:199], v185 offset:35840
	ds_read_b128 v[200:203], v185 offset:36864
	ds_read_b128 v[204:207], v185 offset:37888
	ds_read_b128 v[208:211], v185 offset:38912
	ds_read_b128 v[212:215], v185 offset:39936
	s_waitcnt vmcnt(8)
	s_waitcnt lgkmcnt(0)
	s_barrier
	s_waitcnt lgkmcnt(0)
	v_mfma_f32_16x16x32_bf16 v[114:117], v[130:133], v[180:183], v[114:117]
	v_mfma_f32_16x16x32_bf16 v[118:121], v[138:141], v[180:183], v[118:121]
	v_mfma_f32_16x16x32_bf16 v[106:109], v[130:133], v[192:195], v[106:109]
	v_mfma_f32_16x16x32_bf16 v[98:101], v[138:141], v[192:195], v[98:101]
	v_mfma_f32_16x16x32_bf16 v[90:93], v[130:133], v[200:203], v[90:93]
	v_mfma_f32_16x16x32_bf16 v[82:85], v[138:141], v[200:203], v[82:85]
	v_mfma_f32_16x16x32_bf16 v[74:77], v[130:133], v[208:211], v[74:77]
	v_mfma_f32_16x16x32_bf16 v[66:69], v[138:141], v[208:211], v[66:69]
	v_mfma_f32_16x16x32_bf16 v[114:117], v[134:137], v[188:191], v[114:117]
	v_mfma_f32_16x16x32_bf16 v[118:121], v[142:145], v[188:191], v[118:121]
	v_mfma_f32_16x16x32_bf16 v[106:109], v[134:137], v[196:199], v[106:109]
	v_mfma_f32_16x16x32_bf16 v[98:101], v[142:145], v[196:199], v[98:101]
	v_mfma_f32_16x16x32_bf16 v[90:93], v[134:137], v[204:207], v[90:93]
	v_mfma_f32_16x16x32_bf16 v[82:85], v[142:145], v[204:207], v[82:85]
	v_mfma_f32_16x16x32_bf16 v[74:77], v[134:137], v[212:215], v[74:77]
	v_mfma_f32_16x16x32_bf16 v[66:69], v[142:145], v[212:215], v[66:69]
	v_mfma_f32_16x16x32_bf16 v[122:125], v[146:149], v[180:183], v[122:125]
	v_mfma_f32_16x16x32_bf16 v[126:129], v[172:175], v[180:183], v[126:129]
	v_mfma_f32_16x16x32_bf16 v[110:113], v[146:149], v[192:195], v[110:113]
	v_mfma_f32_16x16x32_bf16 v[102:105], v[172:175], v[192:195], v[102:105]
	v_mfma_f32_16x16x32_bf16 v[94:97], v[146:149], v[200:203], v[94:97]
	v_mfma_f32_16x16x32_bf16 v[86:89], v[172:175], v[200:203], v[86:89]
	v_mfma_f32_16x16x32_bf16 v[78:81], v[146:149], v[208:211], v[78:81]
	v_mfma_f32_16x16x32_bf16 v[70:73], v[172:175], v[208:211], v[70:73]
	v_mfma_f32_16x16x32_bf16 v[122:125], v[150:153], v[188:191], v[122:125]
	v_mfma_f32_16x16x32_bf16 v[126:129], v[176:179], v[188:191], v[126:129]
	v_mfma_f32_16x16x32_bf16 v[110:113], v[150:153], v[196:199], v[110:113]
	v_mfma_f32_16x16x32_bf16 v[102:105], v[176:179], v[196:199], v[102:105]
	v_mfma_f32_16x16x32_bf16 v[94:97], v[150:153], v[204:207], v[94:97]
	v_mfma_f32_16x16x32_bf16 v[86:89], v[176:179], v[204:207], v[86:89]
	v_mfma_f32_16x16x32_bf16 v[78:81], v[150:153], v[212:215], v[78:81]
	v_mfma_f32_16x16x32_bf16 v[70:73], v[176:179], v[212:215], v[70:73]
	s_barrier
	s_add_i32 s28, s33, s36
	s_add_i32 m0, s28, 0xffffff80
	s_nop 0
	global_load_lds_dwordx4 v156, s[24:25] offset:128
	s_add_i32 m0, s28, 0x1f80
	s_add_i32 s28, s42, s36
	global_load_lds_dwordx4 v160, s[24:25] offset:128
	s_add_u32 s24, s24, 0x100080
	s_addc_u32 s25, s25, 0
	s_mov_b32 m0, s28
	s_nop 0
	global_load_lds_dwordx4 v156, s[24:25]
	s_add_i32 m0, s28, 0x2000
	s_nop 0
	global_load_lds_dwordx4 v160, s[24:25]
	s_mov_b32 m0, s44
	s_nop 0
	global_load_lds_dwordx4 v154, s[100:101]
	s_mov_b32 m0, s45
	s_nop 0
	global_load_lds_dwordx4 v158, s[100:101]
	ds_read_b128 v[180:183], v185 offset:49152
	ds_read_b128 v[188:191], v185 offset:50176
	ds_read_b128 v[192:195], v185 offset:51200
	ds_read_b128 v[196:199], v185 offset:52224
	ds_read_b128 v[200:203], v185 offset:53248
	ds_read_b128 v[204:207], v185 offset:54272
	ds_read_b128 v[208:211], v185 offset:55296
	ds_read_b128 v[212:215], v185 offset:56320
	s_waitcnt vmcnt(8)
	s_waitcnt lgkmcnt(0)
	s_barrier
	s_waitcnt lgkmcnt(0)
	v_mfma_f32_16x16x32_bf16 v[58:61], v[130:133], v[180:183], v[58:61]
	v_mfma_f32_16x16x32_bf16 v[54:57], v[138:141], v[180:183], v[54:57]
	v_mfma_f32_16x16x32_bf16 v[42:45], v[130:133], v[192:195], v[42:45]
	v_mfma_f32_16x16x32_bf16 v[34:37], v[138:141], v[192:195], v[34:37]
	v_mfma_f32_16x16x32_bf16 v[26:29], v[130:133], v[200:203], v[26:29]
	v_mfma_f32_16x16x32_bf16 v[18:21], v[138:141], v[200:203], v[18:21]
	v_mfma_f32_16x16x32_bf16 v[6:9], v[130:133], v[208:211], v[6:9]
	v_mfma_f32_16x16x32_bf16 v[2:5], v[138:141], v[208:211], v[2:5]
	v_mfma_f32_16x16x32_bf16 v[58:61], v[134:137], v[188:191], v[58:61]
	v_mfma_f32_16x16x32_bf16 v[54:57], v[142:145], v[188:191], v[54:57]
	v_mfma_f32_16x16x32_bf16 v[42:45], v[134:137], v[196:199], v[42:45]
	v_mfma_f32_16x16x32_bf16 v[34:37], v[142:145], v[196:199], v[34:37]
	v_mfma_f32_16x16x32_bf16 v[26:29], v[134:137], v[204:207], v[26:29]
	v_mfma_f32_16x16x32_bf16 v[18:21], v[142:145], v[204:207], v[18:21]
	v_mfma_f32_16x16x32_bf16 v[6:9], v[134:137], v[212:215], v[6:9]
	v_mfma_f32_16x16x32_bf16 v[2:5], v[142:145], v[212:215], v[2:5]
	v_mfma_f32_16x16x32_bf16 v[62:65], v[146:149], v[180:183], v[62:65]
	v_mfma_f32_16x16x32_bf16 v[50:53], v[172:175], v[180:183], v[50:53]
	v_mfma_f32_16x16x32_bf16 v[46:49], v[146:149], v[192:195], v[46:49]
	v_mfma_f32_16x16x32_bf16 v[38:41], v[172:175], v[192:195], v[38:41]
	v_mfma_f32_16x16x32_bf16 v[30:33], v[146:149], v[200:203], v[30:33]
	v_mfma_f32_16x16x32_bf16 v[22:25], v[172:175], v[200:203], v[22:25]
	v_mfma_f32_16x16x32_bf16 v[10:13], v[146:149], v[208:211], v[10:13]
	v_mfma_f32_16x16x32_bf16 v[14:17], v[172:175], v[208:211], v[14:17]
	v_mfma_f32_16x16x32_bf16 v[62:65], v[150:153], v[188:191], v[62:65]
	v_mfma_f32_16x16x32_bf16 v[50:53], v[176:179], v[188:191], v[50:53]
	v_mfma_f32_16x16x32_bf16 v[46:49], v[150:153], v[196:199], v[46:49]
	v_mfma_f32_16x16x32_bf16 v[38:41], v[176:179], v[196:199], v[38:41]
	v_mfma_f32_16x16x32_bf16 v[30:33], v[150:153], v[204:207], v[30:33]
	v_mfma_f32_16x16x32_bf16 v[22:25], v[176:179], v[204:207], v[22:25]
	v_mfma_f32_16x16x32_bf16 v[10:13], v[150:153], v[212:215], v[10:13]
	v_mfma_f32_16x16x32_bf16 v[14:17], v[176:179], v[212:215], v[14:17]
	s_barrier
	s_add_i32 s62, s62, 2
	s_add_u32 s26, s26, 0x100
	s_addc_u32 s27, s27, 0
	s_add_u32 s52, s52, 0x100
	s_addc_u32 s53, s53, 0
	s_cmp_gt_u32 s62, 61
	s_cbranch_scc0 .LBB0_1595


; #define PG8_BAR __builtin_amdgcn_s_barrier()
; template <class Epi, class Sched, bool ALIGN_EPI = false, bool SP2 = false>
; __device__ __forceinline__ void gemm_phase(PG8_LAS unsigned char* lds, const Gemm g, const Sched& S, const Epi& E) {
;     ...
;         }
;         if constexpr (ALIGN_EPI) { if (wr == 0) PG8_BAR; }
	s_and_b64 vcc, exec, s[10:11]
	s_cbranch_vccz .LBB0_1598
	s_barrier

; #define PG8_STAGE(bufoff, gbase, voff) do { _Pragma("unroll") for (int _i = 0; _i < 2; ++_i) \
;         __builtin_amdgcn_global_load_lds((const unsigned*)((const char*)(gbase) + (voff)[_i]), (PG8_LAS unsigned*)(lds + (bufoff) + ldsw + _i * 8192), 16, 0, 0); } while (0)
; #define PG8_LDA(dst, b, h) do { _Pragma("unroll") for (int m = 0; m < 4; ++m) _Pragma("unroll") for (int k = 0; k < 2; ++k) dst[m][k] = *(const PG8_LAS bf16x8*)(lds + PG8_SA(b, h) + aoff + m * 2048 + k * 1024); } while (0)
; #define PG8_LDB(dst, b, h) do { _Pragma("unroll") for (int n = 0; n < 2; ++n) _Pragma("unroll") for (int k = 0; k < 2; ++k) dst[n][k] = *(const PG8_LAS bf16x8*)(lds + PG8_SB(b, h) + boff + n * 2048 + k * 1024); } while (0)
; #define PG8_MMA(ai, bj, At, Bt) do { __builtin_amdgcn_s_setprio(1); _Pragma("unroll") for (int m = 0; m < 4; ++m) _Pragma("unroll") for (int n = 0; n < 2; ++n) _Pragma("unroll") for (int k = 0; k < 2; ++k) \
;         acc[ai][bj][m][n] = __builtin_amdgcn_mfma_f32_16x16x32_bf16(Bt[n][k], At[m][k], acc[ai][bj][m][n], 0, 0, 0); __builtin_amdgcn_s_setprio(0); } while (0)
; #define PG8_WAIT_V(n) asm volatile("s_waitcnt vmcnt(" #n ")" ::: "memory")
; #define PG8_WAIT_L(n) asm volatile("s_waitcnt lgkmcnt(" #n ")" ::: "memory")
; #define PG8_BAR __builtin_amdgcn_s_barrier()
; #define PG8_SCHED __builtin_amdgcn_sched_barrier(0)
; template <class Epi, class Sched, bool ALIGN_EPI = false, bool SP2 = false>
; __device__ __forceinline__ void gemm_phase(PG8_LAS unsigned char* lds, const Gemm g, const Sched& S, const Epi& E) {
;     ...
;             PG8_LDB(B0, 0, 0); PG8_LDB(B1, 0, 1); PG8_SCHED; PG8_LDA(At, 0, 0); PG8_STAGE(PG8_SA(1, 1), a1 + hstep, voffA);
;             PG8_WAIT_V(8); PG8_WAIT_L(0); PG8_BAR; PG8_MMA(0, 0, At, B0); PG8_MMA(0, 1, At, B1); PG8_BAR; PG8_SCHED;
;             PG8_LDA(At, 0, 1); PG8_STAGE(PG8_SB(0, 0), b2, voffB); PG8_STAGE(PG8_SB(0, 1), b2 + hstep, voffB); PG8_STAGE(PG8_SA(0, 0), a2, voffA);
;             PG8_WAIT_V(8); PG8_WAIT_L(0); PG8_BAR; PG8_MMA(1, 0, At, B0); PG8_MMA(1, 1, At, B1); PG8_BAR; PG8_SCHED;
.LBB0_1681:
	s_add_u32 s22, s24, 0xfff00080
	s_addc_u32 s23, s25, -1
	s_cmp_eq_u32 s52, 60
	s_cselect_b32 s27, s15, s23
	s_cselect_b32 s26, s48, s22
	s_cselect_b32 s23, s13, s51
	s_cselect_b32 s22, s49, s50
	s_add_i32 m0, s21, 0xc000
	s_nop 0
	global_load_lds_dwordx4 v138, s[24:25]
	s_add_i32 m0, s21, 0xe000
	s_nop 0
	global_load_lds_dwordx4 v140, s[24:25]
	ds_read_b128 v[160:163], v241 offset:0
	ds_read_b128 v[166:169], v241 offset:1024
	ds_read_b128 v[170:173], v241 offset:2048
	ds_read_b128 v[174:177], v241 offset:3072
	ds_read_b128 v[178:181], v241 offset:16384
	ds_read_b128 v[182:185], v241 offset:17408
	ds_read_b128 v[186:189], v241 offset:18432
	ds_read_b128 v[190:193], v241 offset:19456
	ds_read_b128 v[194:197], v155
	ds_read_b128 v[198:201], v155 offset:1024
	ds_read_b128 v[202:205], v155 offset:2048
	ds_read_b128 v[206:209], v155 offset:3072
	ds_read_b128 v[210:213], v155 offset:4096
	ds_read_b128 v[214:217], v155 offset:5120
	ds_read_b128 v[218:221], v155 offset:6144
	ds_read_b128 v[222:225], v155 offset:7168
	s_waitcnt vmcnt(8)
	s_waitcnt lgkmcnt(0)
	s_barrier
	s_waitcnt lgkmcnt(0)
	v_mfma_f32_16x16x32_bf16 v[122:125], v[160:163], v[194:197], v[122:125]
	v_mfma_f32_16x16x32_bf16 v[114:117], v[170:173], v[194:197], v[114:117]
	v_mfma_f32_16x16x32_bf16 v[106:109], v[160:163], v[202:205], v[106:109]
	v_mfma_f32_16x16x32_bf16 v[98:101], v[170:173], v[202:205], v[98:101]
	v_mfma_f32_16x16x32_bf16 v[90:93], v[160:163], v[210:213], v[90:93]
	v_mfma_f32_16x16x32_bf16 v[82:85], v[170:173], v[210:213], v[82:85]
	v_mfma_f32_16x16x32_bf16 v[74:77], v[160:163], v[218:221], v[74:77]
	v_mfma_f32_16x16x32_bf16 v[62:65], v[170:173], v[218:221], v[62:65]
	v_mfma_f32_16x16x32_bf16 v[122:125], v[166:169], v[198:201], v[122:125]
	v_mfma_f32_16x16x32_bf16 v[114:117], v[174:177], v[198:201], v[114:117]
	v_mfma_f32_16x16x32_bf16 v[106:109], v[166:169], v[206:209], v[106:109]
	v_mfma_f32_16x16x32_bf16 v[98:101], v[174:177], v[206:209], v[98:101]
	v_mfma_f32_16x16x32_bf16 v[90:93], v[166:169], v[214:217], v[90:93]
	v_mfma_f32_16x16x32_bf16 v[82:85], v[174:177], v[214:217], v[82:85]
	v_mfma_f32_16x16x32_bf16 v[74:77], v[166:169], v[222:225], v[74:77]
	v_mfma_f32_16x16x32_bf16 v[62:65], v[174:177], v[222:225], v[62:65]
	v_mfma_f32_16x16x32_bf16 v[126:129], v[178:181], v[194:197], v[126:129]
	v_mfma_f32_16x16x32_bf16 v[118:121], v[186:189], v[194:197], v[118:121]
	v_mfma_f32_16x16x32_bf16 v[110:113], v[178:181], v[202:205], v[110:113]
	v_mfma_f32_16x16x32_bf16 v[102:105], v[186:189], v[202:205], v[102:105]
	v_mfma_f32_16x16x32_bf16 v[94:97], v[178:181], v[210:213], v[94:97]
	v_mfma_f32_16x16x32_bf16 v[86:89], v[186:189], v[210:213], v[86:89]
	v_mfma_f32_16x16x32_bf16 v[78:81], v[178:181], v[218:221], v[78:81]
	v_mfma_f32_16x16x32_bf16 v[70:73], v[186:189], v[218:221], v[70:73]
	v_mfma_f32_16x16x32_bf16 v[126:129], v[182:185], v[198:201], v[126:129]
	v_mfma_f32_16x16x32_bf16 v[118:121], v[190:193], v[198:201], v[118:121]
	v_mfma_f32_16x16x32_bf16 v[110:113], v[182:185], v[206:209], v[110:113]
	v_mfma_f32_16x16x32_bf16 v[102:105], v[190:193], v[206:209], v[102:105]
	v_mfma_f32_16x16x32_bf16 v[94:97], v[182:185], v[214:217], v[94:97]
	v_mfma_f32_16x16x32_bf16 v[86:89], v[190:193], v[214:217], v[86:89]
	v_mfma_f32_16x16x32_bf16 v[78:81], v[182:185], v[222:225], v[78:81]
	v_mfma_f32_16x16x32_bf16 v[70:73], v[190:193], v[222:225], v[70:73]
	s_barrier
	s_add_i32 s33, s44, s29
	s_mov_b32 m0, s33
	s_nop 0
	global_load_lds_dwordx4 v132, s[22:23]
	s_add_i32 m0, s33, 0x2000
	s_add_u32 s62, s22, 0x100000
	s_addc_u32 s63, s23, 0
	s_add_i32 s33, s45, s29
	global_load_lds_dwordx4 v136, s[22:23]
	s_mov_b32 m0, s33
	s_add_u32 s100, s26, 0x80
	s_addc_u32 s101, s27, 0
	global_load_lds_dwordx4 v132, s[62:63]
	s_add_i32 m0, s33, 0x2000
	s_nop 0
	global_load_lds_dwordx4 v136, s[62:63]
	s_mov_b32 m0, s21
	s_nop 0
	global_load_lds_dwordx4 v130, s[26:27]
	s_mov_b32 m0, s34
	s_nop 0
	global_load_lds_dwordx4 v134, s[26:27]
	ds_read_b128 v[194:197], v155 offset:16384
	ds_read_b128 v[198:201], v155 offset:17408
	ds_read_b128 v[202:205], v155 offset:18432
	ds_read_b128 v[206:209], v155 offset:19456
	ds_read_b128 v[210:213], v155 offset:20480
	ds_read_b128 v[214:217], v155 offset:21504
	ds_read_b128 v[218:221], v155 offset:22528
	ds_read_b128 v[222:225], v155 offset:23552
	s_waitcnt vmcnt(8)
	s_waitcnt lgkmcnt(0)
	s_barrier
	s_waitcnt lgkmcnt(0)
	v_mfma_f32_16x16x32_bf16 v[58:61], v[160:163], v[194:197], v[58:61]
	v_mfma_f32_16x16x32_bf16 v[50:53], v[170:173], v[194:197], v[50:53]
	v_mfma_f32_16x16x32_bf16 v[42:45], v[160:163], v[202:205], v[42:45]
	v_mfma_f32_16x16x32_bf16 v[34:37], v[170:173], v[202:205], v[34:37]
	v_mfma_f32_16x16x32_bf16 v[26:29], v[160:163], v[210:213], v[26:29]
	v_mfma_f32_16x16x32_bf16 v[18:21], v[170:173], v[210:213], v[18:21]
	v_mfma_f32_16x16x32_bf16 v[10:13], v[160:163], v[218:221], v[10:13]
	v_mfma_f32_16x16x32_bf16 v[2:5], v[170:173], v[218:221], v[2:5]
	v_mfma_f32_16x16x32_bf16 v[58:61], v[166:169], v[198:201], v[58:61]
	v_mfma_f32_16x16x32_bf16 v[50:53], v[174:177], v[198:201], v[50:53]
	v_mfma_f32_16x16x32_bf16 v[42:45], v[166:169], v[206:209], v[42:45]
	v_mfma_f32_16x16x32_bf16 v[34:37], v[174:177], v[206:209], v[34:37]
	v_mfma_f32_16x16x32_bf16 v[26:29], v[166:169], v[214:217], v[26:29]
	v_mfma_f32_16x16x32_bf16 v[18:21], v[174:177], v[214:217], v[18:21]
	v_mfma_f32_16x16x32_bf16 v[10:13], v[166:169], v[222:225], v[10:13]
	v_mfma_f32_16x16x32_bf16 v[2:5], v[174:177], v[222:225], v[2:5]
	v_mfma_f32_16x16x32_bf16 v[66:69], v[178:181], v[194:197], v[66:69]
	v_mfma_f32_16x16x32_bf16 v[54:57], v[186:189], v[194:197], v[54:57]
	v_mfma_f32_16x16x32_bf16 v[46:49], v[178:181], v[202:205], v[46:49]
	v_mfma_f32_16x16x32_bf16 v[38:41], v[186:189], v[202:205], v[38:41]
	v_mfma_f32_16x16x32_bf16 v[30:33], v[178:181], v[210:213], v[30:33]
	v_mfma_f32_16x16x32_bf16 v[22:25], v[186:189], v[210:213], v[22:25]
	v_mfma_f32_16x16x32_bf16 v[14:17], v[178:181], v[218:221], v[14:17]
	v_mfma_f32_16x16x32_bf16 v[6:9], v[186:189], v[218:221], v[6:9]
	v_mfma_f32_16x16x32_bf16 v[66:69], v[182:185], v[198:201], v[66:69]
	v_mfma_f32_16x16x32_bf16 v[54:57], v[190:193], v[198:201], v[54:57]
	v_mfma_f32_16x16x32_bf16 v[46:49], v[182:185], v[206:209], v[46:49]
	v_mfma_f32_16x16x32_bf16 v[38:41], v[190:193], v[206:209], v[38:41]
	v_mfma_f32_16x16x32_bf16 v[30:33], v[182:185], v[214:217], v[30:33]
	v_mfma_f32_16x16x32_bf16 v[22:25], v[190:193], v[214:217], v[22:25]
	v_mfma_f32_16x16x32_bf16 v[14:17], v[182:185], v[222:225], v[14:17]
	v_mfma_f32_16x16x32_bf16 v[6:9], v[190:193], v[222:225], v[6:9]
	s_barrier
; #define PG8_STAGE(bufoff, gbase, voff) do { _Pragma("unroll") for (int _i = 0; _i < 2; ++_i) \
;         __builtin_amdgcn_global_load_lds((const unsigned*)((const char*)(gbase) + (voff)[_i]), (PG8_LAS unsigned*)(lds + (bufoff) + ldsw + _i * 8192), 16, 0, 0); } while (0)
; #define PG8_LDA(dst, b, h) do { _Pragma("unroll") for (int m = 0; m < 4; ++m) _Pragma("unroll") for (int k = 0; k < 2; ++k) dst[m][k] = *(const PG8_LAS bf16x8*)(lds + PG8_SA(b, h) + aoff + m * 2048 + k * 1024); } while (0)
; #define PG8_LDB(dst, b, h) do { _Pragma("unroll") for (int n = 0; n < 2; ++n) _Pragma("unroll") for (int k = 0; k < 2; ++k) dst[n][k] = *(const PG8_LAS bf16x8*)(lds + PG8_SB(b, h) + boff + n * 2048 + k * 1024); } while (0)
; #define PG8_MMA(ai, bj, At, Bt) do { __builtin_amdgcn_s_setprio(1); _Pragma("unroll") for (int m = 0; m < 4; ++m) _Pragma("unroll") for (int n = 0; n < 2; ++n) _Pragma("unroll") for (int k = 0; k < 2; ++k) \
;         acc[ai][bj][m][n] = __builtin_amdgcn_mfma_f32_16x16x32_bf16(Bt[n][k], At[m][k], acc[ai][bj][m][n], 0, 0, 0); __builtin_amdgcn_s_setprio(0); } while (0)
; #define PG8_WAIT_V(n) asm volatile("s_waitcnt vmcnt(" #n ")" ::: "memory")
; #define PG8_WAIT_L(n) asm volatile("s_waitcnt lgkmcnt(" #n ")" ::: "memory")
; #define PG8_BAR __builtin_amdgcn_s_barrier()
; #define PG8_SCHED __builtin_amdgcn_sched_barrier(0)
; template <class Epi, class Sched, bool ALIGN_EPI = false, bool SP2 = false>
; __device__ __forceinline__ void gemm_phase(PG8_LAS unsigned char* lds, const Gemm g, const Sched& S, const Epi& E) {
;     ...
;             PG8_LDB(B0, 1, 0); PG8_LDB(B1, 1, 1); PG8_SCHED; PG8_LDA(At, 1, 0); PG8_STAGE(PG8_SA(0, 1), a2 + hstep, voffA);
;             PG8_WAIT_V(8); PG8_WAIT_L(0); PG8_BAR; PG8_MMA(0, 0, At, B0); PG8_MMA(0, 1, At, B1); PG8_BAR; PG8_SCHED;
;             PG8_LDA(At, 1, 1); PG8_STAGE(PG8_SB(1, 0), b3, voffB); PG8_STAGE(PG8_SB(1, 1), b3 + hstep, voffB); PG8_STAGE(PG8_SA(1, 0), a3, voffA);
;             PG8_WAIT_V(8); PG8_WAIT_L(0); PG8_BAR; PG8_MMA(1, 0, At, B0); PG8_MMA(1, 1, At, B1); PG8_BAR; PG8_SCHED;
	s_add_i32 s33, 0, 0x18000
	s_add_i32 s42, 0, 0x1c000
	s_add_u32 s26, s26, 0x100000
	s_addc_u32 s27, s27, 0
	s_mov_b32 m0, s35
	s_nop 0
	global_load_lds_dwordx4 v130, s[26:27]
	s_mov_b32 m0, s36
	s_nop 0
	global_load_lds_dwordx4 v134, s[26:27]
	ds_read_b128 v[160:163], v241 offset:32768
	ds_read_b128 v[166:169], v241 offset:33792
	ds_read_b128 v[170:173], v241 offset:34816
	ds_read_b128 v[174:177], v241 offset:35840
	ds_read_b128 v[178:181], v241 offset:49152
	ds_read_b128 v[182:185], v241 offset:50176
	ds_read_b128 v[186:189], v241 offset:51200
	ds_read_b128 v[190:193], v241 offset:52224
	ds_read_b128 v[194:197], v155 offset:32768
	ds_read_b128 v[198:201], v155 offset:33792
	ds_read_b128 v[202:205], v155 offset:34816
	ds_read_b128 v[206:209], v155 offset:35840
	ds_read_b128 v[210:213], v155 offset:36864
	ds_read_b128 v[214:217], v155 offset:37888
	ds_read_b128 v[218:221], v155 offset:38912
	ds_read_b128 v[222:225], v155 offset:39936
	s_waitcnt vmcnt(8)
	s_waitcnt lgkmcnt(0)
	s_barrier
	s_waitcnt lgkmcnt(0)
	v_mfma_f32_16x16x32_bf16 v[122:125], v[160:163], v[194:197], v[122:125]
	v_mfma_f32_16x16x32_bf16 v[114:117], v[170:173], v[194:197], v[114:117]
	v_mfma_f32_16x16x32_bf16 v[106:109], v[160:163], v[202:205], v[106:109]
	v_mfma_f32_16x16x32_bf16 v[98:101], v[170:173], v[202:205], v[98:101]
	v_mfma_f32_16x16x32_bf16 v[90:93], v[160:163], v[210:213], v[90:93]
	v_mfma_f32_16x16x32_bf16 v[82:85], v[170:173], v[210:213], v[82:85]
	v_mfma_f32_16x16x32_bf16 v[74:77], v[160:163], v[218:221], v[74:77]
	v_mfma_f32_16x16x32_bf16 v[62:65], v[170:173], v[218:221], v[62:65]
	v_mfma_f32_16x16x32_bf16 v[122:125], v[166:169], v[198:201], v[122:125]
	v_mfma_f32_16x16x32_bf16 v[114:117], v[174:177], v[198:201], v[114:117]
	v_mfma_f32_16x16x32_bf16 v[106:109], v[166:169], v[206:209], v[106:109]
	v_mfma_f32_16x16x32_bf16 v[98:101], v[174:177], v[206:209], v[98:101]
	v_mfma_f32_16x16x32_bf16 v[90:93], v[166:169], v[214:217], v[90:93]
	v_mfma_f32_16x16x32_bf16 v[82:85], v[174:177], v[214:217], v[82:85]
	v_mfma_f32_16x16x32_bf16 v[74:77], v[166:169], v[222:225], v[74:77]
	v_mfma_f32_16x16x32_bf16 v[62:65], v[174:177], v[222:225], v[62:65]
	v_mfma_f32_16x16x32_bf16 v[126:129], v[178:181], v[194:197], v[126:129]
	v_mfma_f32_16x16x32_bf16 v[118:121], v[186:189], v[194:197], v[118:121]
	v_mfma_f32_16x16x32_bf16 v[110:113], v[178:181], v[202:205], v[110:113]
	v_mfma_f32_16x16x32_bf16 v[102:105], v[186:189], v[202:205], v[102:105]
	v_mfma_f32_16x16x32_bf16 v[94:97], v[178:181], v[210:213], v[94:97]
	v_mfma_f32_16x16x32_bf16 v[86:89], v[186:189], v[210:213], v[86:89]
	v_mfma_f32_16x16x32_bf16 v[78:81], v[178:181], v[218:221], v[78:81]
	v_mfma_f32_16x16x32_bf16 v[70:73], v[186:189], v[218:221], v[70:73]
	v_mfma_f32_16x16x32_bf16 v[126:129], v[182:185], v[198:201], v[126:129]
	v_mfma_f32_16x16x32_bf16 v[118:121], v[190:193], v[198:201], v[118:121]
	v_mfma_f32_16x16x32_bf16 v[110:113], v[182:185], v[206:209], v[110:113]
	v_mfma_f32_16x16x32_bf16 v[102:105], v[190:193], v[206:209], v[102:105]
	v_mfma_f32_16x16x32_bf16 v[94:97], v[182:185], v[214:217], v[94:97]
	v_mfma_f32_16x16x32_bf16 v[86:89], v[190:193], v[214:217], v[86:89]
	v_mfma_f32_16x16x32_bf16 v[78:81], v[182:185], v[222:225], v[78:81]
	v_mfma_f32_16x16x32_bf16 v[70:73], v[190:193], v[222:225], v[70:73]
	s_barrier
	s_add_i32 s26, s33, s29
	s_add_i32 m0, s26, 0xffffff80
	s_nop 0
	global_load_lds_dwordx4 v132, s[22:23] offset:128
	s_add_i32 m0, s26, 0x1f80
	s_add_i32 s26, s42, s29
	global_load_lds_dwordx4 v136, s[22:23] offset:128
	s_add_u32 s22, s22, 0x100080
	s_addc_u32 s23, s23, 0
	s_mov_b32 m0, s26
	s_nop 0
	global_load_lds_dwordx4 v132, s[22:23]
	s_add_i32 m0, s26, 0x2000
	s_nop 0
	global_load_lds_dwordx4 v136, s[22:23]
	s_mov_b32 m0, s41
	s_nop 0
	global_load_lds_dwordx4 v130, s[100:101]
	s_mov_b32 m0, s43
	s_nop 0
	global_load_lds_dwordx4 v134, s[100:101]
	ds_read_b128 v[194:197], v155 offset:49152
	ds_read_b128 v[198:201], v155 offset:50176
	ds_read_b128 v[202:205], v155 offset:51200
	ds_read_b128 v[206:209], v155 offset:52224
	ds_read_b128 v[210:213], v155 offset:53248
	ds_read_b128 v[214:217], v155 offset:54272
	ds_read_b128 v[218:221], v155 offset:55296
	ds_read_b128 v[222:225], v155 offset:56320
	s_waitcnt vmcnt(8)
	s_waitcnt lgkmcnt(0)
	s_barrier
	s_waitcnt lgkmcnt(0)
	v_mfma_f32_16x16x32_bf16 v[58:61], v[160:163], v[194:197], v[58:61]
	v_mfma_f32_16x16x32_bf16 v[50:53], v[170:173], v[194:197], v[50:53]
	v_mfma_f32_16x16x32_bf16 v[42:45], v[160:163], v[202:205], v[42:45]
	v_mfma_f32_16x16x32_bf16 v[34:37], v[170:173], v[202:205], v[34:37]
	v_mfma_f32_16x16x32_bf16 v[26:29], v[160:163], v[210:213], v[26:29]
	v_mfma_f32_16x16x32_bf16 v[18:21], v[170:173], v[210:213], v[18:21]
	v_mfma_f32_16x16x32_bf16 v[10:13], v[160:163], v[218:221], v[10:13]
	v_mfma_f32_16x16x32_bf16 v[2:5], v[170:173], v[218:221], v[2:5]
	v_mfma_f32_16x16x32_bf16 v[58:61], v[166:169], v[198:201], v[58:61]
	v_mfma_f32_16x16x32_bf16 v[50:53], v[174:177], v[198:201], v[50:53]
	v_mfma_f32_16x16x32_bf16 v[42:45], v[166:169], v[206:209], v[42:45]
	v_mfma_f32_16x16x32_bf16 v[34:37], v[174:177], v[206:209], v[34:37]
	v_mfma_f32_16x16x32_bf16 v[26:29], v[166:169], v[214:217], v[26:29]
	v_mfma_f32_16x16x32_bf16 v[18:21], v[174:177], v[214:217], v[18:21]
	v_mfma_f32_16x16x32_bf16 v[10:13], v[166:169], v[222:225], v[10:13]
	v_mfma_f32_16x16x32_bf16 v[2:5], v[174:177], v[222:225], v[2:5]
	v_mfma_f32_16x16x32_bf16 v[66:69], v[178:181], v[194:197], v[66:69]
	v_mfma_f32_16x16x32_bf16 v[54:57], v[186:189], v[194:197], v[54:57]
	v_mfma_f32_16x16x32_bf16 v[46:49], v[178:181], v[202:205], v[46:49]
	v_mfma_f32_16x16x32_bf16 v[38:41], v[186:189], v[202:205], v[38:41]
	v_mfma_f32_16x16x32_bf16 v[30:33], v[178:181], v[210:213], v[30:33]
	v_mfma_f32_16x16x32_bf16 v[22:25], v[186:189], v[210:213], v[22:25]
	v_mfma_f32_16x16x32_bf16 v[14:17], v[178:181], v[218:221], v[14:17]
	v_mfma_f32_16x16x32_bf16 v[6:9], v[186:189], v[218:221], v[6:9]
	v_mfma_f32_16x16x32_bf16 v[66:69], v[182:185], v[198:201], v[66:69]
	v_mfma_f32_16x16x32_bf16 v[54:57], v[190:193], v[198:201], v[54:57]
	v_mfma_f32_16x16x32_bf16 v[46:49], v[182:185], v[206:209], v[46:49]
	v_mfma_f32_16x16x32_bf16 v[38:41], v[190:193], v[206:209], v[38:41]
	v_mfma_f32_16x16x32_bf16 v[30:33], v[182:185], v[214:217], v[30:33]
	v_mfma_f32_16x16x32_bf16 v[22:25], v[190:193], v[214:217], v[22:25]
	v_mfma_f32_16x16x32_bf16 v[14:17], v[182:185], v[222:225], v[14:17]
	v_mfma_f32_16x16x32_bf16 v[6:9], v[190:193], v[222:225], v[6:9]
	s_barrier
	s_add_i32 s52, s52, 2
	s_add_u32 s24, s24, 0x100
	s_addc_u32 s25, s25, 0
	s_add_u32 s50, s50, 0x100
	s_addc_u32 s51, s51, 0
	s_cmp_gt_u32 s52, 61
	s_cbranch_scc0 .LBB0_1681


; #define PG8_BAR __builtin_amdgcn_s_barrier()
; template <class Epi, class Sched, bool ALIGN_EPI = false, bool SP2 = false>
; __device__ __forceinline__ void gemm_phase(PG8_LAS unsigned char* lds, const Gemm g, const Sched& S, const Epi& E) {
;     ...
;         }
;         if constexpr (ALIGN_EPI) { if (wr == 0) PG8_BAR; }
	s_and_b64 vcc, exec, s[8:9]
	s_cbranch_vccz .LBB0_1684
	s_barrier

; #define PG8_STAGE(bufoff, gbase, voff) do { _Pragma("unroll") for (int _i = 0; _i < 2; ++_i) \
;         __builtin_amdgcn_global_load_lds((const unsigned*)((const char*)(gbase) + (voff)[_i]), (PG8_LAS unsigned*)(lds + (bufoff) + ldsw + _i * 8192), 16, 0, 0); } while (0)
; #define PG8_LDA(dst, b, h) do { _Pragma("unroll") for (int m = 0; m < 4; ++m) _Pragma("unroll") for (int k = 0; k < 2; ++k) dst[m][k] = *(const PG8_LAS bf16x8*)(lds + PG8_SA(b, h) + aoff + m * 2048 + k * 1024); } while (0)
; #define PG8_LDB(dst, b, h) do { _Pragma("unroll") for (int n = 0; n < 2; ++n) _Pragma("unroll") for (int k = 0; k < 2; ++k) dst[n][k] = *(const PG8_LAS bf16x8*)(lds + PG8_SB(b, h) + boff + n * 2048 + k * 1024); } while (0)
; #define PG8_MMA(ai, bj, At, Bt) do { __builtin_amdgcn_s_setprio(1); _Pragma("unroll") for (int m = 0; m < 4; ++m) _Pragma("unroll") for (int n = 0; n < 2; ++n) _Pragma("unroll") for (int k = 0; k < 2; ++k) \
;         acc[ai][bj][m][n] = __builtin_amdgcn_mfma_f32_16x16x32_bf16(Bt[n][k], At[m][k], acc[ai][bj][m][n], 0, 0, 0); __builtin_amdgcn_s_setprio(0); } while (0)
; #define PG8_WAIT_V(n) asm volatile("s_waitcnt vmcnt(" #n ")" ::: "memory")
; #define PG8_WAIT_L(n) asm volatile("s_waitcnt lgkmcnt(" #n ")" ::: "memory")
; #define PG8_BAR __builtin_amdgcn_s_barrier()
; #define PG8_SCHED __builtin_amdgcn_sched_barrier(0)
; template <class Epi, class Sched, bool ALIGN_EPI = false, bool SP2 = false>
; __device__ __forceinline__ void gemm_phase(PG8_LAS unsigned char* lds, const Gemm g, const Sched& S, const Epi& E) {
;     ...
;             PG8_LDB(B0, 0, 0); PG8_LDB(B1, 0, 1); PG8_SCHED; PG8_LDA(At, 0, 0); PG8_STAGE(PG8_SA(1, 1), a1 + hstep, voffA);
;             PG8_WAIT_V(8); PG8_WAIT_L(0); PG8_BAR; PG8_MMA(0, 0, At, B0); PG8_MMA(0, 1, At, B1); PG8_BAR; PG8_SCHED;
;             PG8_LDA(At, 0, 1); PG8_STAGE(PG8_SB(0, 0), b2, voffB); PG8_STAGE(PG8_SB(0, 1), b2 + hstep, voffB); PG8_STAGE(PG8_SA(0, 0), a2, voffA);
;             PG8_WAIT_V(8); PG8_WAIT_L(0); PG8_BAR; PG8_MMA(1, 0, At, B0); PG8_MMA(1, 1, At, B1); PG8_BAR; PG8_SCHED;
.LBB0_1801:
	s_add_u32 s16, s18, 0xffd50080
	s_addc_u32 s17, s19, -1
	s_cmpk_eq_i32 s48, 0xa8
	s_cselect_b32 s21, s5, s17
	s_cselect_b32 s20, s4, s16
	s_cselect_b32 s17, s15, s47
	s_cselect_b32 s16, s14, s46
	s_add_i32 m0, s25, 0xc000
	s_nop 0
	global_load_lds_dwordx4 v0, s[18:19]
	s_add_i32 m0, s25, 0xe000
	s_nop 0
	global_load_lds_dwordx4 v162, s[18:19]
	ds_read_b128 v[130:133], v241 offset:0
	ds_read_b128 v[134:137], v241 offset:1024
	ds_read_b128 v[138:141], v241 offset:2048
	ds_read_b128 v[142:145], v241 offset:3072
	ds_read_b128 v[146:149], v241 offset:16384
	ds_read_b128 v[150:153], v241 offset:17408
	ds_read_b128 v[170:173], v241 offset:18432
	ds_read_b128 v[174:177], v241 offset:19456
	ds_read_b128 v[178:181], v184
	ds_read_b128 v[186:189], v184 offset:1024
	ds_read_b128 v[190:193], v184 offset:2048
	ds_read_b128 v[194:197], v184 offset:3072
	ds_read_b128 v[198:201], v184 offset:4096
	ds_read_b128 v[202:205], v184 offset:5120
	ds_read_b128 v[206:209], v184 offset:6144
	ds_read_b128 v[210:213], v184 offset:7168
	s_waitcnt vmcnt(8)
	s_waitcnt lgkmcnt(0)
	s_barrier
	s_waitcnt lgkmcnt(0)
	v_mfma_f32_16x16x32_bf16 v[114:117], v[130:133], v[178:181], v[114:117]
	v_mfma_f32_16x16x32_bf16 v[118:121], v[138:141], v[178:181], v[118:121]
	v_mfma_f32_16x16x32_bf16 v[106:109], v[130:133], v[190:193], v[106:109]
	v_mfma_f32_16x16x32_bf16 v[98:101], v[138:141], v[190:193], v[98:101]
	v_mfma_f32_16x16x32_bf16 v[90:93], v[130:133], v[198:201], v[90:93]
	v_mfma_f32_16x16x32_bf16 v[82:85], v[138:141], v[198:201], v[82:85]
	v_mfma_f32_16x16x32_bf16 v[74:77], v[130:133], v[206:209], v[74:77]
	v_mfma_f32_16x16x32_bf16 v[66:69], v[138:141], v[206:209], v[66:69]
	v_mfma_f32_16x16x32_bf16 v[114:117], v[134:137], v[186:189], v[114:117]
	v_mfma_f32_16x16x32_bf16 v[118:121], v[142:145], v[186:189], v[118:121]
	v_mfma_f32_16x16x32_bf16 v[106:109], v[134:137], v[194:197], v[106:109]
	v_mfma_f32_16x16x32_bf16 v[98:101], v[142:145], v[194:197], v[98:101]
	v_mfma_f32_16x16x32_bf16 v[90:93], v[134:137], v[202:205], v[90:93]
	v_mfma_f32_16x16x32_bf16 v[82:85], v[142:145], v[202:205], v[82:85]
	v_mfma_f32_16x16x32_bf16 v[74:77], v[134:137], v[210:213], v[74:77]
	v_mfma_f32_16x16x32_bf16 v[66:69], v[142:145], v[210:213], v[66:69]
	v_mfma_f32_16x16x32_bf16 v[122:125], v[146:149], v[178:181], v[122:125]
	v_mfma_f32_16x16x32_bf16 v[126:129], v[170:173], v[178:181], v[126:129]
	v_mfma_f32_16x16x32_bf16 v[110:113], v[146:149], v[190:193], v[110:113]
	v_mfma_f32_16x16x32_bf16 v[102:105], v[170:173], v[190:193], v[102:105]
	v_mfma_f32_16x16x32_bf16 v[94:97], v[146:149], v[198:201], v[94:97]
	v_mfma_f32_16x16x32_bf16 v[86:89], v[170:173], v[198:201], v[86:89]
	v_mfma_f32_16x16x32_bf16 v[78:81], v[146:149], v[206:209], v[78:81]
	v_mfma_f32_16x16x32_bf16 v[70:73], v[170:173], v[206:209], v[70:73]
	v_mfma_f32_16x16x32_bf16 v[122:125], v[150:153], v[186:189], v[122:125]
	v_mfma_f32_16x16x32_bf16 v[126:129], v[174:177], v[186:189], v[126:129]
	v_mfma_f32_16x16x32_bf16 v[110:113], v[150:153], v[194:197], v[110:113]
	v_mfma_f32_16x16x32_bf16 v[102:105], v[174:177], v[194:197], v[102:105]
	v_mfma_f32_16x16x32_bf16 v[94:97], v[150:153], v[202:205], v[94:97]
	v_mfma_f32_16x16x32_bf16 v[86:89], v[174:177], v[202:205], v[86:89]
	v_mfma_f32_16x16x32_bf16 v[78:81], v[150:153], v[210:213], v[78:81]
	v_mfma_f32_16x16x32_bf16 v[70:73], v[174:177], v[210:213], v[70:73]
	s_barrier
	s_add_i32 s33, s36, s24
	s_mov_b32 m0, s33
	s_nop 0
	global_load_lds_dwordx4 v156, s[16:17]
	s_add_i32 m0, s33, 0x2000
	s_add_u32 s50, s16, 0x2b0000
	s_addc_u32 s51, s17, 0
	s_add_i32 s33, s37, s24
	global_load_lds_dwordx4 v160, s[16:17]
	s_mov_b32 m0, s33
	s_add_u32 s100, s20, 0x80
	s_addc_u32 s101, s21, 0
	global_load_lds_dwordx4 v156, s[50:51]
	s_add_i32 m0, s33, 0x2000
	s_nop 0
	global_load_lds_dwordx4 v160, s[50:51]
	s_mov_b32 m0, s25
	s_nop 0
	global_load_lds_dwordx4 v154, s[20:21]
	s_mov_b32 m0, s26
	s_nop 0
	global_load_lds_dwordx4 v158, s[20:21]
	ds_read_b128 v[178:181], v184 offset:16384
	ds_read_b128 v[186:189], v184 offset:17408
	ds_read_b128 v[190:193], v184 offset:18432
	ds_read_b128 v[194:197], v184 offset:19456
	ds_read_b128 v[198:201], v184 offset:20480
	ds_read_b128 v[202:205], v184 offset:21504
	ds_read_b128 v[206:209], v184 offset:22528
	ds_read_b128 v[210:213], v184 offset:23552
	s_waitcnt vmcnt(8)
	s_waitcnt lgkmcnt(0)
	s_barrier
	s_waitcnt lgkmcnt(0)
	v_mfma_f32_16x16x32_bf16 v[58:61], v[130:133], v[178:181], v[58:61]
	v_mfma_f32_16x16x32_bf16 v[54:57], v[138:141], v[178:181], v[54:57]
	v_mfma_f32_16x16x32_bf16 v[42:45], v[130:133], v[190:193], v[42:45]
	v_mfma_f32_16x16x32_bf16 v[34:37], v[138:141], v[190:193], v[34:37]
	v_mfma_f32_16x16x32_bf16 v[26:29], v[130:133], v[198:201], v[26:29]
	v_mfma_f32_16x16x32_bf16 v[18:21], v[138:141], v[198:201], v[18:21]
	v_mfma_f32_16x16x32_bf16 v[6:9], v[130:133], v[206:209], v[6:9]
	v_mfma_f32_16x16x32_bf16 v[2:5], v[138:141], v[206:209], v[2:5]
	v_mfma_f32_16x16x32_bf16 v[58:61], v[134:137], v[186:189], v[58:61]
	v_mfma_f32_16x16x32_bf16 v[54:57], v[142:145], v[186:189], v[54:57]
	v_mfma_f32_16x16x32_bf16 v[42:45], v[134:137], v[194:197], v[42:45]
	v_mfma_f32_16x16x32_bf16 v[34:37], v[142:145], v[194:197], v[34:37]
	v_mfma_f32_16x16x32_bf16 v[26:29], v[134:137], v[202:205], v[26:29]
	v_mfma_f32_16x16x32_bf16 v[18:21], v[142:145], v[202:205], v[18:21]
	v_mfma_f32_16x16x32_bf16 v[6:9], v[134:137], v[210:213], v[6:9]
	v_mfma_f32_16x16x32_bf16 v[2:5], v[142:145], v[210:213], v[2:5]
	v_mfma_f32_16x16x32_bf16 v[62:65], v[146:149], v[178:181], v[62:65]
	v_mfma_f32_16x16x32_bf16 v[50:53], v[170:173], v[178:181], v[50:53]
	v_mfma_f32_16x16x32_bf16 v[46:49], v[146:149], v[190:193], v[46:49]
	v_mfma_f32_16x16x32_bf16 v[38:41], v[170:173], v[190:193], v[38:41]
	v_mfma_f32_16x16x32_bf16 v[30:33], v[146:149], v[198:201], v[30:33]
	v_mfma_f32_16x16x32_bf16 v[22:25], v[170:173], v[198:201], v[22:25]
	v_mfma_f32_16x16x32_bf16 v[10:13], v[146:149], v[206:209], v[10:13]
	v_mfma_f32_16x16x32_bf16 v[14:17], v[170:173], v[206:209], v[14:17]
	v_mfma_f32_16x16x32_bf16 v[62:65], v[150:153], v[186:189], v[62:65]
	v_mfma_f32_16x16x32_bf16 v[50:53], v[174:177], v[186:189], v[50:53]
	v_mfma_f32_16x16x32_bf16 v[46:49], v[150:153], v[194:197], v[46:49]
	v_mfma_f32_16x16x32_bf16 v[38:41], v[174:177], v[194:197], v[38:41]
	v_mfma_f32_16x16x32_bf16 v[30:33], v[150:153], v[202:205], v[30:33]
	v_mfma_f32_16x16x32_bf16 v[22:25], v[174:177], v[202:205], v[22:25]
	v_mfma_f32_16x16x32_bf16 v[10:13], v[150:153], v[210:213], v[10:13]
	v_mfma_f32_16x16x32_bf16 v[14:17], v[174:177], v[210:213], v[14:17]
	s_barrier
; #define PG8_STAGE(bufoff, gbase, voff) do { _Pragma("unroll") for (int _i = 0; _i < 2; ++_i) \
;         __builtin_amdgcn_global_load_lds((const unsigned*)((const char*)(gbase) + (voff)[_i]), (PG8_LAS unsigned*)(lds + (bufoff) + ldsw + _i * 8192), 16, 0, 0); } while (0)
; #define PG8_LDA(dst, b, h) do { _Pragma("unroll") for (int m = 0; m < 4; ++m) _Pragma("unroll") for (int k = 0; k < 2; ++k) dst[m][k] = *(const PG8_LAS bf16x8*)(lds + PG8_SA(b, h) + aoff + m * 2048 + k * 1024); } while (0)
; #define PG8_LDB(dst, b, h) do { _Pragma("unroll") for (int n = 0; n < 2; ++n) _Pragma("unroll") for (int k = 0; k < 2; ++k) dst[n][k] = *(const PG8_LAS bf16x8*)(lds + PG8_SB(b, h) + boff + n * 2048 + k * 1024); } while (0)
; #define PG8_MMA(ai, bj, At, Bt) do { __builtin_amdgcn_s_setprio(1); _Pragma("unroll") for (int m = 0; m < 4; ++m) _Pragma("unroll") for (int n = 0; n < 2; ++n) _Pragma("unroll") for (int k = 0; k < 2; ++k) \
;         acc[ai][bj][m][n] = __builtin_amdgcn_mfma_f32_16x16x32_bf16(Bt[n][k], At[m][k], acc[ai][bj][m][n], 0, 0, 0); __builtin_amdgcn_s_setprio(0); } while (0)
; #define PG8_WAIT_V(n) asm volatile("s_waitcnt vmcnt(" #n ")" ::: "memory")
; #define PG8_WAIT_L(n) asm volatile("s_waitcnt lgkmcnt(" #n ")" ::: "memory")
; #define PG8_BAR __builtin_amdgcn_s_barrier()
; #define PG8_SCHED __builtin_amdgcn_sched_barrier(0)
; template <class Epi, class Sched, bool ALIGN_EPI = false, bool SP2 = false>
; __device__ __forceinline__ void gemm_phase(PG8_LAS unsigned char* lds, const Gemm g, const Sched& S, const Epi& E) {
;     ...
;             PG8_LDB(B0, 1, 0); PG8_LDB(B1, 1, 1); PG8_SCHED; PG8_LDA(At, 1, 0); PG8_STAGE(PG8_SA(0, 1), a2 + hstep, voffA);
;             PG8_WAIT_V(8); PG8_WAIT_L(0); PG8_BAR; PG8_MMA(0, 0, At, B0); PG8_MMA(0, 1, At, B1); PG8_BAR; PG8_SCHED;
;             PG8_LDA(At, 1, 1); PG8_STAGE(PG8_SB(1, 0), b3, voffB); PG8_STAGE(PG8_SB(1, 1), b3 + hstep, voffB); PG8_STAGE(PG8_SA(1, 0), a3, voffA);
;             PG8_WAIT_V(8); PG8_WAIT_L(0); PG8_BAR; PG8_MMA(1, 0, At, B0); PG8_MMA(1, 1, At, B1); PG8_BAR; PG8_SCHED;
	s_add_i32 s33, 0, 0x18000
	s_add_i32 s42, 0, 0x1c000
	s_add_u32 s20, s20, 0x2b0000
	s_addc_u32 s21, s21, 0
	s_mov_b32 m0, s27
	s_nop 0
	global_load_lds_dwordx4 v154, s[20:21]
	s_mov_b32 m0, s28
	s_nop 0
	global_load_lds_dwordx4 v158, s[20:21]
	ds_read_b128 v[130:133], v241 offset:32768
	ds_read_b128 v[134:137], v241 offset:33792
	ds_read_b128 v[138:141], v241 offset:34816
	ds_read_b128 v[142:145], v241 offset:35840
	ds_read_b128 v[146:149], v241 offset:49152
	ds_read_b128 v[150:153], v241 offset:50176
	ds_read_b128 v[170:173], v241 offset:51200
	ds_read_b128 v[174:177], v241 offset:52224
	ds_read_b128 v[178:181], v184 offset:32768
	ds_read_b128 v[186:189], v184 offset:33792
	ds_read_b128 v[190:193], v184 offset:34816
	ds_read_b128 v[194:197], v184 offset:35840
	ds_read_b128 v[198:201], v184 offset:36864
	ds_read_b128 v[202:205], v184 offset:37888
	ds_read_b128 v[206:209], v184 offset:38912
	ds_read_b128 v[210:213], v184 offset:39936
	s_waitcnt vmcnt(8)
	s_waitcnt lgkmcnt(0)
	s_barrier
	s_waitcnt lgkmcnt(0)
	v_mfma_f32_16x16x32_bf16 v[114:117], v[130:133], v[178:181], v[114:117]
	v_mfma_f32_16x16x32_bf16 v[118:121], v[138:141], v[178:181], v[118:121]
	v_mfma_f32_16x16x32_bf16 v[106:109], v[130:133], v[190:193], v[106:109]
	v_mfma_f32_16x16x32_bf16 v[98:101], v[138:141], v[190:193], v[98:101]
	v_mfma_f32_16x16x32_bf16 v[90:93], v[130:133], v[198:201], v[90:93]
	v_mfma_f32_16x16x32_bf16 v[82:85], v[138:141], v[198:201], v[82:85]
	v_mfma_f32_16x16x32_bf16 v[74:77], v[130:133], v[206:209], v[74:77]
	v_mfma_f32_16x16x32_bf16 v[66:69], v[138:141], v[206:209], v[66:69]
	v_mfma_f32_16x16x32_bf16 v[114:117], v[134:137], v[186:189], v[114:117]
	v_mfma_f32_16x16x32_bf16 v[118:121], v[142:145], v[186:189], v[118:121]
	v_mfma_f32_16x16x32_bf16 v[106:109], v[134:137], v[194:197], v[106:109]
	v_mfma_f32_16x16x32_bf16 v[98:101], v[142:145], v[194:197], v[98:101]
	v_mfma_f32_16x16x32_bf16 v[90:93], v[134:137], v[202:205], v[90:93]
	v_mfma_f32_16x16x32_bf16 v[82:85], v[142:145], v[202:205], v[82:85]
	v_mfma_f32_16x16x32_bf16 v[74:77], v[134:137], v[210:213], v[74:77]
	v_mfma_f32_16x16x32_bf16 v[66:69], v[142:145], v[210:213], v[66:69]
	v_mfma_f32_16x16x32_bf16 v[122:125], v[146:149], v[178:181], v[122:125]
	v_mfma_f32_16x16x32_bf16 v[126:129], v[170:173], v[178:181], v[126:129]
	v_mfma_f32_16x16x32_bf16 v[110:113], v[146:149], v[190:193], v[110:113]
	v_mfma_f32_16x16x32_bf16 v[102:105], v[170:173], v[190:193], v[102:105]
	v_mfma_f32_16x16x32_bf16 v[94:97], v[146:149], v[198:201], v[94:97]
	v_mfma_f32_16x16x32_bf16 v[86:89], v[170:173], v[198:201], v[86:89]
	v_mfma_f32_16x16x32_bf16 v[78:81], v[146:149], v[206:209], v[78:81]
	v_mfma_f32_16x16x32_bf16 v[70:73], v[170:173], v[206:209], v[70:73]
	v_mfma_f32_16x16x32_bf16 v[122:125], v[150:153], v[186:189], v[122:125]
	v_mfma_f32_16x16x32_bf16 v[126:129], v[174:177], v[186:189], v[126:129]
	v_mfma_f32_16x16x32_bf16 v[110:113], v[150:153], v[194:197], v[110:113]
	v_mfma_f32_16x16x32_bf16 v[102:105], v[174:177], v[194:197], v[102:105]
	v_mfma_f32_16x16x32_bf16 v[94:97], v[150:153], v[202:205], v[94:97]
	v_mfma_f32_16x16x32_bf16 v[86:89], v[174:177], v[202:205], v[86:89]
	v_mfma_f32_16x16x32_bf16 v[78:81], v[150:153], v[210:213], v[78:81]
	v_mfma_f32_16x16x32_bf16 v[70:73], v[174:177], v[210:213], v[70:73]
	s_barrier
	s_add_i32 s20, s33, s24
	s_add_i32 m0, s20, 0xffffff80
	s_nop 0
	global_load_lds_dwordx4 v156, s[16:17] offset:128
	s_add_i32 m0, s20, 0x1f80
	s_add_i32 s20, s42, s24
	global_load_lds_dwordx4 v160, s[16:17] offset:128
	s_add_u32 s16, s16, 0x2b0080
	s_addc_u32 s17, s17, 0
	s_mov_b32 m0, s20
	s_nop 0
	global_load_lds_dwordx4 v156, s[16:17]
	s_add_i32 m0, s20, 0x2000
	s_nop 0
	global_load_lds_dwordx4 v160, s[16:17]
	s_mov_b32 m0, s30
	s_nop 0
	global_load_lds_dwordx4 v154, s[100:101]
	s_mov_b32 m0, s31
	s_nop 0
	global_load_lds_dwordx4 v158, s[100:101]
	ds_read_b128 v[178:181], v184 offset:49152
	ds_read_b128 v[186:189], v184 offset:50176
	ds_read_b128 v[190:193], v184 offset:51200
	ds_read_b128 v[194:197], v184 offset:52224
	ds_read_b128 v[198:201], v184 offset:53248
	ds_read_b128 v[202:205], v184 offset:54272
	ds_read_b128 v[206:209], v184 offset:55296
	ds_read_b128 v[210:213], v184 offset:56320
	s_waitcnt vmcnt(8)
	s_waitcnt lgkmcnt(0)
	s_barrier
	s_waitcnt lgkmcnt(0)
	v_mfma_f32_16x16x32_bf16 v[58:61], v[130:133], v[178:181], v[58:61]
	v_mfma_f32_16x16x32_bf16 v[54:57], v[138:141], v[178:181], v[54:57]
	v_mfma_f32_16x16x32_bf16 v[42:45], v[130:133], v[190:193], v[42:45]
	v_mfma_f32_16x16x32_bf16 v[34:37], v[138:141], v[190:193], v[34:37]
	v_mfma_f32_16x16x32_bf16 v[26:29], v[130:133], v[198:201], v[26:29]
	v_mfma_f32_16x16x32_bf16 v[18:21], v[138:141], v[198:201], v[18:21]
	v_mfma_f32_16x16x32_bf16 v[6:9], v[130:133], v[206:209], v[6:9]
	v_mfma_f32_16x16x32_bf16 v[2:5], v[138:141], v[206:209], v[2:5]
	v_mfma_f32_16x16x32_bf16 v[58:61], v[134:137], v[186:189], v[58:61]
	v_mfma_f32_16x16x32_bf16 v[54:57], v[142:145], v[186:189], v[54:57]
	v_mfma_f32_16x16x32_bf16 v[42:45], v[134:137], v[194:197], v[42:45]
	v_mfma_f32_16x16x32_bf16 v[34:37], v[142:145], v[194:197], v[34:37]
	v_mfma_f32_16x16x32_bf16 v[26:29], v[134:137], v[202:205], v[26:29]
	v_mfma_f32_16x16x32_bf16 v[18:21], v[142:145], v[202:205], v[18:21]
	v_mfma_f32_16x16x32_bf16 v[6:9], v[134:137], v[210:213], v[6:9]
	v_mfma_f32_16x16x32_bf16 v[2:5], v[142:145], v[210:213], v[2:5]
	v_mfma_f32_16x16x32_bf16 v[62:65], v[146:149], v[178:181], v[62:65]
	v_mfma_f32_16x16x32_bf16 v[50:53], v[170:173], v[178:181], v[50:53]
	v_mfma_f32_16x16x32_bf16 v[46:49], v[146:149], v[190:193], v[46:49]
	v_mfma_f32_16x16x32_bf16 v[38:41], v[170:173], v[190:193], v[38:41]
	v_mfma_f32_16x16x32_bf16 v[30:33], v[146:149], v[198:201], v[30:33]
	v_mfma_f32_16x16x32_bf16 v[22:25], v[170:173], v[198:201], v[22:25]
	v_mfma_f32_16x16x32_bf16 v[10:13], v[146:149], v[206:209], v[10:13]
	v_mfma_f32_16x16x32_bf16 v[14:17], v[170:173], v[206:209], v[14:17]
	v_mfma_f32_16x16x32_bf16 v[62:65], v[150:153], v[186:189], v[62:65]
	v_mfma_f32_16x16x32_bf16 v[50:53], v[174:177], v[186:189], v[50:53]
	v_mfma_f32_16x16x32_bf16 v[46:49], v[150:153], v[194:197], v[46:49]
	v_mfma_f32_16x16x32_bf16 v[38:41], v[174:177], v[194:197], v[38:41]
	v_mfma_f32_16x16x32_bf16 v[30:33], v[150:153], v[202:205], v[30:33]
	v_mfma_f32_16x16x32_bf16 v[22:25], v[174:177], v[202:205], v[22:25]
	v_mfma_f32_16x16x32_bf16 v[10:13], v[150:153], v[210:213], v[10:13]
	v_mfma_f32_16x16x32_bf16 v[14:17], v[174:177], v[210:213], v[14:17]
	s_barrier
	s_add_i32 s48, s48, 2
	s_add_u32 s18, s18, 0x100
	s_addc_u32 s19, s19, 0
	s_add_u32 s46, s46, 0x100
	s_addc_u32 s47, s47, 0
	s_cmpk_gt_u32 s48, 0xa9
	s_cbranch_scc0 .LBB0_1801


; #define PG8_BAR __builtin_amdgcn_s_barrier()
; template <class Epi, class Sched, bool ALIGN_EPI = false, bool SP2 = false>
; __device__ __forceinline__ void gemm_phase(PG8_LAS unsigned char* lds, const Gemm g, const Sched& S, const Epi& E) {
;     ...
;         }
;         if constexpr (ALIGN_EPI) { if (wr == 0) PG8_BAR; }
	s_and_b64 vcc, exec, s[12:13]
	s_cbranch_vccz .LBB0_1804
	s_barrier
